# also: transposes with 32 loads in flight + one coalesced gain load via ds_bpermute, store-phase LDS reads batched, split-K read-back / kv_unit staging / final RMSNorm / attention Q loads issued togeth
# baseline (speedup 1.0000x reference)
; #define LAS __attribute__((address_space(3)))
; __device__ __forceinline__ unsigned cvt_pk_bf16(float lo, float hi) { unsigned r; asm volatile("v_cvt_pk_bf16_f32 %0, %1, %2" : "=v"(r) : "v"(lo), "v"(hi)); return r; }
;     ...
;     const int c = lane & 7;
; #pragma unroll
;     for (int j = 0; j < 4; ++j) { const int n = (lane >> 3) + 8 * j; const LAS float* s = scr + (8 * c) * 33 + n;
;         u32x4 o; o.x = cvt_pk_bf16(s[0 * 33], s[1 * 33]); o.y = cvt_pk_bf16(s[2 * 33], s[3 * 33]); o.z = cvt_pk_bf16(s[4 * 33], s[5 * 33]); o.w = cvt_pk_bf16(s[6 * 33], s[7 * 33]);
;         const int nn = n0 + n; const int orow = mode ? ((nn >> 7) * 256 + (nn & 127) + (mode == 2 ? 128 : 0)) : nn;
;         *(u32x4*)(WT + (size_t)orow * K + k0 + 8 * c) = o; }
;     asm volatile("s_waitcnt lgkmcnt(0)" ::: "memory");
.LBB0_25:
	s_waitcnt lgkmcnt(0)
	ds_read2_b32 v[100:101], v30 offset1:33
	ds_read2_b32 v[102:103], v30 offset0:66 offset1:99
	ds_read2_b32 v[104:105], v30 offset0:132 offset1:165
	ds_read2_b32 v[106:107], v30 offset0:198 offset1:231
	ds_read2_b32 v[108:109], v30 offset0:8 offset1:41
	ds_read2_b32 v[110:111], v30 offset0:74 offset1:107
	ds_read2_b32 v[112:113], v30 offset0:140 offset1:173
	ds_read2_b32 v[114:115], v30 offset0:206 offset1:239
	ds_read2_b32 v[116:117], v30 offset0:16 offset1:49
	ds_read2_b32 v[118:119], v30 offset0:82 offset1:115
	ds_read2_b32 v[120:121], v30 offset0:148 offset1:181
	ds_read2_b32 v[122:123], v30 offset0:214 offset1:247
	ds_read2_b32 v[124:125], v30 offset0:24 offset1:57
	ds_read2_b32 v[126:127], v30 offset0:90 offset1:123
	ds_read2_b32 v[128:129], v30 offset0:156 offset1:189
	ds_read2_b32 v[130:131], v30 offset0:222 offset1:255
	s_waitcnt lgkmcnt(0)
	v_or_b32_e32 v16, s0, v3
	v_ashrrev_i32_e32 v17, 31, v16
	s_waitcnt lgkmcnt(0)
	v_cvt_pk_bf16_f32 v8, v100, v101
	v_lshl_add_u64 v[14:15], s[4:5], 1, v[4:5]
	v_lshlrev_b64 v[16:17], 12, v[16:17]
	s_waitcnt lgkmcnt(0)
	v_cvt_pk_bf16_f32 v9, v102, v103
	v_lshl_add_u64 v[16:17], v[14:15], 0, v[16:17]
	s_waitcnt lgkmcnt(0)
	v_cvt_pk_bf16_f32 v10, v104, v105
	s_waitcnt lgkmcnt(0)
	v_cvt_pk_bf16_f32 v11, v106, v107
	global_store_dwordx4 v[16:17], v[8:11], off
	v_or_b32_e32 v16, s0, v31
	s_waitcnt lgkmcnt(0)
	v_cvt_pk_bf16_f32 v8, v108, v109
	v_ashrrev_i32_e32 v17, 31, v16
	s_waitcnt lgkmcnt(0)
	v_cvt_pk_bf16_f32 v9, v110, v111
	v_lshlrev_b64 v[16:17], 12, v[16:17]
	s_waitcnt lgkmcnt(0)
	v_cvt_pk_bf16_f32 v10, v112, v113
	s_waitcnt lgkmcnt(0)
	v_cvt_pk_bf16_f32 v11, v114, v115
	v_lshl_add_u64 v[16:17], v[14:15], 0, v[16:17]
	global_store_dwordx4 v[16:17], v[8:11], off
	v_or_b32_e32 v16, s0, v32
	v_ashrrev_i32_e32 v17, 31, v16
	s_waitcnt lgkmcnt(0)
	v_cvt_pk_bf16_f32 v8, v116, v117
	s_waitcnt lgkmcnt(0)
	v_cvt_pk_bf16_f32 v9, v118, v119
	s_waitcnt lgkmcnt(0)
	v_cvt_pk_bf16_f32 v10, v120, v121
	v_lshlrev_b64 v[16:17], 12, v[16:17]
	s_waitcnt lgkmcnt(0)
	v_cvt_pk_bf16_f32 v11, v122, v123
	v_lshl_add_u64 v[16:17], v[14:15], 0, v[16:17]
	global_store_dwordx4 v[16:17], v[8:11], off
	s_add_i32 s12, s12, s21
	s_cmpk_lt_i32 s12, 0x1800
	s_waitcnt lgkmcnt(0)
	v_cvt_pk_bf16_f32 v8, v124, v125
	v_or_b32_e32 v12, s0, v33
	v_ashrrev_i32_e32 v13, 31, v12
	v_lshlrev_b64 v[12:13], 12, v[12:13]
	s_waitcnt lgkmcnt(0)
	v_cvt_pk_bf16_f32 v9, v126, v127
	v_lshl_add_u64 v[12:13], v[14:15], 0, v[12:13]
	s_waitcnt lgkmcnt(0)
	v_cvt_pk_bf16_f32 v10, v128, v129
	s_waitcnt lgkmcnt(0)
	v_cvt_pk_bf16_f32 v11, v130, v131
	global_store_dwordx4 v[12:13], v[8:11], off
	s_waitcnt lgkmcnt(0)
	s_cbranch_scc0 .LBB0_44

;     const int nblk = N / 32, kb = item / nblk, nb = item % nblk, k0 = 64 * kb, n0 = 32 * nb;
; #pragma unroll 8
;     for (int i = 0; i < 32; ++i) { const int kk = 2 * i + (lane >> 5); float v = __builtin_nontemporal_load(W + (size_t)(k0 + kk) * N + n0 + (lane & 31)); if (gain) v *= gain[k0 + kk]; scr[kk * 33 + (lane & 31)] = v; }
;     asm volatile("s_waitcnt lgkmcnt(0)" ::: "memory");
.LBB0_27:
.LBB0_28:
	s_and_b64 vcc, exec, s[52:53]
	s_cbranch_vccnz .Lcvt_rows_1
	v_mbcnt_lo_u32_b32 v166, -1, 0
	v_mbcnt_hi_u32_b32 v166, -1, v166
	v_lshrrev_b32_e32 v169, 5, v166
	v_lshlrev_b32_e32 v169, 2, v169
	v_lshlrev_b32_e32 v166, 2, v166
	v_sub_u32_e32 v166, v166, v169
	v_mov_b32_e32 v167, 0
	v_lshl_add_u64 v[164:165], s[10:11], 0, v[24:25]
	v_lshl_add_u64 v[164:165], v[164:165], 0, v[166:167]
	global_load_dword v168, v[164:165], off
.Lcvt_rows_1:
	v_lshl_add_u64 v[164:165], v[26:27], 0, s[6:7]
	global_load_dword v100, v[164:165], off nt
	v_lshl_add_u64 v[164:165], v[22:23], 0, s[6:7]
	global_load_dword v101, v[164:165], off nt
	v_lshl_add_u64 v[164:165], v[20:21], 0, s[6:7]
	global_load_dword v102, v[164:165], off nt
	v_lshl_add_u64 v[164:165], v[18:19], 0, s[6:7]
	global_load_dword v103, v[164:165], off nt
	v_lshl_add_u64 v[164:165], v[16:17], 0, s[6:7]
	global_load_dword v104, v[164:165], off nt
	v_lshl_add_u64 v[164:165], v[14:15], 0, s[6:7]
	global_load_dword v105, v[164:165], off nt
	v_lshl_add_u64 v[164:165], v[12:13], 0, s[6:7]
	global_load_dword v106, v[164:165], off nt
	v_lshl_add_u64 v[164:165], v[8:9], 0, s[6:7]
	global_load_dword v107, v[164:165], off nt
	s_add_u32 s6, s6, 0x60000
	s_addc_u32 s7, s7, 0
	v_lshl_add_u64 v[164:165], v[26:27], 0, s[6:7]
	global_load_dword v108, v[164:165], off nt
	v_lshl_add_u64 v[164:165], v[22:23], 0, s[6:7]
	global_load_dword v109, v[164:165], off nt
	v_lshl_add_u64 v[164:165], v[20:21], 0, s[6:7]
	global_load_dword v110, v[164:165], off nt
	v_lshl_add_u64 v[164:165], v[18:19], 0, s[6:7]
	global_load_dword v111, v[164:165], off nt
	v_lshl_add_u64 v[164:165], v[16:17], 0, s[6:7]
	global_load_dword v112, v[164:165], off nt
	v_lshl_add_u64 v[164:165], v[14:15], 0, s[6:7]
	global_load_dword v113, v[164:165], off nt
	v_lshl_add_u64 v[164:165], v[12:13], 0, s[6:7]
	global_load_dword v114, v[164:165], off nt
	v_lshl_add_u64 v[164:165], v[8:9], 0, s[6:7]
	global_load_dword v115, v[164:165], off nt
	s_add_u32 s6, s6, 0x60000
	s_addc_u32 s7, s7, 0
	v_lshl_add_u64 v[164:165], v[26:27], 0, s[6:7]
	global_load_dword v116, v[164:165], off nt
	v_lshl_add_u64 v[164:165], v[22:23], 0, s[6:7]
	global_load_dword v117, v[164:165], off nt
	v_lshl_add_u64 v[164:165], v[20:21], 0, s[6:7]
	global_load_dword v118, v[164:165], off nt
	v_lshl_add_u64 v[164:165], v[18:19], 0, s[6:7]
	global_load_dword v119, v[164:165], off nt
	v_lshl_add_u64 v[164:165], v[16:17], 0, s[6:7]
	global_load_dword v120, v[164:165], off nt
	v_lshl_add_u64 v[164:165], v[14:15], 0, s[6:7]
	global_load_dword v121, v[164:165], off nt
	v_lshl_add_u64 v[164:165], v[12:13], 0, s[6:7]
	global_load_dword v122, v[164:165], off nt
	v_lshl_add_u64 v[164:165], v[8:9], 0, s[6:7]
	global_load_dword v123, v[164:165], off nt
	s_add_u32 s6, s6, 0x60000
	s_addc_u32 s7, s7, 0
	v_lshl_add_u64 v[164:165], v[26:27], 0, s[6:7]
	global_load_dword v124, v[164:165], off nt
	v_lshl_add_u64 v[164:165], v[22:23], 0, s[6:7]
	global_load_dword v125, v[164:165], off nt
	v_lshl_add_u64 v[164:165], v[20:21], 0, s[6:7]
	global_load_dword v126, v[164:165], off nt
	v_lshl_add_u64 v[164:165], v[18:19], 0, s[6:7]
	global_load_dword v127, v[164:165], off nt
	v_lshl_add_u64 v[164:165], v[16:17], 0, s[6:7]
	global_load_dword v128, v[164:165], off nt
	v_lshl_add_u64 v[164:165], v[14:15], 0, s[6:7]
	global_load_dword v129, v[164:165], off nt
	v_lshl_add_u64 v[164:165], v[12:13], 0, s[6:7]
	global_load_dword v130, v[164:165], off nt
	v_lshl_add_u64 v[164:165], v[8:9], 0, s[6:7]
	global_load_dword v131, v[164:165], off nt
	s_add_u32 s6, s6, 0x60000
	s_addc_u32 s7, s7, 0
	s_and_b64 vcc, exec, s[52:53]
	s_cbranch_vccnz .Lcvt_put_1
	s_waitcnt vmcnt(32)
	ds_bpermute_b32 v132, v169, v168
	ds_bpermute_b32 v133, v169, v168 offset:8
	ds_bpermute_b32 v134, v169, v168 offset:16
	ds_bpermute_b32 v135, v169, v168 offset:24
	ds_bpermute_b32 v136, v169, v168 offset:32
	ds_bpermute_b32 v137, v169, v168 offset:40
	ds_bpermute_b32 v138, v169, v168 offset:48
	ds_bpermute_b32 v139, v169, v168 offset:56
	ds_bpermute_b32 v140, v169, v168 offset:64
	ds_bpermute_b32 v141, v169, v168 offset:72
	ds_bpermute_b32 v142, v169, v168 offset:80
	ds_bpermute_b32 v143, v169, v168 offset:88
	ds_bpermute_b32 v144, v169, v168 offset:96
	ds_bpermute_b32 v145, v169, v168 offset:104
	ds_bpermute_b32 v146, v169, v168 offset:112
	ds_bpermute_b32 v147, v169, v168 offset:120
	ds_bpermute_b32 v148, v169, v168 offset:128
	ds_bpermute_b32 v149, v169, v168 offset:136
	ds_bpermute_b32 v150, v169, v168 offset:144
	ds_bpermute_b32 v151, v169, v168 offset:152
	ds_bpermute_b32 v152, v169, v168 offset:160
	ds_bpermute_b32 v153, v169, v168 offset:168
	ds_bpermute_b32 v154, v169, v168 offset:176
	ds_bpermute_b32 v155, v169, v168 offset:184
	ds_bpermute_b32 v156, v169, v168 offset:192
	ds_bpermute_b32 v157, v169, v168 offset:200
	ds_bpermute_b32 v158, v169, v168 offset:208
	ds_bpermute_b32 v159, v169, v168 offset:216
	ds_bpermute_b32 v160, v169, v168 offset:224
	ds_bpermute_b32 v161, v169, v168 offset:232
	ds_bpermute_b32 v162, v169, v168 offset:240
	ds_bpermute_b32 v163, v169, v168 offset:248
	s_waitcnt vmcnt(0) lgkmcnt(0)
	v_mul_f32_e32 v100, v100, v132
	v_mul_f32_e32 v101, v101, v133
	v_mul_f32_e32 v102, v102, v134
	v_mul_f32_e32 v103, v103, v135
	v_mul_f32_e32 v104, v104, v136
	v_mul_f32_e32 v105, v105, v137
	v_mul_f32_e32 v106, v106, v138
	v_mul_f32_e32 v107, v107, v139
	v_mul_f32_e32 v108, v108, v140
	v_mul_f32_e32 v109, v109, v141
	v_mul_f32_e32 v110, v110, v142
	v_mul_f32_e32 v111, v111, v143
	v_mul_f32_e32 v112, v112, v144
	v_mul_f32_e32 v113, v113, v145
	v_mul_f32_e32 v114, v114, v146
	v_mul_f32_e32 v115, v115, v147
	v_mul_f32_e32 v116, v116, v148
	v_mul_f32_e32 v117, v117, v149
	v_mul_f32_e32 v118, v118, v150
	v_mul_f32_e32 v119, v119, v151
	v_mul_f32_e32 v120, v120, v152
	v_mul_f32_e32 v121, v121, v153
	v_mul_f32_e32 v122, v122, v154
	v_mul_f32_e32 v123, v123, v155
	v_mul_f32_e32 v124, v124, v156
	v_mul_f32_e32 v125, v125, v157
	v_mul_f32_e32 v126, v126, v158
	v_mul_f32_e32 v127, v127, v159
	v_mul_f32_e32 v128, v128, v160
	v_mul_f32_e32 v129, v129, v161
	v_mul_f32_e32 v130, v130, v162
	v_mul_f32_e32 v131, v131, v163
;     ...
;     for (int i = 0; i < 32; ++i) { const int kk = 2 * i + (lane >> 5); float v = __builtin_nontemporal_load(W + (size_t)(k0 + kk) * N + n0 + (lane & 31)); if (gain) v *= gain[k0 + kk]; scr[kk * 33 + (lane & 31)] = v; }
;     asm volatile("s_waitcnt lgkmcnt(0)" ::: "memory");
.Lcvt_put_1:
	s_waitcnt vmcnt(0)
	ds_write_b32 v43, v100
	ds_write_b32 v43, v101 offset:264
	ds_write_b32 v43, v102 offset:528
	ds_write_b32 v43, v103 offset:792
	ds_write_b32 v43, v104 offset:1056
	ds_write_b32 v43, v105 offset:1320
	ds_write_b32 v43, v106 offset:1584
	ds_write_b32 v43, v107 offset:1848
	ds_write_b32 v43, v108 offset:2112
	ds_write_b32 v43, v109 offset:2376
	ds_write_b32 v43, v110 offset:2640
	ds_write_b32 v43, v111 offset:2904
	ds_write_b32 v43, v112 offset:3168
	ds_write_b32 v43, v113 offset:3432
	ds_write_b32 v43, v114 offset:3696
	ds_write_b32 v43, v115 offset:3960
	ds_write_b32 v43, v116 offset:4224
	ds_write_b32 v43, v117 offset:4488
	ds_write_b32 v43, v118 offset:4752
	ds_write_b32 v43, v119 offset:5016
	ds_write_b32 v43, v120 offset:5280
	ds_write_b32 v43, v121 offset:5544
	ds_write_b32 v43, v122 offset:5808
	ds_write_b32 v43, v123 offset:6072
	ds_write_b32 v43, v124 offset:6336
	ds_write_b32 v43, v125 offset:6600
	ds_write_b32 v43, v126 offset:6864
	ds_write_b32 v43, v127 offset:7128
	ds_write_b32 v43, v128 offset:7392
	ds_write_b32 v43, v129 offset:7656
	ds_write_b32 v43, v130 offset:7920
	ds_write_b32 v43, v131 offset:8184
	v_add_u32_e32 v43, 0x2100, v43
	s_add_u32 s10, s10, 0x100
	s_addc_u32 s11, s11, 0
	s_branch .LBB0_25

; #define LAS __attribute__((address_space(3)))
; __device__ __forceinline__ unsigned cvt_pk_bf16(float lo, float hi) { unsigned r; asm volatile("v_cvt_pk_bf16_f32 %0, %1, %2" : "=v"(r) : "v"(lo), "v"(hi)); return r; }
;     ...
;     const int c = lane & 7;
; #pragma unroll
;     for (int j = 0; j < 4; ++j) { const int n = (lane >> 3) + 8 * j; const LAS float* s = scr + (8 * c) * 33 + n;
;         u32x4 o; o.x = cvt_pk_bf16(s[0 * 33], s[1 * 33]); o.y = cvt_pk_bf16(s[2 * 33], s[3 * 33]); o.z = cvt_pk_bf16(s[4 * 33], s[5 * 33]); o.w = cvt_pk_bf16(s[6 * 33], s[7 * 33]);
;         const int nn = n0 + n; const int orow = mode ? ((nn >> 7) * 256 + (nn & 127) + (mode == 2 ? 128 : 0)) : nn;
;         *(u32x4*)(WT + (size_t)orow * K + k0 + 8 * c) = o; }
;     asm volatile("s_waitcnt lgkmcnt(0)" ::: "memory");
.LBB0_46:
	s_waitcnt lgkmcnt(0)
	ds_read2_b32 v[100:101], v19 offset1:33
	ds_read2_b32 v[102:103], v19 offset0:66 offset1:99
	ds_read2_b32 v[104:105], v19 offset0:132 offset1:165
	ds_read2_b32 v[106:107], v19 offset0:198 offset1:231
	ds_read2_b32 v[108:109], v19 offset0:8 offset1:41
	ds_read2_b32 v[110:111], v19 offset0:74 offset1:107
	ds_read2_b32 v[112:113], v19 offset0:140 offset1:173
	ds_read2_b32 v[114:115], v19 offset0:206 offset1:239
	ds_read2_b32 v[116:117], v19 offset0:16 offset1:49
	ds_read2_b32 v[118:119], v19 offset0:82 offset1:115
	ds_read2_b32 v[120:121], v19 offset0:148 offset1:181
	ds_read2_b32 v[122:123], v19 offset0:214 offset1:247
	ds_read2_b32 v[124:125], v19 offset0:24 offset1:57
	ds_read2_b32 v[126:127], v19 offset0:90 offset1:123
	ds_read2_b32 v[128:129], v19 offset0:156 offset1:189
	ds_read2_b32 v[130:131], v19 offset0:222 offset1:255
	s_waitcnt lgkmcnt(0)
	v_or_b32_e32 v34, s4, v3
	v_ashrrev_i32_e32 v35, 31, v34
	s_waitcnt lgkmcnt(0)
	v_cvt_pk_bf16_f32 v26, v100, v101
	v_lshl_add_u64 v[32:33], s[6:7], 1, v[12:13]
	v_lshlrev_b64 v[34:35], 12, v[34:35]
	s_waitcnt lgkmcnt(0)
	v_cvt_pk_bf16_f32 v27, v102, v103
	v_lshl_add_u64 v[34:35], v[32:33], 0, v[34:35]
	s_waitcnt lgkmcnt(0)
	v_cvt_pk_bf16_f32 v28, v104, v105
	s_waitcnt lgkmcnt(0)
	v_cvt_pk_bf16_f32 v29, v106, v107
	global_store_dwordx4 v[34:35], v[26:29], off
	v_or_b32_e32 v34, s4, v49
	v_ashrrev_i32_e32 v35, 31, v34
	s_waitcnt lgkmcnt(0)
	v_cvt_pk_bf16_f32 v26, v108, v109
	v_lshlrev_b64 v[34:35], 12, v[34:35]
	s_waitcnt lgkmcnt(0)
	v_cvt_pk_bf16_f32 v27, v110, v111
	v_lshl_add_u64 v[34:35], v[32:33], 0, v[34:35]
	s_waitcnt lgkmcnt(0)
	v_cvt_pk_bf16_f32 v28, v112, v113
	s_waitcnt lgkmcnt(0)
	v_cvt_pk_bf16_f32 v29, v114, v115
	global_store_dwordx4 v[34:35], v[26:29], off
	v_or_b32_e32 v34, s4, v50
	s_waitcnt lgkmcnt(0)
	v_cvt_pk_bf16_f32 v26, v116, v117
	v_ashrrev_i32_e32 v35, 31, v34
	s_waitcnt lgkmcnt(0)
	v_cvt_pk_bf16_f32 v27, v118, v119
	v_lshlrev_b64 v[34:35], 12, v[34:35]
	s_waitcnt lgkmcnt(0)
	v_cvt_pk_bf16_f32 v28, v120, v121
	s_waitcnt lgkmcnt(0)
	v_cvt_pk_bf16_f32 v29, v122, v123
	v_lshl_add_u64 v[34:35], v[32:33], 0, v[34:35]
	global_store_dwordx4 v[34:35], v[26:29], off
	v_or_b32_e32 v34, s4, v51
	v_ashrrev_i32_e32 v35, 31, v34
	s_waitcnt lgkmcnt(0)
	v_cvt_pk_bf16_f32 v26, v124, v125
	s_waitcnt lgkmcnt(0)
	v_cvt_pk_bf16_f32 v27, v126, v127
	s_waitcnt lgkmcnt(0)
	v_cvt_pk_bf16_f32 v28, v128, v129
	v_lshlrev_b64 v[34:35], 12, v[34:35]
	s_waitcnt lgkmcnt(0)
	v_cvt_pk_bf16_f32 v29, v130, v131
	v_lshl_add_u64 v[30:31], v[32:33], 0, v[34:35]
	global_store_dwordx4 v[30:31], v[26:29], off
	s_waitcnt lgkmcnt(0)

; #define LAS __attribute__((address_space(3)))
; __device__ __forceinline__ unsigned cvt_pk_bf16(float lo, float hi) { unsigned r; asm volatile("v_cvt_pk_bf16_f32 %0, %1, %2" : "=v"(r) : "v"(lo), "v"(hi)); return r; }
;     const int nblk = N / 32, kb = item / nblk, nb = item % nblk, k0 = 64 * kb, n0 = 32 * nb;
; #pragma unroll 8
;     for (int i = 0; i < 32; ++i) { const int kk = 2 * i + (lane >> 5); float v = __builtin_nontemporal_load(W + (size_t)(k0 + kk) * N + n0 + (lane & 31)); if (gain) v *= gain[k0 + kk]; scr[kk * 33 + (lane & 31)] = v; }
;     asm volatile("s_waitcnt lgkmcnt(0)" ::: "memory");
;     const int c = lane & 7;
; #pragma unroll
;     for (int j = 0; j < 4; ++j) { const int n = (lane >> 3) + 8 * j; const LAS float* s = scr + (8 * c) * 33 + n;
;         u32x4 o; o.x = cvt_pk_bf16(s[0 * 33], s[1 * 33]); o.y = cvt_pk_bf16(s[2 * 33], s[3 * 33]); o.z = cvt_pk_bf16(s[4 * 33], s[5 * 33]); o.w = cvt_pk_bf16(s[6 * 33], s[7 * 33]);
;         const int nn = n0 + n; const int orow = mode ? ((nn >> 7) * 256 + (nn & 127) + (mode == 2 ? 128 : 0)) : nn;
;         *(u32x4*)(WT + (size_t)orow * K + k0 + 8 * c) = o; }
;     asm volatile("s_waitcnt lgkmcnt(0)" ::: "memory");
.LBB0_53:
	v_lshl_add_u64 v[164:165], v[40:41], 0, s[4:5]
	global_load_dword v100, v[164:165], off nt
	v_lshl_add_u64 v[164:165], v[38:39], 0, s[4:5]
	global_load_dword v101, v[164:165], off nt
	v_lshl_add_u64 v[164:165], v[36:37], 0, s[4:5]
	global_load_dword v102, v[164:165], off nt
	v_lshl_add_u64 v[164:165], v[34:35], 0, s[4:5]
	global_load_dword v103, v[164:165], off nt
	v_lshl_add_u64 v[164:165], v[32:33], 0, s[4:5]
	global_load_dword v104, v[164:165], off nt
	v_lshl_add_u64 v[164:165], v[30:31], 0, s[4:5]
	global_load_dword v105, v[164:165], off nt
	v_lshl_add_u64 v[164:165], v[28:29], 0, s[4:5]
	global_load_dword v106, v[164:165], off nt
	v_lshl_add_u64 v[164:165], v[26:27], 0, s[4:5]
	global_load_dword v107, v[164:165], off nt
	s_add_u32 s4, s4, 0x20000
	s_addc_u32 s5, s5, 0
	v_lshl_add_u64 v[164:165], v[40:41], 0, s[4:5]
	global_load_dword v108, v[164:165], off nt
	v_lshl_add_u64 v[164:165], v[38:39], 0, s[4:5]
	global_load_dword v109, v[164:165], off nt
	v_lshl_add_u64 v[164:165], v[36:37], 0, s[4:5]
	global_load_dword v110, v[164:165], off nt
	v_lshl_add_u64 v[164:165], v[34:35], 0, s[4:5]
	global_load_dword v111, v[164:165], off nt
	v_lshl_add_u64 v[164:165], v[32:33], 0, s[4:5]
	global_load_dword v112, v[164:165], off nt
	v_lshl_add_u64 v[164:165], v[30:31], 0, s[4:5]
	global_load_dword v113, v[164:165], off nt
	v_lshl_add_u64 v[164:165], v[28:29], 0, s[4:5]
	global_load_dword v114, v[164:165], off nt
	v_lshl_add_u64 v[164:165], v[26:27], 0, s[4:5]
	global_load_dword v115, v[164:165], off nt
	s_add_u32 s4, s4, 0x20000
	s_addc_u32 s5, s5, 0
	v_lshl_add_u64 v[164:165], v[40:41], 0, s[4:5]
	global_load_dword v116, v[164:165], off nt
	v_lshl_add_u64 v[164:165], v[38:39], 0, s[4:5]
	global_load_dword v117, v[164:165], off nt
	v_lshl_add_u64 v[164:165], v[36:37], 0, s[4:5]
	global_load_dword v118, v[164:165], off nt
	v_lshl_add_u64 v[164:165], v[34:35], 0, s[4:5]
	global_load_dword v119, v[164:165], off nt
	v_lshl_add_u64 v[164:165], v[32:33], 0, s[4:5]
	global_load_dword v120, v[164:165], off nt
	v_lshl_add_u64 v[164:165], v[30:31], 0, s[4:5]
	global_load_dword v121, v[164:165], off nt
	v_lshl_add_u64 v[164:165], v[28:29], 0, s[4:5]
	global_load_dword v122, v[164:165], off nt
	v_lshl_add_u64 v[164:165], v[26:27], 0, s[4:5]
	global_load_dword v123, v[164:165], off nt
	s_add_u32 s4, s4, 0x20000
	s_addc_u32 s5, s5, 0
	v_lshl_add_u64 v[164:165], v[40:41], 0, s[4:5]
	global_load_dword v124, v[164:165], off nt
	v_lshl_add_u64 v[164:165], v[38:39], 0, s[4:5]
	global_load_dword v125, v[164:165], off nt
	v_lshl_add_u64 v[164:165], v[36:37], 0, s[4:5]
	global_load_dword v126, v[164:165], off nt
	v_lshl_add_u64 v[164:165], v[34:35], 0, s[4:5]
	global_load_dword v127, v[164:165], off nt
	v_lshl_add_u64 v[164:165], v[32:33], 0, s[4:5]
	global_load_dword v128, v[164:165], off nt
	v_lshl_add_u64 v[164:165], v[30:31], 0, s[4:5]
	global_load_dword v129, v[164:165], off nt
	v_lshl_add_u64 v[164:165], v[28:29], 0, s[4:5]
	global_load_dword v130, v[164:165], off nt
	v_lshl_add_u64 v[164:165], v[26:27], 0, s[4:5]
	global_load_dword v131, v[164:165], off nt
	s_add_u32 s4, s4, 0x20000
	s_addc_u32 s5, s5, 0
	s_waitcnt vmcnt(24)
	ds_write_b32 v4, v100
	ds_write_b32 v4, v101 offset:264
	ds_write_b32 v4, v102 offset:528
	ds_write_b32 v4, v103 offset:792
	ds_write_b32 v4, v104 offset:1056
	ds_write_b32 v4, v105 offset:1320
	ds_write_b32 v4, v106 offset:1584
	ds_write_b32 v4, v107 offset:1848
	s_waitcnt vmcnt(16)
	ds_write_b32 v4, v108 offset:2112
	ds_write_b32 v4, v109 offset:2376
	ds_write_b32 v4, v110 offset:2640
	ds_write_b32 v4, v111 offset:2904
	ds_write_b32 v4, v112 offset:3168
	ds_write_b32 v4, v113 offset:3432
	ds_write_b32 v4, v114 offset:3696
	ds_write_b32 v4, v115 offset:3960
	s_waitcnt vmcnt(8)
	ds_write_b32 v4, v116 offset:4224
	ds_write_b32 v4, v117 offset:4488
	ds_write_b32 v4, v118 offset:4752
	ds_write_b32 v4, v119 offset:5016
	ds_write_b32 v4, v120 offset:5280
	ds_write_b32 v4, v121 offset:5544
	ds_write_b32 v4, v122 offset:5808
	ds_write_b32 v4, v123 offset:6072
	s_waitcnt vmcnt(0)
	ds_write_b32 v4, v124 offset:6336
	ds_write_b32 v4, v125 offset:6600
	ds_write_b32 v4, v126 offset:6864
	ds_write_b32 v4, v127 offset:7128
	ds_write_b32 v4, v128 offset:7392
	ds_write_b32 v4, v129 offset:7656
	ds_write_b32 v4, v130 offset:7920
	ds_write_b32 v4, v131 offset:8184
	v_add_u32_e32 v4, 0x2100, v4
	s_lshl_b32 s4, s3, 5
	s_waitcnt lgkmcnt(0)
	ds_read2_b32 v[100:101], v19 offset1:33
	ds_read2_b32 v[102:103], v19 offset0:66 offset1:99
	ds_read2_b32 v[104:105], v19 offset0:132 offset1:165
	ds_read2_b32 v[106:107], v19 offset0:198 offset1:231
	ds_read2_b32 v[108:109], v19 offset0:8 offset1:41
	ds_read2_b32 v[110:111], v19 offset0:74 offset1:107
	ds_read2_b32 v[112:113], v19 offset0:140 offset1:173
	ds_read2_b32 v[114:115], v19 offset0:206 offset1:239
	ds_read2_b32 v[116:117], v19 offset0:16 offset1:49
	ds_read2_b32 v[118:119], v19 offset0:82 offset1:115
	ds_read2_b32 v[120:121], v19 offset0:148 offset1:181
	ds_read2_b32 v[122:123], v19 offset0:214 offset1:247
	ds_read2_b32 v[124:125], v19 offset0:24 offset1:57
	ds_read2_b32 v[126:127], v19 offset0:90 offset1:123
	ds_read2_b32 v[128:129], v19 offset0:156 offset1:189
	ds_read2_b32 v[130:131], v19 offset0:222 offset1:255
	s_waitcnt lgkmcnt(0)
	s_and_b32 s4, s4, 0x7e0
	v_or_b32_e32 v4, s4, v3
	s_waitcnt lgkmcnt(0)
	v_cvt_pk_bf16_f32 v26, v100, v101
	s_addk_i32 s0, 0xb400
	v_mul_u32_u24_e32 v4, 0x1600, v4
	s_waitcnt lgkmcnt(0)
	v_cvt_pk_bf16_f32 v27, v102, v103
	v_lshl_add_u64 v[32:33], s[0:1], 1, v[6:7]
	v_lshlrev_b32_e32 v4, 1, v4
	s_waitcnt lgkmcnt(0)
	v_cvt_pk_bf16_f32 v28, v104, v105
	s_waitcnt lgkmcnt(0)
	v_cvt_pk_bf16_f32 v29, v106, v107
	v_lshl_add_u64 v[34:35], v[32:33], 0, v[4:5]
	v_or_b32_e32 v4, s4, v49
	global_store_dwordx4 v[34:35], v[26:29], off
	v_mul_u32_u24_e32 v4, 0x1600, v4
	v_lshlrev_b32_e32 v4, 1, v4
	s_waitcnt lgkmcnt(0)
	v_cvt_pk_bf16_f32 v26, v108, v109
	s_waitcnt lgkmcnt(0)
	v_cvt_pk_bf16_f32 v27, v110, v111
	s_waitcnt lgkmcnt(0)
	v_cvt_pk_bf16_f32 v28, v112, v113
	s_waitcnt lgkmcnt(0)
	v_cvt_pk_bf16_f32 v29, v114, v115
	v_lshl_add_u64 v[34:35], v[32:33], 0, v[4:5]
	v_or_b32_e32 v4, s4, v50
	global_store_dwordx4 v[34:35], v[26:29], off
	v_mul_u32_u24_e32 v4, 0x1600, v4
	v_lshlrev_b32_e32 v4, 1, v4
	s_waitcnt lgkmcnt(0)
	v_cvt_pk_bf16_f32 v26, v116, v117
	s_waitcnt lgkmcnt(0)
	v_cvt_pk_bf16_f32 v27, v118, v119
	s_waitcnt lgkmcnt(0)
	v_cvt_pk_bf16_f32 v28, v120, v121
	s_waitcnt lgkmcnt(0)
	v_cvt_pk_bf16_f32 v29, v122, v123
	v_lshl_add_u64 v[34:35], v[32:33], 0, v[4:5]
	global_store_dwordx4 v[34:35], v[26:29], off
	v_or_b32_e32 v4, s4, v51
	v_mul_u32_u24_e32 v4, 0x1600, v4
	s_waitcnt lgkmcnt(0)
	v_cvt_pk_bf16_f32 v26, v124, v125
	s_waitcnt lgkmcnt(0)
	v_cvt_pk_bf16_f32 v27, v126, v127
	s_waitcnt lgkmcnt(0)
	v_cvt_pk_bf16_f32 v28, v128, v129
	v_lshlrev_b32_e32 v4, 1, v4
	s_waitcnt lgkmcnt(0)
	v_cvt_pk_bf16_f32 v29, v130, v131
	v_lshl_add_u64 v[30:31], v[32:33], 0, v[4:5]
	global_store_dwordx4 v[30:31], v[26:29], off
	s_waitcnt lgkmcnt(0)
	s_mov_b64 s[4:5], 0

;     const int nblk = N / 32, kb = item / nblk, nb = item % nblk, k0 = 64 * kb, n0 = 32 * nb;
; #pragma unroll 8
;     for (int i = 0; i < 32; ++i) { const int kk = 2 * i + (lane >> 5); float v = __builtin_nontemporal_load(W + (size_t)(k0 + kk) * N + n0 + (lane & 31)); if (gain) v *= gain[k0 + kk]; scr[kk * 33 + (lane & 31)] = v; }
;     asm volatile("s_waitcnt lgkmcnt(0)" ::: "memory");
.LBB0_57:
.LBB0_58:
	v_cndmask_b32_e64 v45, 0, 1, s[96:97]
	v_cmp_ne_u32_e64 s[4:5], 1, v45
	s_andn2_b64 vcc, exec, s[96:97]
	s_cbranch_vccnz .Lcvt_rows_2
	v_mbcnt_lo_u32_b32 v166, -1, 0
	v_mbcnt_hi_u32_b32 v166, -1, v166
	v_lshrrev_b32_e32 v169, 5, v166
	v_lshlrev_b32_e32 v169, 2, v169
	v_lshlrev_b32_e32 v166, 2, v166
	v_sub_u32_e32 v166, v166, v169
	v_mov_b32_e32 v167, 0
	v_lshl_add_u64 v[164:165], s[10:11], 0, v[4:5]
	v_lshl_add_u64 v[164:165], v[164:165], 0, v[166:167]
	global_load_dword v168, v[164:165], off
.Lcvt_rows_2:
	v_lshl_add_u64 v[164:165], v[42:43], 0, s[6:7]
	global_load_dword v100, v[164:165], off nt
	v_lshl_add_u64 v[164:165], v[40:41], 0, s[6:7]
	global_load_dword v101, v[164:165], off nt
	v_lshl_add_u64 v[164:165], v[38:39], 0, s[6:7]
	global_load_dword v102, v[164:165], off nt
	v_lshl_add_u64 v[164:165], v[36:37], 0, s[6:7]
	global_load_dword v103, v[164:165], off nt
	v_lshl_add_u64 v[164:165], v[34:35], 0, s[6:7]
	global_load_dword v104, v[164:165], off nt
	v_lshl_add_u64 v[164:165], v[32:33], 0, s[6:7]
	global_load_dword v105, v[164:165], off nt
	v_lshl_add_u64 v[164:165], v[30:31], 0, s[6:7]
	global_load_dword v106, v[164:165], off nt
	v_lshl_add_u64 v[164:165], v[26:27], 0, s[6:7]
	global_load_dword v107, v[164:165], off nt
	s_add_u32 s6, s6, 0x58000
	s_addc_u32 s7, s7, 0
	v_lshl_add_u64 v[164:165], v[42:43], 0, s[6:7]
	global_load_dword v108, v[164:165], off nt
	v_lshl_add_u64 v[164:165], v[40:41], 0, s[6:7]
	global_load_dword v109, v[164:165], off nt
	v_lshl_add_u64 v[164:165], v[38:39], 0, s[6:7]
	global_load_dword v110, v[164:165], off nt
	v_lshl_add_u64 v[164:165], v[36:37], 0, s[6:7]
	global_load_dword v111, v[164:165], off nt
	v_lshl_add_u64 v[164:165], v[34:35], 0, s[6:7]
	global_load_dword v112, v[164:165], off nt
	v_lshl_add_u64 v[164:165], v[32:33], 0, s[6:7]
	global_load_dword v113, v[164:165], off nt
	v_lshl_add_u64 v[164:165], v[30:31], 0, s[6:7]
	global_load_dword v114, v[164:165], off nt
	v_lshl_add_u64 v[164:165], v[26:27], 0, s[6:7]
	global_load_dword v115, v[164:165], off nt
	s_add_u32 s6, s6, 0x58000
	s_addc_u32 s7, s7, 0
	v_lshl_add_u64 v[164:165], v[42:43], 0, s[6:7]
	global_load_dword v116, v[164:165], off nt
	v_lshl_add_u64 v[164:165], v[40:41], 0, s[6:7]
	global_load_dword v117, v[164:165], off nt
	v_lshl_add_u64 v[164:165], v[38:39], 0, s[6:7]
	global_load_dword v118, v[164:165], off nt
	v_lshl_add_u64 v[164:165], v[36:37], 0, s[6:7]
	global_load_dword v119, v[164:165], off nt
	v_lshl_add_u64 v[164:165], v[34:35], 0, s[6:7]
	global_load_dword v120, v[164:165], off nt
	v_lshl_add_u64 v[164:165], v[32:33], 0, s[6:7]
	global_load_dword v121, v[164:165], off nt
	v_lshl_add_u64 v[164:165], v[30:31], 0, s[6:7]
	global_load_dword v122, v[164:165], off nt
	v_lshl_add_u64 v[164:165], v[26:27], 0, s[6:7]
	global_load_dword v123, v[164:165], off nt
	s_add_u32 s6, s6, 0x58000
	s_addc_u32 s7, s7, 0
	v_lshl_add_u64 v[164:165], v[42:43], 0, s[6:7]
	global_load_dword v124, v[164:165], off nt
	v_lshl_add_u64 v[164:165], v[40:41], 0, s[6:7]
	global_load_dword v125, v[164:165], off nt
	v_lshl_add_u64 v[164:165], v[38:39], 0, s[6:7]
	global_load_dword v126, v[164:165], off nt
	v_lshl_add_u64 v[164:165], v[36:37], 0, s[6:7]
	global_load_dword v127, v[164:165], off nt
	v_lshl_add_u64 v[164:165], v[34:35], 0, s[6:7]
	global_load_dword v128, v[164:165], off nt
	v_lshl_add_u64 v[164:165], v[32:33], 0, s[6:7]
	global_load_dword v129, v[164:165], off nt
	v_lshl_add_u64 v[164:165], v[30:31], 0, s[6:7]
	global_load_dword v130, v[164:165], off nt
	v_lshl_add_u64 v[164:165], v[26:27], 0, s[6:7]
	global_load_dword v131, v[164:165], off nt
	s_add_u32 s6, s6, 0x58000
	s_addc_u32 s7, s7, 0
	v_cndmask_b32_e64 v45, 0, 1, s[96:97]
	v_cmp_ne_u32_e64 s[4:5], 1, v45
	s_andn2_b64 vcc, exec, s[96:97]
	s_cbranch_vccnz .Lcvt_put_2
	s_waitcnt vmcnt(32)
	ds_bpermute_b32 v132, v169, v168
	ds_bpermute_b32 v133, v169, v168 offset:8
	ds_bpermute_b32 v134, v169, v168 offset:16
	ds_bpermute_b32 v135, v169, v168 offset:24
	ds_bpermute_b32 v136, v169, v168 offset:32
	ds_bpermute_b32 v137, v169, v168 offset:40
	ds_bpermute_b32 v138, v169, v168 offset:48
	ds_bpermute_b32 v139, v169, v168 offset:56
	ds_bpermute_b32 v140, v169, v168 offset:64
	ds_bpermute_b32 v141, v169, v168 offset:72
	ds_bpermute_b32 v142, v169, v168 offset:80
	ds_bpermute_b32 v143, v169, v168 offset:88
	ds_bpermute_b32 v144, v169, v168 offset:96
	ds_bpermute_b32 v145, v169, v168 offset:104
	ds_bpermute_b32 v146, v169, v168 offset:112
	ds_bpermute_b32 v147, v169, v168 offset:120
	ds_bpermute_b32 v148, v169, v168 offset:128
	ds_bpermute_b32 v149, v169, v168 offset:136
	ds_bpermute_b32 v150, v169, v168 offset:144
	ds_bpermute_b32 v151, v169, v168 offset:152
	ds_bpermute_b32 v152, v169, v168 offset:160
	ds_bpermute_b32 v153, v169, v168 offset:168
	ds_bpermute_b32 v154, v169, v168 offset:176
	ds_bpermute_b32 v155, v169, v168 offset:184
	ds_bpermute_b32 v156, v169, v168 offset:192
	ds_bpermute_b32 v157, v169, v168 offset:200
	ds_bpermute_b32 v158, v169, v168 offset:208
	ds_bpermute_b32 v159, v169, v168 offset:216
	ds_bpermute_b32 v160, v169, v168 offset:224
	ds_bpermute_b32 v161, v169, v168 offset:232
	ds_bpermute_b32 v162, v169, v168 offset:240
	ds_bpermute_b32 v163, v169, v168 offset:248
	s_waitcnt vmcnt(0) lgkmcnt(0)
	v_mul_f32_e32 v100, v100, v132
	v_mul_f32_e32 v101, v101, v133
	v_mul_f32_e32 v102, v102, v134
	v_mul_f32_e32 v103, v103, v135
	v_mul_f32_e32 v104, v104, v136
	v_mul_f32_e32 v105, v105, v137
	v_mul_f32_e32 v106, v106, v138
	v_mul_f32_e32 v107, v107, v139
	v_mul_f32_e32 v108, v108, v140
	v_mul_f32_e32 v109, v109, v141
	v_mul_f32_e32 v110, v110, v142
	v_mul_f32_e32 v111, v111, v143
	v_mul_f32_e32 v112, v112, v144
	v_mul_f32_e32 v113, v113, v145
	v_mul_f32_e32 v114, v114, v146
	v_mul_f32_e32 v115, v115, v147
	v_mul_f32_e32 v116, v116, v148
	v_mul_f32_e32 v117, v117, v149
	v_mul_f32_e32 v118, v118, v150
	v_mul_f32_e32 v119, v119, v151
	v_mul_f32_e32 v120, v120, v152
	v_mul_f32_e32 v121, v121, v153
	v_mul_f32_e32 v122, v122, v154
	v_mul_f32_e32 v123, v123, v155
	v_mul_f32_e32 v124, v124, v156
	v_mul_f32_e32 v125, v125, v157
	v_mul_f32_e32 v126, v126, v158
	v_mul_f32_e32 v127, v127, v159
	v_mul_f32_e32 v128, v128, v160
	v_mul_f32_e32 v129, v129, v161
	v_mul_f32_e32 v130, v130, v162
	v_mul_f32_e32 v131, v131, v163
; #define LAS __attribute__((address_space(3)))
; __device__ __forceinline__ unsigned cvt_pk_bf16(float lo, float hi) { unsigned r; asm volatile("v_cvt_pk_bf16_f32 %0, %1, %2" : "=v"(r) : "v"(lo), "v"(hi)); return r; }
;     ...
;     for (int i = 0; i < 32; ++i) { const int kk = 2 * i + (lane >> 5); float v = __builtin_nontemporal_load(W + (size_t)(k0 + kk) * N + n0 + (lane & 31)); if (gain) v *= gain[k0 + kk]; scr[kk * 33 + (lane & 31)] = v; }
;     asm volatile("s_waitcnt lgkmcnt(0)" ::: "memory");
;     const int c = lane & 7;
; #pragma unroll
;     for (int j = 0; j < 4; ++j) { const int n = (lane >> 3) + 8 * j; const LAS float* s = scr + (8 * c) * 33 + n;
;         u32x4 o; o.x = cvt_pk_bf16(s[0 * 33], s[1 * 33]); o.y = cvt_pk_bf16(s[2 * 33], s[3 * 33]); o.z = cvt_pk_bf16(s[4 * 33], s[5 * 33]); o.w = cvt_pk_bf16(s[6 * 33], s[7 * 33]);
;         const int nn = n0 + n; const int orow = mode ? ((nn >> 7) * 256 + (nn & 127) + (mode == 2 ? 128 : 0)) : nn;
;         *(u32x4*)(WT + (size_t)orow * K + k0 + 8 * c) = o; }
;     asm volatile("s_waitcnt lgkmcnt(0)" ::: "memory");
.Lcvt_put_2:
	s_waitcnt vmcnt(0)
	ds_write_b32 v46, v100
	ds_write_b32 v46, v101 offset:264
	ds_write_b32 v46, v102 offset:528
	ds_write_b32 v46, v103 offset:792
	ds_write_b32 v46, v104 offset:1056
	ds_write_b32 v46, v105 offset:1320
	ds_write_b32 v46, v106 offset:1584
	ds_write_b32 v46, v107 offset:1848
	ds_write_b32 v46, v108 offset:2112
	ds_write_b32 v46, v109 offset:2376
	ds_write_b32 v46, v110 offset:2640
	ds_write_b32 v46, v111 offset:2904
	ds_write_b32 v46, v112 offset:3168
	ds_write_b32 v46, v113 offset:3432
	ds_write_b32 v46, v114 offset:3696
	ds_write_b32 v46, v115 offset:3960
	ds_write_b32 v46, v116 offset:4224
	ds_write_b32 v46, v117 offset:4488
	ds_write_b32 v46, v118 offset:4752
	ds_write_b32 v46, v119 offset:5016
	ds_write_b32 v46, v120 offset:5280
	ds_write_b32 v46, v121 offset:5544
	ds_write_b32 v46, v122 offset:5808
	ds_write_b32 v46, v123 offset:6072
	ds_write_b32 v46, v124 offset:6336
	ds_write_b32 v46, v125 offset:6600
	ds_write_b32 v46, v126 offset:6864
	ds_write_b32 v46, v127 offset:7128
	ds_write_b32 v46, v128 offset:7392
	ds_write_b32 v46, v129 offset:7656
	ds_write_b32 v46, v130 offset:7920
	ds_write_b32 v46, v131 offset:8184
	v_add_u32_e32 v46, 0x2100, v46
	s_add_u32 s10, s10, 0x100
	s_addc_u32 s11, s11, 0
	s_branch .LBB0_74
.LBB0_74:
	s_lshl_b32 s0, s19, 6
	s_waitcnt lgkmcnt(0)
	ds_read2_b32 v[100:101], v19 offset1:33
	ds_read2_b32 v[102:103], v19 offset0:66 offset1:99
	ds_read2_b32 v[104:105], v19 offset0:132 offset1:165
	ds_read2_b32 v[106:107], v19 offset0:198 offset1:231
	ds_read2_b32 v[108:109], v19 offset0:8 offset1:41
	ds_read2_b32 v[110:111], v19 offset0:74 offset1:107
	ds_read2_b32 v[112:113], v19 offset0:140 offset1:173
	ds_read2_b32 v[114:115], v19 offset0:206 offset1:239
	ds_read2_b32 v[116:117], v19 offset0:16 offset1:49
	ds_read2_b32 v[118:119], v19 offset0:82 offset1:115
	ds_read2_b32 v[120:121], v19 offset0:148 offset1:181
	ds_read2_b32 v[122:123], v19 offset0:214 offset1:247
	ds_read2_b32 v[124:125], v19 offset0:24 offset1:57
	ds_read2_b32 v[126:127], v19 offset0:90 offset1:123
	ds_read2_b32 v[128:129], v19 offset0:156 offset1:189
	ds_read2_b32 v[130:131], v19 offset0:222 offset1:255
	s_waitcnt lgkmcnt(0)
	s_and_b32 s5, s13, 0x60
	s_and_b32 s6, s0, 0x3f00
	s_and_b32 s4, 0xffff, s20
	v_or_b32_e32 v4, s5, v3
	s_bitset1_b32 s6, 7
	s_waitcnt lgkmcnt(0)
	v_cvt_pk_bf16_f32 v26, v100, v101
	s_lshl_b32 s0, s4, 1
	v_or_b32_e32 v4, s6, v4
	s_waitcnt lgkmcnt(0)
	v_cvt_pk_bf16_f32 v27, v102, v103
	v_lshl_add_u64 v[32:33], v[8:9], 0, s[0:1]
	v_lshlrev_b32_e32 v4, 12, v4
	s_waitcnt lgkmcnt(0)
	v_cvt_pk_bf16_f32 v28, v104, v105
	s_waitcnt lgkmcnt(0)
	v_cvt_pk_bf16_f32 v29, v106, v107
	v_lshl_add_u64 v[34:35], v[32:33], 0, v[4:5]
	v_or_b32_e32 v4, s5, v49
	global_store_dwordx4 v[34:35], v[26:29], off
	v_or_b32_e32 v4, s6, v4
	v_lshlrev_b32_e32 v4, 12, v4
	s_waitcnt lgkmcnt(0)
	v_cvt_pk_bf16_f32 v26, v108, v109
	s_waitcnt lgkmcnt(0)
	v_cvt_pk_bf16_f32 v27, v110, v111
	s_waitcnt lgkmcnt(0)
	v_cvt_pk_bf16_f32 v28, v112, v113
	s_waitcnt lgkmcnt(0)
	v_cvt_pk_bf16_f32 v29, v114, v115
	v_lshl_add_u64 v[34:35], v[32:33], 0, v[4:5]
	v_or_b32_e32 v4, s5, v50
	global_store_dwordx4 v[34:35], v[26:29], off
	v_or_b32_e32 v4, s6, v4
	v_lshlrev_b32_e32 v4, 12, v4
	s_waitcnt lgkmcnt(0)
	v_cvt_pk_bf16_f32 v26, v116, v117
	s_waitcnt lgkmcnt(0)
	v_cvt_pk_bf16_f32 v27, v118, v119
	s_waitcnt lgkmcnt(0)
	v_cvt_pk_bf16_f32 v28, v120, v121
	s_waitcnt lgkmcnt(0)
	v_cvt_pk_bf16_f32 v29, v122, v123
	v_lshl_add_u64 v[34:35], v[32:33], 0, v[4:5]
	global_store_dwordx4 v[34:35], v[26:29], off
	v_or_b32_e32 v4, s5, v51
	v_or_b32_e32 v4, s6, v4
	s_waitcnt lgkmcnt(0)
	v_cvt_pk_bf16_f32 v26, v124, v125
	s_waitcnt lgkmcnt(0)
	v_cvt_pk_bf16_f32 v27, v126, v127
	s_waitcnt lgkmcnt(0)
	v_cvt_pk_bf16_f32 v28, v128, v129
	v_lshlrev_b32_e32 v4, 12, v4
	s_waitcnt lgkmcnt(0)
	v_cvt_pk_bf16_f32 v29, v130, v131
	v_lshl_add_u64 v[30:31], v[32:33], 0, v[4:5]
	global_store_dwordx4 v[30:31], v[26:29], off
	s_waitcnt lgkmcnt(0)

; #define LAS __attribute__((address_space(3)))
; __device__ __forceinline__ unsigned cvt_pk_bf16(float lo, float hi) { unsigned r; asm volatile("v_cvt_pk_bf16_f32 %0, %1, %2" : "=v"(r) : "v"(lo), "v"(hi)); return r; }
;     ...
;     const int c = lane & 7;
; #pragma unroll
;     for (int j = 0; j < 4; ++j) { const int n = (lane >> 3) + 8 * j; const LAS float* s = scr + (8 * c) * 33 + n;
;         u32x4 o; o.x = cvt_pk_bf16(s[0 * 33], s[1 * 33]); o.y = cvt_pk_bf16(s[2 * 33], s[3 * 33]); o.z = cvt_pk_bf16(s[4 * 33], s[5 * 33]); o.w = cvt_pk_bf16(s[6 * 33], s[7 * 33]);
;         const int nn = n0 + n; const int orow = mode ? ((nn >> 7) * 256 + (nn & 127) + (mode == 2 ? 128 : 0)) : nn;
;         *(u32x4*)(WT + (size_t)orow * K + k0 + 8 * c) = o; }
;     asm volatile("s_waitcnt lgkmcnt(0)" ::: "memory");
.LBB0_95:
	s_waitcnt lgkmcnt(0)
	ds_read2_b32 v[100:101], v19 offset1:33
	ds_read2_b32 v[102:103], v19 offset0:66 offset1:99
	ds_read2_b32 v[104:105], v19 offset0:132 offset1:165
	ds_read2_b32 v[106:107], v19 offset0:198 offset1:231
	ds_read2_b32 v[108:109], v19 offset0:8 offset1:41
	ds_read2_b32 v[110:111], v19 offset0:74 offset1:107
	ds_read2_b32 v[112:113], v19 offset0:140 offset1:173
	ds_read2_b32 v[114:115], v19 offset0:206 offset1:239
	ds_read2_b32 v[116:117], v19 offset0:16 offset1:49
	ds_read2_b32 v[118:119], v19 offset0:82 offset1:115
	ds_read2_b32 v[120:121], v19 offset0:148 offset1:181
	ds_read2_b32 v[122:123], v19 offset0:214 offset1:247
	ds_read2_b32 v[124:125], v19 offset0:24 offset1:57
	ds_read2_b32 v[126:127], v19 offset0:90 offset1:123
	ds_read2_b32 v[128:129], v19 offset0:156 offset1:189
	ds_read2_b32 v[130:131], v19 offset0:222 offset1:255
	s_waitcnt lgkmcnt(0)
	s_lshl_b32 s0, s19, 6
	s_and_b32 s5, s13, 0x60
	s_and_b32 s4, 0xffff, s20
	s_and_b32 s6, s0, 0x3f00
	v_or_b32_e32 v4, s5, v3
	s_waitcnt lgkmcnt(0)
	v_cvt_pk_bf16_f32 v26, v100, v101
	s_lshl_b32 s0, s4, 1
	v_or_b32_e32 v4, s6, v4
	s_waitcnt lgkmcnt(0)
	v_cvt_pk_bf16_f32 v27, v102, v103
	v_lshl_add_u64 v[32:33], v[8:9], 0, s[0:1]
	v_lshlrev_b32_e32 v4, 12, v4
	s_waitcnt lgkmcnt(0)
	v_cvt_pk_bf16_f32 v28, v104, v105
	s_waitcnt lgkmcnt(0)
	v_cvt_pk_bf16_f32 v29, v106, v107
	v_lshl_add_u64 v[34:35], v[32:33], 0, v[4:5]
	v_or_b32_e32 v4, s5, v49
	global_store_dwordx4 v[34:35], v[26:29], off
	v_or_b32_e32 v4, s6, v4
	v_lshlrev_b32_e32 v4, 12, v4
	s_waitcnt lgkmcnt(0)
	v_cvt_pk_bf16_f32 v26, v108, v109
	s_waitcnt lgkmcnt(0)
	v_cvt_pk_bf16_f32 v27, v110, v111
	s_waitcnt lgkmcnt(0)
	v_cvt_pk_bf16_f32 v28, v112, v113
	s_waitcnt lgkmcnt(0)
	v_cvt_pk_bf16_f32 v29, v114, v115
	v_lshl_add_u64 v[34:35], v[32:33], 0, v[4:5]
	v_or_b32_e32 v4, s5, v50
	global_store_dwordx4 v[34:35], v[26:29], off
	v_or_b32_e32 v4, s6, v4
	v_lshlrev_b32_e32 v4, 12, v4
	s_waitcnt lgkmcnt(0)
	v_cvt_pk_bf16_f32 v26, v116, v117
	s_waitcnt lgkmcnt(0)
	v_cvt_pk_bf16_f32 v27, v118, v119
	s_waitcnt lgkmcnt(0)
	v_cvt_pk_bf16_f32 v28, v120, v121
	s_waitcnt lgkmcnt(0)
	v_cvt_pk_bf16_f32 v29, v122, v123
	v_lshl_add_u64 v[34:35], v[32:33], 0, v[4:5]
	global_store_dwordx4 v[34:35], v[26:29], off
	v_or_b32_e32 v4, s5, v51
	v_or_b32_e32 v4, s6, v4
	s_waitcnt lgkmcnt(0)
	v_cvt_pk_bf16_f32 v26, v124, v125
	s_waitcnt lgkmcnt(0)
	v_cvt_pk_bf16_f32 v27, v126, v127
	s_waitcnt lgkmcnt(0)
	v_cvt_pk_bf16_f32 v28, v128, v129
	v_lshlrev_b32_e32 v4, 12, v4
	s_waitcnt lgkmcnt(0)
	v_cvt_pk_bf16_f32 v29, v130, v131
	v_lshl_add_u64 v[30:31], v[32:33], 0, v[4:5]
	global_store_dwordx4 v[30:31], v[26:29], off
	s_waitcnt lgkmcnt(0)

; #define LAS __attribute__((address_space(3)))
; __device__ __forceinline__ unsigned cvt_pk_bf16(float lo, float hi) { unsigned r; asm volatile("v_cvt_pk_bf16_f32 %0, %1, %2" : "=v"(r) : "v"(lo), "v"(hi)); return r; }
;     const int nblk = N / 32, kb = item / nblk, nb = item % nblk, k0 = 64 * kb, n0 = 32 * nb;
; #pragma unroll 8
;     for (int i = 0; i < 32; ++i) { const int kk = 2 * i + (lane >> 5); float v = __builtin_nontemporal_load(W + (size_t)(k0 + kk) * N + n0 + (lane & 31)); if (gain) v *= gain[k0 + kk]; scr[kk * 33 + (lane & 31)] = v; }
;     asm volatile("s_waitcnt lgkmcnt(0)" ::: "memory");
;     const int c = lane & 7;
; #pragma unroll
;     for (int j = 0; j < 4; ++j) { const int n = (lane >> 3) + 8 * j; const LAS float* s = scr + (8 * c) * 33 + n;
;         u32x4 o; o.x = cvt_pk_bf16(s[0 * 33], s[1 * 33]); o.y = cvt_pk_bf16(s[2 * 33], s[3 * 33]); o.z = cvt_pk_bf16(s[4 * 33], s[5 * 33]); o.w = cvt_pk_bf16(s[6 * 33], s[7 * 33]);
;         const int nn = n0 + n; const int orow = mode ? ((nn >> 7) * 256 + (nn & 127) + (mode == 2 ? 128 : 0)) : nn;
;         *(u32x4*)(WT + (size_t)orow * K + k0 + 8 * c) = o; }
;     asm volatile("s_waitcnt lgkmcnt(0)" ::: "memory");
.LBB0_99:
	v_lshl_add_u64 v[164:165], v[40:41], 0, s[4:5]
	global_load_dword v100, v[164:165], off nt
	v_lshl_add_u64 v[164:165], v[38:39], 0, s[4:5]
	global_load_dword v101, v[164:165], off nt
	v_lshl_add_u64 v[164:165], v[36:37], 0, s[4:5]
	global_load_dword v102, v[164:165], off nt
	v_lshl_add_u64 v[164:165], v[34:35], 0, s[4:5]
	global_load_dword v103, v[164:165], off nt
	v_lshl_add_u64 v[164:165], v[32:33], 0, s[4:5]
	global_load_dword v104, v[164:165], off nt
	v_lshl_add_u64 v[164:165], v[30:31], 0, s[4:5]
	global_load_dword v105, v[164:165], off nt
	v_lshl_add_u64 v[164:165], v[28:29], 0, s[4:5]
	global_load_dword v106, v[164:165], off nt
	v_lshl_add_u64 v[164:165], v[26:27], 0, s[4:5]
	global_load_dword v107, v[164:165], off nt
	s_add_u32 s4, s4, 0x20000
	s_addc_u32 s5, s5, 0
	v_lshl_add_u64 v[164:165], v[40:41], 0, s[4:5]
	global_load_dword v108, v[164:165], off nt
	v_lshl_add_u64 v[164:165], v[38:39], 0, s[4:5]
	global_load_dword v109, v[164:165], off nt
	v_lshl_add_u64 v[164:165], v[36:37], 0, s[4:5]
	global_load_dword v110, v[164:165], off nt
	v_lshl_add_u64 v[164:165], v[34:35], 0, s[4:5]
	global_load_dword v111, v[164:165], off nt
	v_lshl_add_u64 v[164:165], v[32:33], 0, s[4:5]
	global_load_dword v112, v[164:165], off nt
	v_lshl_add_u64 v[164:165], v[30:31], 0, s[4:5]
	global_load_dword v113, v[164:165], off nt
	v_lshl_add_u64 v[164:165], v[28:29], 0, s[4:5]
	global_load_dword v114, v[164:165], off nt
	v_lshl_add_u64 v[164:165], v[26:27], 0, s[4:5]
	global_load_dword v115, v[164:165], off nt
	s_add_u32 s4, s4, 0x20000
	s_addc_u32 s5, s5, 0
	v_lshl_add_u64 v[164:165], v[40:41], 0, s[4:5]
	global_load_dword v116, v[164:165], off nt
	v_lshl_add_u64 v[164:165], v[38:39], 0, s[4:5]
	global_load_dword v117, v[164:165], off nt
	v_lshl_add_u64 v[164:165], v[36:37], 0, s[4:5]
	global_load_dword v118, v[164:165], off nt
	v_lshl_add_u64 v[164:165], v[34:35], 0, s[4:5]
	global_load_dword v119, v[164:165], off nt
	v_lshl_add_u64 v[164:165], v[32:33], 0, s[4:5]
	global_load_dword v120, v[164:165], off nt
	v_lshl_add_u64 v[164:165], v[30:31], 0, s[4:5]
	global_load_dword v121, v[164:165], off nt
	v_lshl_add_u64 v[164:165], v[28:29], 0, s[4:5]
	global_load_dword v122, v[164:165], off nt
	v_lshl_add_u64 v[164:165], v[26:27], 0, s[4:5]
	global_load_dword v123, v[164:165], off nt
	s_add_u32 s4, s4, 0x20000
	s_addc_u32 s5, s5, 0
	v_lshl_add_u64 v[164:165], v[40:41], 0, s[4:5]
	global_load_dword v124, v[164:165], off nt
	v_lshl_add_u64 v[164:165], v[38:39], 0, s[4:5]
	global_load_dword v125, v[164:165], off nt
	v_lshl_add_u64 v[164:165], v[36:37], 0, s[4:5]
	global_load_dword v126, v[164:165], off nt
	v_lshl_add_u64 v[164:165], v[34:35], 0, s[4:5]
	global_load_dword v127, v[164:165], off nt
	v_lshl_add_u64 v[164:165], v[32:33], 0, s[4:5]
	global_load_dword v128, v[164:165], off nt
	v_lshl_add_u64 v[164:165], v[30:31], 0, s[4:5]
	global_load_dword v129, v[164:165], off nt
	v_lshl_add_u64 v[164:165], v[28:29], 0, s[4:5]
	global_load_dword v130, v[164:165], off nt
	v_lshl_add_u64 v[164:165], v[26:27], 0, s[4:5]
	global_load_dword v131, v[164:165], off nt
	s_add_u32 s4, s4, 0x20000
	s_addc_u32 s5, s5, 0
	s_waitcnt vmcnt(24)
	ds_write_b32 v4, v100
	ds_write_b32 v4, v101 offset:264
	ds_write_b32 v4, v102 offset:528
	ds_write_b32 v4, v103 offset:792
	ds_write_b32 v4, v104 offset:1056
	ds_write_b32 v4, v105 offset:1320
	ds_write_b32 v4, v106 offset:1584
	ds_write_b32 v4, v107 offset:1848
	s_waitcnt vmcnt(16)
	ds_write_b32 v4, v108 offset:2112
	ds_write_b32 v4, v109 offset:2376
	ds_write_b32 v4, v110 offset:2640
	ds_write_b32 v4, v111 offset:2904
	ds_write_b32 v4, v112 offset:3168
	ds_write_b32 v4, v113 offset:3432
	ds_write_b32 v4, v114 offset:3696
	ds_write_b32 v4, v115 offset:3960
	s_waitcnt vmcnt(8)
	ds_write_b32 v4, v116 offset:4224
	ds_write_b32 v4, v117 offset:4488
	ds_write_b32 v4, v118 offset:4752
	ds_write_b32 v4, v119 offset:5016
	ds_write_b32 v4, v120 offset:5280
	ds_write_b32 v4, v121 offset:5544
	ds_write_b32 v4, v122 offset:5808
	ds_write_b32 v4, v123 offset:6072
	s_waitcnt vmcnt(0)
	ds_write_b32 v4, v124 offset:6336
	ds_write_b32 v4, v125 offset:6600
	ds_write_b32 v4, v126 offset:6864
	ds_write_b32 v4, v127 offset:7128
	ds_write_b32 v4, v128 offset:7392
	ds_write_b32 v4, v129 offset:7656
	ds_write_b32 v4, v130 offset:7920
	ds_write_b32 v4, v131 offset:8184
	v_add_u32_e32 v4, 0x2100, v4
	s_waitcnt lgkmcnt(0)
	ds_read2_b32 v[100:101], v19 offset1:33
	ds_read2_b32 v[102:103], v19 offset0:66 offset1:99
	ds_read2_b32 v[104:105], v19 offset0:132 offset1:165
	ds_read2_b32 v[106:107], v19 offset0:198 offset1:231
	ds_read2_b32 v[108:109], v19 offset0:8 offset1:41
	ds_read2_b32 v[110:111], v19 offset0:74 offset1:107
	ds_read2_b32 v[112:113], v19 offset0:140 offset1:173
	ds_read2_b32 v[114:115], v19 offset0:206 offset1:239
	ds_read2_b32 v[116:117], v19 offset0:16 offset1:49
	ds_read2_b32 v[118:119], v19 offset0:82 offset1:115
	ds_read2_b32 v[120:121], v19 offset0:148 offset1:181
	ds_read2_b32 v[122:123], v19 offset0:214 offset1:247
	ds_read2_b32 v[124:125], v19 offset0:24 offset1:57
	ds_read2_b32 v[126:127], v19 offset0:90 offset1:123
	ds_read2_b32 v[128:129], v19 offset0:156 offset1:189
	ds_read2_b32 v[130:131], v19 offset0:222 offset1:255
	s_waitcnt lgkmcnt(0)
	s_add_i32 s0, s3, 0xe800
	s_lshl_b32 s4, s3, 5
	s_and_b32 s0, s0, 0xffc0
	s_and_b32 s4, s4, 0x7e0
	s_waitcnt lgkmcnt(0)
	v_cvt_pk_bf16_f32 v26, v100, v101
	s_lshl_b32 s0, s0, 1
	v_or_b32_e32 v4, s4, v3
	s_waitcnt lgkmcnt(0)
	v_cvt_pk_bf16_f32 v27, v102, v103
	v_lshl_add_u64 v[32:33], v[10:11], 0, s[0:1]
	v_lshlrev_b32_e32 v4, 12, v4
	s_waitcnt lgkmcnt(0)
	v_cvt_pk_bf16_f32 v28, v104, v105
	s_waitcnt lgkmcnt(0)
	v_cvt_pk_bf16_f32 v29, v106, v107
	v_lshl_add_u64 v[34:35], v[32:33], 0, v[4:5]
	global_store_dwordx4 v[34:35], v[26:29], off
	v_or_b32_e32 v4, s4, v49
	v_lshlrev_b32_e32 v4, 12, v4
	s_waitcnt lgkmcnt(0)
	v_cvt_pk_bf16_f32 v26, v108, v109
	s_waitcnt lgkmcnt(0)
	v_cvt_pk_bf16_f32 v27, v110, v111
	s_waitcnt lgkmcnt(0)
	v_cvt_pk_bf16_f32 v28, v112, v113
	s_waitcnt lgkmcnt(0)
	v_cvt_pk_bf16_f32 v29, v114, v115
	v_lshl_add_u64 v[34:35], v[32:33], 0, v[4:5]
	global_store_dwordx4 v[34:35], v[26:29], off
	v_or_b32_e32 v4, s4, v50
	v_lshlrev_b32_e32 v4, 12, v4
	s_waitcnt lgkmcnt(0)
	v_cvt_pk_bf16_f32 v26, v116, v117
	s_waitcnt lgkmcnt(0)
	v_cvt_pk_bf16_f32 v27, v118, v119
	s_waitcnt lgkmcnt(0)
	v_cvt_pk_bf16_f32 v28, v120, v121
	s_waitcnt lgkmcnt(0)
	v_cvt_pk_bf16_f32 v29, v122, v123
	v_lshl_add_u64 v[34:35], v[32:33], 0, v[4:5]
	global_store_dwordx4 v[34:35], v[26:29], off
	v_or_b32_e32 v4, s4, v51
	v_lshlrev_b32_e32 v4, 12, v4
	s_waitcnt lgkmcnt(0)
	v_cvt_pk_bf16_f32 v26, v124, v125
	s_waitcnt lgkmcnt(0)
	v_cvt_pk_bf16_f32 v27, v126, v127
	s_waitcnt lgkmcnt(0)
	v_cvt_pk_bf16_f32 v28, v128, v129
	s_waitcnt lgkmcnt(0)
	v_cvt_pk_bf16_f32 v29, v130, v131
	v_lshl_add_u64 v[30:31], v[32:33], 0, v[4:5]
	global_store_dwordx4 v[30:31], v[26:29], off
	s_waitcnt lgkmcnt(0)

;     const int nblk = N / 32, kb = item / nblk, nb = item % nblk, k0 = 64 * kb, n0 = 32 * nb;
; #pragma unroll 8
;     for (int i = 0; i < 32; ++i) { const int kk = 2 * i + (lane >> 5); float v = __builtin_nontemporal_load(W + (size_t)(k0 + kk) * N + n0 + (lane & 31)); if (gain) v *= gain[k0 + kk]; scr[kk * 33 + (lane & 31)] = v; }
;     asm volatile("s_waitcnt lgkmcnt(0)" ::: "memory");
.LBB0_104:
.LBB0_105:
	s_and_b64 vcc, exec, s[52:53]
	s_cbranch_vccnz .Lcvt_rows_4
	v_mbcnt_lo_u32_b32 v166, -1, 0
	v_mbcnt_hi_u32_b32 v166, -1, v166
	v_lshrrev_b32_e32 v169, 5, v166
	v_lshlrev_b32_e32 v169, 2, v169
	v_lshlrev_b32_e32 v166, 2, v166
	v_sub_u32_e32 v166, v166, v169
	v_mov_b32_e32 v167, 0
	v_lshl_add_u64 v[164:165], s[12:13], 0, v[42:43]
	v_lshl_add_u64 v[164:165], v[164:165], 0, v[166:167]
	global_load_dword v168, v[164:165], off
.Lcvt_rows_4:
	v_lshl_add_u64 v[164:165], v[44:45], 0, s[10:11]
	global_load_dword v100, v[164:165], off nt
	v_lshl_add_u64 v[164:165], v[40:41], 0, s[10:11]
	global_load_dword v101, v[164:165], off nt
	v_lshl_add_u64 v[164:165], v[38:39], 0, s[10:11]
	global_load_dword v102, v[164:165], off nt
	v_lshl_add_u64 v[164:165], v[36:37], 0, s[10:11]
	global_load_dword v103, v[164:165], off nt
	v_lshl_add_u64 v[164:165], v[34:35], 0, s[10:11]
	global_load_dword v104, v[164:165], off nt
	v_lshl_add_u64 v[164:165], v[32:33], 0, s[10:11]
	global_load_dword v105, v[164:165], off nt
	v_lshl_add_u64 v[164:165], v[30:31], 0, s[10:11]
	global_load_dword v106, v[164:165], off nt
	v_lshl_add_u64 v[164:165], v[26:27], 0, s[10:11]
	global_load_dword v107, v[164:165], off nt
	s_add_u32 s10, s10, 0x60000
	s_addc_u32 s11, s11, 0
	v_lshl_add_u64 v[164:165], v[44:45], 0, s[10:11]
	global_load_dword v108, v[164:165], off nt
	v_lshl_add_u64 v[164:165], v[40:41], 0, s[10:11]
	global_load_dword v109, v[164:165], off nt
	v_lshl_add_u64 v[164:165], v[38:39], 0, s[10:11]
	global_load_dword v110, v[164:165], off nt
	v_lshl_add_u64 v[164:165], v[36:37], 0, s[10:11]
	global_load_dword v111, v[164:165], off nt
	v_lshl_add_u64 v[164:165], v[34:35], 0, s[10:11]
	global_load_dword v112, v[164:165], off nt
	v_lshl_add_u64 v[164:165], v[32:33], 0, s[10:11]
	global_load_dword v113, v[164:165], off nt
	v_lshl_add_u64 v[164:165], v[30:31], 0, s[10:11]
	global_load_dword v114, v[164:165], off nt
	v_lshl_add_u64 v[164:165], v[26:27], 0, s[10:11]
	global_load_dword v115, v[164:165], off nt
	s_add_u32 s10, s10, 0x60000
	s_addc_u32 s11, s11, 0
	v_lshl_add_u64 v[164:165], v[44:45], 0, s[10:11]
	global_load_dword v116, v[164:165], off nt
	v_lshl_add_u64 v[164:165], v[40:41], 0, s[10:11]
	global_load_dword v117, v[164:165], off nt
	v_lshl_add_u64 v[164:165], v[38:39], 0, s[10:11]
	global_load_dword v118, v[164:165], off nt
	v_lshl_add_u64 v[164:165], v[36:37], 0, s[10:11]
	global_load_dword v119, v[164:165], off nt
	v_lshl_add_u64 v[164:165], v[34:35], 0, s[10:11]
	global_load_dword v120, v[164:165], off nt
	v_lshl_add_u64 v[164:165], v[32:33], 0, s[10:11]
	global_load_dword v121, v[164:165], off nt
	v_lshl_add_u64 v[164:165], v[30:31], 0, s[10:11]
	global_load_dword v122, v[164:165], off nt
	v_lshl_add_u64 v[164:165], v[26:27], 0, s[10:11]
	global_load_dword v123, v[164:165], off nt
	s_add_u32 s10, s10, 0x60000
	s_addc_u32 s11, s11, 0
	v_lshl_add_u64 v[164:165], v[44:45], 0, s[10:11]
	global_load_dword v124, v[164:165], off nt
	v_lshl_add_u64 v[164:165], v[40:41], 0, s[10:11]
	global_load_dword v125, v[164:165], off nt
	v_lshl_add_u64 v[164:165], v[38:39], 0, s[10:11]
	global_load_dword v126, v[164:165], off nt
	v_lshl_add_u64 v[164:165], v[36:37], 0, s[10:11]
	global_load_dword v127, v[164:165], off nt
	v_lshl_add_u64 v[164:165], v[34:35], 0, s[10:11]
	global_load_dword v128, v[164:165], off nt
	v_lshl_add_u64 v[164:165], v[32:33], 0, s[10:11]
	global_load_dword v129, v[164:165], off nt
	v_lshl_add_u64 v[164:165], v[30:31], 0, s[10:11]
	global_load_dword v130, v[164:165], off nt
	v_lshl_add_u64 v[164:165], v[26:27], 0, s[10:11]
	global_load_dword v131, v[164:165], off nt
	s_add_u32 s10, s10, 0x60000
	s_addc_u32 s11, s11, 0
	s_and_b64 vcc, exec, s[52:53]
	s_cbranch_vccnz .Lcvt_put_4
	s_waitcnt vmcnt(32)
	ds_bpermute_b32 v132, v169, v168
	ds_bpermute_b32 v133, v169, v168 offset:8
	ds_bpermute_b32 v134, v169, v168 offset:16
	ds_bpermute_b32 v135, v169, v168 offset:24
	ds_bpermute_b32 v136, v169, v168 offset:32
	ds_bpermute_b32 v137, v169, v168 offset:40
	ds_bpermute_b32 v138, v169, v168 offset:48
	ds_bpermute_b32 v139, v169, v168 offset:56
	ds_bpermute_b32 v140, v169, v168 offset:64
	ds_bpermute_b32 v141, v169, v168 offset:72
	ds_bpermute_b32 v142, v169, v168 offset:80
	ds_bpermute_b32 v143, v169, v168 offset:88
	ds_bpermute_b32 v144, v169, v168 offset:96
	ds_bpermute_b32 v145, v169, v168 offset:104
	ds_bpermute_b32 v146, v169, v168 offset:112
	ds_bpermute_b32 v147, v169, v168 offset:120
	ds_bpermute_b32 v148, v169, v168 offset:128
	ds_bpermute_b32 v149, v169, v168 offset:136
	ds_bpermute_b32 v150, v169, v168 offset:144
	ds_bpermute_b32 v151, v169, v168 offset:152
	ds_bpermute_b32 v152, v169, v168 offset:160
	ds_bpermute_b32 v153, v169, v168 offset:168
	ds_bpermute_b32 v154, v169, v168 offset:176
	ds_bpermute_b32 v155, v169, v168 offset:184
	ds_bpermute_b32 v156, v169, v168 offset:192
	ds_bpermute_b32 v157, v169, v168 offset:200
	ds_bpermute_b32 v158, v169, v168 offset:208
	ds_bpermute_b32 v159, v169, v168 offset:216
	ds_bpermute_b32 v160, v169, v168 offset:224
	ds_bpermute_b32 v161, v169, v168 offset:232
	ds_bpermute_b32 v162, v169, v168 offset:240
	ds_bpermute_b32 v163, v169, v168 offset:248
	s_waitcnt vmcnt(0) lgkmcnt(0)
	v_mul_f32_e32 v100, v100, v132
	v_mul_f32_e32 v101, v101, v133
	v_mul_f32_e32 v102, v102, v134
	v_mul_f32_e32 v103, v103, v135
	v_mul_f32_e32 v104, v104, v136
	v_mul_f32_e32 v105, v105, v137
	v_mul_f32_e32 v106, v106, v138
	v_mul_f32_e32 v107, v107, v139
	v_mul_f32_e32 v108, v108, v140
	v_mul_f32_e32 v109, v109, v141
	v_mul_f32_e32 v110, v110, v142
	v_mul_f32_e32 v111, v111, v143
	v_mul_f32_e32 v112, v112, v144
	v_mul_f32_e32 v113, v113, v145
	v_mul_f32_e32 v114, v114, v146
	v_mul_f32_e32 v115, v115, v147
	v_mul_f32_e32 v116, v116, v148
	v_mul_f32_e32 v117, v117, v149
	v_mul_f32_e32 v118, v118, v150
	v_mul_f32_e32 v119, v119, v151
	v_mul_f32_e32 v120, v120, v152
	v_mul_f32_e32 v121, v121, v153
	v_mul_f32_e32 v122, v122, v154
	v_mul_f32_e32 v123, v123, v155
	v_mul_f32_e32 v124, v124, v156
	v_mul_f32_e32 v125, v125, v157
	v_mul_f32_e32 v126, v126, v158
	v_mul_f32_e32 v127, v127, v159
	v_mul_f32_e32 v128, v128, v160
	v_mul_f32_e32 v129, v129, v161
	v_mul_f32_e32 v130, v130, v162
	v_mul_f32_e32 v131, v131, v163
;     ...
;     for (int i = 0; i < 32; ++i) { const int kk = 2 * i + (lane >> 5); float v = __builtin_nontemporal_load(W + (size_t)(k0 + kk) * N + n0 + (lane & 31)); if (gain) v *= gain[k0 + kk]; scr[kk * 33 + (lane & 31)] = v; }
;     asm volatile("s_waitcnt lgkmcnt(0)" ::: "memory");
.Lcvt_put_4:
	s_waitcnt vmcnt(0)
	ds_write_b32 v4, v100
	ds_write_b32 v4, v101 offset:264
	ds_write_b32 v4, v102 offset:528
	ds_write_b32 v4, v103 offset:792
	ds_write_b32 v4, v104 offset:1056
	ds_write_b32 v4, v105 offset:1320
	ds_write_b32 v4, v106 offset:1584
	ds_write_b32 v4, v107 offset:1848
	ds_write_b32 v4, v108 offset:2112
	ds_write_b32 v4, v109 offset:2376
	ds_write_b32 v4, v110 offset:2640
	ds_write_b32 v4, v111 offset:2904
	ds_write_b32 v4, v112 offset:3168
	ds_write_b32 v4, v113 offset:3432
	ds_write_b32 v4, v114 offset:3696
	ds_write_b32 v4, v115 offset:3960
	ds_write_b32 v4, v116 offset:4224
	ds_write_b32 v4, v117 offset:4488
	ds_write_b32 v4, v118 offset:4752
	ds_write_b32 v4, v119 offset:5016
	ds_write_b32 v4, v120 offset:5280
	ds_write_b32 v4, v121 offset:5544
	ds_write_b32 v4, v122 offset:5808
	ds_write_b32 v4, v123 offset:6072
	ds_write_b32 v4, v124 offset:6336
	ds_write_b32 v4, v125 offset:6600
	ds_write_b32 v4, v126 offset:6864
	ds_write_b32 v4, v127 offset:7128
	ds_write_b32 v4, v128 offset:7392
	ds_write_b32 v4, v129 offset:7656
	ds_write_b32 v4, v130 offset:7920
	ds_write_b32 v4, v131 offset:8184
	v_add_u32_e32 v4, 0x2100, v4
	s_add_u32 s12, s12, 0x100
	s_addc_u32 s13, s13, 0
	s_branch .LBB0_46

; #define LAS __attribute__((address_space(3)))
; __device__ __forceinline__ unsigned cvt_pk_bf16(float lo, float hi) { unsigned r; asm volatile("v_cvt_pk_bf16_f32 %0, %1, %2" : "=v"(r) : "v"(lo), "v"(hi)); return r; }
;     ...
;     const int c = lane & 7;
; #pragma unroll
;     for (int j = 0; j < 4; ++j) { const int n = (lane >> 3) + 8 * j; const LAS float* s = scr + (8 * c) * 33 + n;
;         u32x4 o; o.x = cvt_pk_bf16(s[0 * 33], s[1 * 33]); o.y = cvt_pk_bf16(s[2 * 33], s[3 * 33]); o.z = cvt_pk_bf16(s[4 * 33], s[5 * 33]); o.w = cvt_pk_bf16(s[6 * 33], s[7 * 33]);
;         const int nn = n0 + n; const int orow = mode ? ((nn >> 7) * 256 + (nn & 127) + (mode == 2 ? 128 : 0)) : nn;
;         *(u32x4*)(WT + (size_t)orow * K + k0 + 8 * c) = o; }
;     asm volatile("s_waitcnt lgkmcnt(0)" ::: "memory");
.LBB0_158:
	s_waitcnt lgkmcnt(0)
	ds_read2_b32 v[100:101], v40 offset1:33
	ds_read2_b32 v[102:103], v40 offset0:66 offset1:99
	ds_read2_b32 v[104:105], v40 offset0:132 offset1:165
	ds_read2_b32 v[106:107], v40 offset0:198 offset1:231
	ds_read2_b32 v[108:109], v40 offset0:8 offset1:41
	ds_read2_b32 v[110:111], v40 offset0:74 offset1:107
	ds_read2_b32 v[112:113], v40 offset0:140 offset1:173
	ds_read2_b32 v[114:115], v40 offset0:206 offset1:239
	ds_read2_b32 v[116:117], v40 offset0:16 offset1:49
	ds_read2_b32 v[118:119], v40 offset0:82 offset1:115
	ds_read2_b32 v[120:121], v40 offset0:148 offset1:181
	ds_read2_b32 v[122:123], v40 offset0:214 offset1:247
	ds_read2_b32 v[124:125], v40 offset0:24 offset1:57
	ds_read2_b32 v[126:127], v40 offset0:90 offset1:123
	ds_read2_b32 v[128:129], v40 offset0:156 offset1:189
	ds_read2_b32 v[130:131], v40 offset0:222 offset1:255
	s_waitcnt lgkmcnt(0)
	s_waitcnt lgkmcnt(0)
	v_cvt_pk_bf16_f32 v18, v100, v101
	s_waitcnt lgkmcnt(0)
	v_cvt_pk_bf16_f32 v19, v102, v103
	s_waitcnt lgkmcnt(0)
	v_cvt_pk_bf16_f32 v20, v104, v105
	s_waitcnt lgkmcnt(0)
	v_cvt_pk_bf16_f32 v21, v106, v107
	v_or_b32_e32 v24, s14, v13
	v_ashrrev_i32_e32 v25, 31, v24
	v_lshl_add_u64 v[22:23], s[16:17], 1, v[8:9]
	v_lshlrev_b64 v[24:25], 12, v[24:25]
	v_lshl_add_u64 v[24:25], v[22:23], 0, v[24:25]
	global_store_dwordx4 v[24:25], v[18:21], off
	s_waitcnt lgkmcnt(0)
	v_cvt_pk_bf16_f32 v18, v108, v109
	s_waitcnt lgkmcnt(0)
	v_cvt_pk_bf16_f32 v19, v110, v111
	s_waitcnt lgkmcnt(0)
	v_cvt_pk_bf16_f32 v20, v112, v113
	s_waitcnt lgkmcnt(0)
	v_cvt_pk_bf16_f32 v21, v114, v115
	v_or_b32_e32 v24, s14, v41
	v_ashrrev_i32_e32 v25, 31, v24
	v_lshlrev_b64 v[24:25], 12, v[24:25]
	v_lshl_add_u64 v[24:25], v[22:23], 0, v[24:25]
	global_store_dwordx4 v[24:25], v[18:21], off
	s_waitcnt lgkmcnt(0)
	v_cvt_pk_bf16_f32 v18, v116, v117
	s_waitcnt lgkmcnt(0)
	v_cvt_pk_bf16_f32 v19, v118, v119
	s_waitcnt lgkmcnt(0)
	v_cvt_pk_bf16_f32 v20, v120, v121
	s_waitcnt lgkmcnt(0)
	v_cvt_pk_bf16_f32 v21, v122, v123
	v_or_b32_e32 v24, s14, v42
	v_ashrrev_i32_e32 v25, 31, v24
	v_lshlrev_b64 v[24:25], 12, v[24:25]
	v_lshl_add_u64 v[24:25], v[22:23], 0, v[24:25]
	global_store_dwordx4 v[24:25], v[18:21], off
	s_waitcnt lgkmcnt(0)
	v_cvt_pk_bf16_f32 v18, v124, v125
	s_waitcnt lgkmcnt(0)
	v_cvt_pk_bf16_f32 v19, v126, v127
	s_waitcnt lgkmcnt(0)
	v_cvt_pk_bf16_f32 v20, v128, v129
	s_waitcnt lgkmcnt(0)
	v_cvt_pk_bf16_f32 v21, v130, v131
	v_or_b32_e32 v24, s14, v43
	v_ashrrev_i32_e32 v25, 31, v24
	v_lshlrev_b64 v[24:25], 12, v[24:25]
	v_lshl_add_u64 v[22:23], v[22:23], 0, v[24:25]
	global_store_dwordx4 v[22:23], v[18:21], off
	s_waitcnt lgkmcnt(0)

;     const int nblk = N / 32, kb = item / nblk, nb = item % nblk, k0 = 64 * kb, n0 = 32 * nb;
; #pragma unroll 8
;     for (int i = 0; i < 32; ++i) { const int kk = 2 * i + (lane >> 5); float v = __builtin_nontemporal_load(W + (size_t)(k0 + kk) * N + n0 + (lane & 31)); if (gain) v *= gain[k0 + kk]; scr[kk * 33 + (lane & 31)] = v; }
;     asm volatile("s_waitcnt lgkmcnt(0)" ::: "memory");
.LBB0_163:
.LBB0_164:
	v_cndmask_b32_e64 v37, 0, 1, s[96:97]
	v_cmp_ne_u32_e64 s[38:39], 1, v37
	s_andn2_b64 vcc, exec, s[96:97]
	s_cbranch_vccnz .Lcvt_rows_5
	v_mbcnt_lo_u32_b32 v166, -1, 0
	v_mbcnt_hi_u32_b32 v166, -1, v166
	v_lshrrev_b32_e32 v169, 5, v166
	v_lshlrev_b32_e32 v169, 2, v169
	v_lshlrev_b32_e32 v166, 2, v166
	v_sub_u32_e32 v166, v166, v169
	v_mov_b32_e32 v167, 0
	v_lshl_add_u64 v[164:165], s[16:17], 0, v[0:1]
	v_lshl_add_u64 v[164:165], v[164:165], 0, v[166:167]
	global_load_dword v168, v[164:165], off
.Lcvt_rows_5:
	v_lshl_add_u64 v[164:165], v[34:35], 0, s[14:15]
	global_load_dword v100, v[164:165], off nt
	v_lshl_add_u64 v[164:165], v[32:33], 0, s[14:15]
	global_load_dword v101, v[164:165], off nt
	v_lshl_add_u64 v[164:165], v[30:31], 0, s[14:15]
	global_load_dword v102, v[164:165], off nt
	v_lshl_add_u64 v[164:165], v[28:29], 0, s[14:15]
	global_load_dword v103, v[164:165], off nt
	v_lshl_add_u64 v[164:165], v[26:27], 0, s[14:15]
	global_load_dword v104, v[164:165], off nt
	v_lshl_add_u64 v[164:165], v[24:25], 0, s[14:15]
	global_load_dword v105, v[164:165], off nt
	v_lshl_add_u64 v[164:165], v[22:23], 0, s[14:15]
	global_load_dword v106, v[164:165], off nt
	v_lshl_add_u64 v[164:165], v[18:19], 0, s[14:15]
	global_load_dword v107, v[164:165], off nt
	s_add_u32 s14, s14, 0x58000
	s_addc_u32 s15, s15, 0
	v_lshl_add_u64 v[164:165], v[34:35], 0, s[14:15]
	global_load_dword v108, v[164:165], off nt
	v_lshl_add_u64 v[164:165], v[32:33], 0, s[14:15]
	global_load_dword v109, v[164:165], off nt
	v_lshl_add_u64 v[164:165], v[30:31], 0, s[14:15]
	global_load_dword v110, v[164:165], off nt
	v_lshl_add_u64 v[164:165], v[28:29], 0, s[14:15]
	global_load_dword v111, v[164:165], off nt
	v_lshl_add_u64 v[164:165], v[26:27], 0, s[14:15]
	global_load_dword v112, v[164:165], off nt
	v_lshl_add_u64 v[164:165], v[24:25], 0, s[14:15]
	global_load_dword v113, v[164:165], off nt
	v_lshl_add_u64 v[164:165], v[22:23], 0, s[14:15]
	global_load_dword v114, v[164:165], off nt
	v_lshl_add_u64 v[164:165], v[18:19], 0, s[14:15]
	global_load_dword v115, v[164:165], off nt
	s_add_u32 s14, s14, 0x58000
	s_addc_u32 s15, s15, 0
	v_lshl_add_u64 v[164:165], v[34:35], 0, s[14:15]
	global_load_dword v116, v[164:165], off nt
	v_lshl_add_u64 v[164:165], v[32:33], 0, s[14:15]
	global_load_dword v117, v[164:165], off nt
	v_lshl_add_u64 v[164:165], v[30:31], 0, s[14:15]
	global_load_dword v118, v[164:165], off nt
	v_lshl_add_u64 v[164:165], v[28:29], 0, s[14:15]
	global_load_dword v119, v[164:165], off nt
	v_lshl_add_u64 v[164:165], v[26:27], 0, s[14:15]
	global_load_dword v120, v[164:165], off nt
	v_lshl_add_u64 v[164:165], v[24:25], 0, s[14:15]
	global_load_dword v121, v[164:165], off nt
	v_lshl_add_u64 v[164:165], v[22:23], 0, s[14:15]
	global_load_dword v122, v[164:165], off nt
	v_lshl_add_u64 v[164:165], v[18:19], 0, s[14:15]
	global_load_dword v123, v[164:165], off nt
	s_add_u32 s14, s14, 0x58000
	s_addc_u32 s15, s15, 0
	v_lshl_add_u64 v[164:165], v[34:35], 0, s[14:15]
	global_load_dword v124, v[164:165], off nt
	v_lshl_add_u64 v[164:165], v[32:33], 0, s[14:15]
	global_load_dword v125, v[164:165], off nt
	v_lshl_add_u64 v[164:165], v[30:31], 0, s[14:15]
	global_load_dword v126, v[164:165], off nt
	v_lshl_add_u64 v[164:165], v[28:29], 0, s[14:15]
	global_load_dword v127, v[164:165], off nt
	v_lshl_add_u64 v[164:165], v[26:27], 0, s[14:15]
	global_load_dword v128, v[164:165], off nt
	v_lshl_add_u64 v[164:165], v[24:25], 0, s[14:15]
	global_load_dword v129, v[164:165], off nt
	v_lshl_add_u64 v[164:165], v[22:23], 0, s[14:15]
	global_load_dword v130, v[164:165], off nt
	v_lshl_add_u64 v[164:165], v[18:19], 0, s[14:15]
	global_load_dword v131, v[164:165], off nt
	s_add_u32 s14, s14, 0x58000
	s_addc_u32 s15, s15, 0
	v_cndmask_b32_e64 v37, 0, 1, s[96:97]
	v_cmp_ne_u32_e64 s[38:39], 1, v37
	s_andn2_b64 vcc, exec, s[96:97]
	s_cbranch_vccnz .Lcvt_put_5
	s_waitcnt vmcnt(32)
	ds_bpermute_b32 v132, v169, v168
	ds_bpermute_b32 v133, v169, v168 offset:8
	ds_bpermute_b32 v134, v169, v168 offset:16
	ds_bpermute_b32 v135, v169, v168 offset:24
	ds_bpermute_b32 v136, v169, v168 offset:32
	ds_bpermute_b32 v137, v169, v168 offset:40
	ds_bpermute_b32 v138, v169, v168 offset:48
	ds_bpermute_b32 v139, v169, v168 offset:56
	ds_bpermute_b32 v140, v169, v168 offset:64
	ds_bpermute_b32 v141, v169, v168 offset:72
	ds_bpermute_b32 v142, v169, v168 offset:80
	ds_bpermute_b32 v143, v169, v168 offset:88
	ds_bpermute_b32 v144, v169, v168 offset:96
	ds_bpermute_b32 v145, v169, v168 offset:104
	ds_bpermute_b32 v146, v169, v168 offset:112
	ds_bpermute_b32 v147, v169, v168 offset:120
	ds_bpermute_b32 v148, v169, v168 offset:128
	ds_bpermute_b32 v149, v169, v168 offset:136
	ds_bpermute_b32 v150, v169, v168 offset:144
	ds_bpermute_b32 v151, v169, v168 offset:152
	ds_bpermute_b32 v152, v169, v168 offset:160
	ds_bpermute_b32 v153, v169, v168 offset:168
	ds_bpermute_b32 v154, v169, v168 offset:176
	ds_bpermute_b32 v155, v169, v168 offset:184
	ds_bpermute_b32 v156, v169, v168 offset:192
	ds_bpermute_b32 v157, v169, v168 offset:200
	ds_bpermute_b32 v158, v169, v168 offset:208
	ds_bpermute_b32 v159, v169, v168 offset:216
	ds_bpermute_b32 v160, v169, v168 offset:224
	ds_bpermute_b32 v161, v169, v168 offset:232
	ds_bpermute_b32 v162, v169, v168 offset:240
	ds_bpermute_b32 v163, v169, v168 offset:248
	s_waitcnt vmcnt(0) lgkmcnt(0)
	v_mul_f32_e32 v100, v100, v132
	v_mul_f32_e32 v101, v101, v133
	v_mul_f32_e32 v102, v102, v134
	v_mul_f32_e32 v103, v103, v135
	v_mul_f32_e32 v104, v104, v136
	v_mul_f32_e32 v105, v105, v137
	v_mul_f32_e32 v106, v106, v138
	v_mul_f32_e32 v107, v107, v139
	v_mul_f32_e32 v108, v108, v140
	v_mul_f32_e32 v109, v109, v141
	v_mul_f32_e32 v110, v110, v142
	v_mul_f32_e32 v111, v111, v143
	v_mul_f32_e32 v112, v112, v144
	v_mul_f32_e32 v113, v113, v145
	v_mul_f32_e32 v114, v114, v146
	v_mul_f32_e32 v115, v115, v147
	v_mul_f32_e32 v116, v116, v148
	v_mul_f32_e32 v117, v117, v149
	v_mul_f32_e32 v118, v118, v150
	v_mul_f32_e32 v119, v119, v151
	v_mul_f32_e32 v120, v120, v152
	v_mul_f32_e32 v121, v121, v153
	v_mul_f32_e32 v122, v122, v154
	v_mul_f32_e32 v123, v123, v155
	v_mul_f32_e32 v124, v124, v156
	v_mul_f32_e32 v125, v125, v157
	v_mul_f32_e32 v126, v126, v158
	v_mul_f32_e32 v127, v127, v159
	v_mul_f32_e32 v128, v128, v160
	v_mul_f32_e32 v129, v129, v161
	v_mul_f32_e32 v130, v130, v162
	v_mul_f32_e32 v131, v131, v163
; #define LAS __attribute__((address_space(3)))
; __device__ __forceinline__ unsigned cvt_pk_bf16(float lo, float hi) { unsigned r; asm volatile("v_cvt_pk_bf16_f32 %0, %1, %2" : "=v"(r) : "v"(lo), "v"(hi)); return r; }
;     ...
;     for (int i = 0; i < 32; ++i) { const int kk = 2 * i + (lane >> 5); float v = __builtin_nontemporal_load(W + (size_t)(k0 + kk) * N + n0 + (lane & 31)); if (gain) v *= gain[k0 + kk]; scr[kk * 33 + (lane & 31)] = v; }
;     asm volatile("s_waitcnt lgkmcnt(0)" ::: "memory");
;     const int c = lane & 7;
; #pragma unroll
;     for (int j = 0; j < 4; ++j) { const int n = (lane >> 3) + 8 * j; const LAS float* s = scr + (8 * c) * 33 + n;
;         u32x4 o; o.x = cvt_pk_bf16(s[0 * 33], s[1 * 33]); o.y = cvt_pk_bf16(s[2 * 33], s[3 * 33]); o.z = cvt_pk_bf16(s[4 * 33], s[5 * 33]); o.w = cvt_pk_bf16(s[6 * 33], s[7 * 33]);
;         const int nn = n0 + n; const int orow = mode ? ((nn >> 7) * 256 + (nn & 127) + (mode == 2 ? 128 : 0)) : nn;
;         *(u32x4*)(WT + (size_t)orow * K + k0 + 8 * c) = o; }
;     asm volatile("s_waitcnt lgkmcnt(0)" ::: "memory");
.Lcvt_put_5:
	s_waitcnt vmcnt(0)
	ds_write_b32 v38, v100
	ds_write_b32 v38, v101 offset:264
	ds_write_b32 v38, v102 offset:528
	ds_write_b32 v38, v103 offset:792
	ds_write_b32 v38, v104 offset:1056
	ds_write_b32 v38, v105 offset:1320
	ds_write_b32 v38, v106 offset:1584
	ds_write_b32 v38, v107 offset:1848
	ds_write_b32 v38, v108 offset:2112
	ds_write_b32 v38, v109 offset:2376
	ds_write_b32 v38, v110 offset:2640
	ds_write_b32 v38, v111 offset:2904
	ds_write_b32 v38, v112 offset:3168
	ds_write_b32 v38, v113 offset:3432
	ds_write_b32 v38, v114 offset:3696
	ds_write_b32 v38, v115 offset:3960
	ds_write_b32 v38, v116 offset:4224
	ds_write_b32 v38, v117 offset:4488
	ds_write_b32 v38, v118 offset:4752
	ds_write_b32 v38, v119 offset:5016
	ds_write_b32 v38, v120 offset:5280
	ds_write_b32 v38, v121 offset:5544
	ds_write_b32 v38, v122 offset:5808
	ds_write_b32 v38, v123 offset:6072
	ds_write_b32 v38, v124 offset:6336
	ds_write_b32 v38, v125 offset:6600
	ds_write_b32 v38, v126 offset:6864
	ds_write_b32 v38, v127 offset:7128
	ds_write_b32 v38, v128 offset:7392
	ds_write_b32 v38, v129 offset:7656
	ds_write_b32 v38, v130 offset:7920
	ds_write_b32 v38, v131 offset:8184
	v_add_u32_e32 v38, 0x2100, v38
	s_add_u32 s16, s16, 0x100
	s_addc_u32 s17, s17, 0
	s_branch .LBB0_180
.LBB0_180:
	s_waitcnt lgkmcnt(0)
	ds_read2_b32 v[100:101], v40 offset1:33
	ds_read2_b32 v[102:103], v40 offset0:66 offset1:99
	ds_read2_b32 v[104:105], v40 offset0:132 offset1:165
	ds_read2_b32 v[106:107], v40 offset0:198 offset1:231
	ds_read2_b32 v[108:109], v40 offset0:8 offset1:41
	ds_read2_b32 v[110:111], v40 offset0:74 offset1:107
	ds_read2_b32 v[112:113], v40 offset0:140 offset1:173
	ds_read2_b32 v[114:115], v40 offset0:206 offset1:239
	ds_read2_b32 v[116:117], v40 offset0:16 offset1:49
	ds_read2_b32 v[118:119], v40 offset0:82 offset1:115
	ds_read2_b32 v[120:121], v40 offset0:148 offset1:181
	ds_read2_b32 v[122:123], v40 offset0:214 offset1:247
	ds_read2_b32 v[124:125], v40 offset0:24 offset1:57
	ds_read2_b32 v[126:127], v40 offset0:90 offset1:123
	ds_read2_b32 v[128:129], v40 offset0:156 offset1:189
	ds_read2_b32 v[130:131], v40 offset0:222 offset1:255
	s_waitcnt lgkmcnt(0)
	s_lshl_b32 s10, s10, 6
	s_and_b32 s3, s3, 0x60
	s_and_b32 s10, s10, 0x3f00
	s_and_b32 s11, 0xffff, s11
	s_waitcnt lgkmcnt(0)
	v_cvt_pk_bf16_f32 v20, v100, v101
	v_or_b32_e32 v0, s3, v13
	s_lshl_b32 s8, s11, 1
	s_waitcnt lgkmcnt(0)
	v_cvt_pk_bf16_f32 v21, v102, v103
	v_or_b32_e32 v0, s10, v0
	v_lshl_add_u64 v[18:19], v[4:5], 0, s[8:9]
	s_waitcnt lgkmcnt(0)
	v_cvt_pk_bf16_f32 v22, v104, v105
	v_lshlrev_b32_e32 v0, 12, v0
	s_waitcnt lgkmcnt(0)
	v_cvt_pk_bf16_f32 v23, v106, v107
	v_lshl_add_u64 v[24:25], v[18:19], 0, v[0:1]
	global_store_dwordx4 v[24:25], v[20:23], off
	v_or_b32_e32 v0, s3, v41
	s_waitcnt lgkmcnt(0)
	v_cvt_pk_bf16_f32 v20, v108, v109
	s_waitcnt lgkmcnt(0)
	v_cvt_pk_bf16_f32 v21, v110, v111
	v_or_b32_e32 v0, s10, v0
	s_waitcnt lgkmcnt(0)
	v_cvt_pk_bf16_f32 v22, v112, v113
	v_lshlrev_b32_e32 v0, 12, v0
	s_waitcnt lgkmcnt(0)
	v_cvt_pk_bf16_f32 v23, v114, v115
	v_lshl_add_u64 v[24:25], v[18:19], 0, v[0:1]
	global_store_dwordx4 v[24:25], v[20:23], off
	v_or_b32_e32 v0, s3, v42
	s_waitcnt lgkmcnt(0)
	v_cvt_pk_bf16_f32 v20, v116, v117
	s_waitcnt lgkmcnt(0)
	v_cvt_pk_bf16_f32 v21, v118, v119
	v_or_b32_e32 v0, s10, v0
	s_waitcnt lgkmcnt(0)
	v_cvt_pk_bf16_f32 v22, v120, v121
	v_lshlrev_b32_e32 v0, 12, v0
	s_waitcnt lgkmcnt(0)
	v_cvt_pk_bf16_f32 v23, v122, v123
	v_lshl_add_u64 v[24:25], v[18:19], 0, v[0:1]
	v_or_b32_e32 v0, s3, v43
	global_store_dwordx4 v[24:25], v[20:23], off
	v_or_b32_e32 v0, s10, v0
	s_waitcnt lgkmcnt(0)
	v_cvt_pk_bf16_f32 v20, v124, v125
	v_lshlrev_b32_e32 v0, 12, v0
	s_waitcnt lgkmcnt(0)
	v_cvt_pk_bf16_f32 v21, v126, v127
	v_lshl_add_u64 v[18:19], v[18:19], 0, v[0:1]
	s_waitcnt lgkmcnt(0)
	v_cvt_pk_bf16_f32 v22, v128, v129
	s_waitcnt lgkmcnt(0)
	v_cvt_pk_bf16_f32 v23, v130, v131
	global_store_dwordx4 v[18:19], v[20:23], off
	s_waitcnt lgkmcnt(0)
	s_mov_b64 s[14:15], 0

; #define LAS __attribute__((address_space(3)))
; __device__ __forceinline__ unsigned cvt_pk_bf16(float lo, float hi) { unsigned r; asm volatile("v_cvt_pk_bf16_f32 %0, %1, %2" : "=v"(r) : "v"(lo), "v"(hi)); return r; }
;     const int nblk = N / 32, kb = item / nblk, nb = item % nblk, k0 = 64 * kb, n0 = 32 * nb;
; #pragma unroll 8
;     for (int i = 0; i < 32; ++i) { const int kk = 2 * i + (lane >> 5); float v = __builtin_nontemporal_load(W + (size_t)(k0 + kk) * N + n0 + (lane & 31)); if (gain) v *= gain[k0 + kk]; scr[kk * 33 + (lane & 31)] = v; }
;     asm volatile("s_waitcnt lgkmcnt(0)" ::: "memory");
;     const int c = lane & 7;
; #pragma unroll
;     for (int j = 0; j < 4; ++j) { const int n = (lane >> 3) + 8 * j; const LAS float* s = scr + (8 * c) * 33 + n;
;         u32x4 o; o.x = cvt_pk_bf16(s[0 * 33], s[1 * 33]); o.y = cvt_pk_bf16(s[2 * 33], s[3 * 33]); o.z = cvt_pk_bf16(s[4 * 33], s[5 * 33]); o.w = cvt_pk_bf16(s[6 * 33], s[7 * 33]);
;         const int nn = n0 + n; const int orow = mode ? ((nn >> 7) * 256 + (nn & 127) + (mode == 2 ? 128 : 0)) : nn;
;         *(u32x4*)(WT + (size_t)orow * K + k0 + 8 * c) = o; }
;     asm volatile("s_waitcnt lgkmcnt(0)" ::: "memory");
.LBB0_183:
	v_lshl_add_u64 v[164:165], v[32:33], 0, s[14:15]
	global_load_dword v100, v[164:165], off nt
	v_lshl_add_u64 v[164:165], v[30:31], 0, s[14:15]
	global_load_dword v101, v[164:165], off nt
	v_lshl_add_u64 v[164:165], v[28:29], 0, s[14:15]
	global_load_dword v102, v[164:165], off nt
	v_lshl_add_u64 v[164:165], v[26:27], 0, s[14:15]
	global_load_dword v103, v[164:165], off nt
	v_lshl_add_u64 v[164:165], v[24:25], 0, s[14:15]
	global_load_dword v104, v[164:165], off nt
	v_lshl_add_u64 v[164:165], v[22:23], 0, s[14:15]
	global_load_dword v105, v[164:165], off nt
	v_lshl_add_u64 v[164:165], v[20:21], 0, s[14:15]
	global_load_dword v106, v[164:165], off nt
	v_lshl_add_u64 v[164:165], v[18:19], 0, s[14:15]
	global_load_dword v107, v[164:165], off nt
	s_add_u32 s14, s14, 0x20000
	s_addc_u32 s15, s15, 0
	v_lshl_add_u64 v[164:165], v[32:33], 0, s[14:15]
	global_load_dword v108, v[164:165], off nt
	v_lshl_add_u64 v[164:165], v[30:31], 0, s[14:15]
	global_load_dword v109, v[164:165], off nt
	v_lshl_add_u64 v[164:165], v[28:29], 0, s[14:15]
	global_load_dword v110, v[164:165], off nt
	v_lshl_add_u64 v[164:165], v[26:27], 0, s[14:15]
	global_load_dword v111, v[164:165], off nt
	v_lshl_add_u64 v[164:165], v[24:25], 0, s[14:15]
	global_load_dword v112, v[164:165], off nt
	v_lshl_add_u64 v[164:165], v[22:23], 0, s[14:15]
	global_load_dword v113, v[164:165], off nt
	v_lshl_add_u64 v[164:165], v[20:21], 0, s[14:15]
	global_load_dword v114, v[164:165], off nt
	v_lshl_add_u64 v[164:165], v[18:19], 0, s[14:15]
	global_load_dword v115, v[164:165], off nt
	s_add_u32 s14, s14, 0x20000
	s_addc_u32 s15, s15, 0
	v_lshl_add_u64 v[164:165], v[32:33], 0, s[14:15]
	global_load_dword v116, v[164:165], off nt
	v_lshl_add_u64 v[164:165], v[30:31], 0, s[14:15]
	global_load_dword v117, v[164:165], off nt
	v_lshl_add_u64 v[164:165], v[28:29], 0, s[14:15]
	global_load_dword v118, v[164:165], off nt
	v_lshl_add_u64 v[164:165], v[26:27], 0, s[14:15]
	global_load_dword v119, v[164:165], off nt
	v_lshl_add_u64 v[164:165], v[24:25], 0, s[14:15]
	global_load_dword v120, v[164:165], off nt
	v_lshl_add_u64 v[164:165], v[22:23], 0, s[14:15]
	global_load_dword v121, v[164:165], off nt
	v_lshl_add_u64 v[164:165], v[20:21], 0, s[14:15]
	global_load_dword v122, v[164:165], off nt
	v_lshl_add_u64 v[164:165], v[18:19], 0, s[14:15]
	global_load_dword v123, v[164:165], off nt
	s_add_u32 s14, s14, 0x20000
	s_addc_u32 s15, s15, 0
	v_lshl_add_u64 v[164:165], v[32:33], 0, s[14:15]
	global_load_dword v124, v[164:165], off nt
	v_lshl_add_u64 v[164:165], v[30:31], 0, s[14:15]
	global_load_dword v125, v[164:165], off nt
	v_lshl_add_u64 v[164:165], v[28:29], 0, s[14:15]
	global_load_dword v126, v[164:165], off nt
	v_lshl_add_u64 v[164:165], v[26:27], 0, s[14:15]
	global_load_dword v127, v[164:165], off nt
	v_lshl_add_u64 v[164:165], v[24:25], 0, s[14:15]
	global_load_dword v128, v[164:165], off nt
	v_lshl_add_u64 v[164:165], v[22:23], 0, s[14:15]
	global_load_dword v129, v[164:165], off nt
	v_lshl_add_u64 v[164:165], v[20:21], 0, s[14:15]
	global_load_dword v130, v[164:165], off nt
	v_lshl_add_u64 v[164:165], v[18:19], 0, s[14:15]
	global_load_dword v131, v[164:165], off nt
	s_add_u32 s14, s14, 0x20000
	s_addc_u32 s15, s15, 0
	s_waitcnt vmcnt(24)
	ds_write_b32 v0, v100
	ds_write_b32 v0, v101 offset:264
	ds_write_b32 v0, v102 offset:528
	ds_write_b32 v0, v103 offset:792
	ds_write_b32 v0, v104 offset:1056
	ds_write_b32 v0, v105 offset:1320
	ds_write_b32 v0, v106 offset:1584
	ds_write_b32 v0, v107 offset:1848
	s_waitcnt vmcnt(16)
	ds_write_b32 v0, v108 offset:2112
	ds_write_b32 v0, v109 offset:2376
	ds_write_b32 v0, v110 offset:2640
	ds_write_b32 v0, v111 offset:2904
	ds_write_b32 v0, v112 offset:3168
	ds_write_b32 v0, v113 offset:3432
	ds_write_b32 v0, v114 offset:3696
	ds_write_b32 v0, v115 offset:3960
	s_waitcnt vmcnt(8)
	ds_write_b32 v0, v116 offset:4224
	ds_write_b32 v0, v117 offset:4488
	ds_write_b32 v0, v118 offset:4752
	ds_write_b32 v0, v119 offset:5016
	ds_write_b32 v0, v120 offset:5280
	ds_write_b32 v0, v121 offset:5544
	ds_write_b32 v0, v122 offset:5808
	ds_write_b32 v0, v123 offset:6072
	s_waitcnt vmcnt(0)
	ds_write_b32 v0, v124 offset:6336
	ds_write_b32 v0, v125 offset:6600
	ds_write_b32 v0, v126 offset:6864
	ds_write_b32 v0, v127 offset:7128
	ds_write_b32 v0, v128 offset:7392
	ds_write_b32 v0, v129 offset:7656
	ds_write_b32 v0, v130 offset:7920
	ds_write_b32 v0, v131 offset:8184
	v_add_u32_e32 v0, 0x2100, v0
	s_add_i32 s3, s0, 0xe800
	s_waitcnt lgkmcnt(0)
	ds_read2_b32 v[100:101], v40 offset1:33
	ds_read2_b32 v[102:103], v40 offset0:66 offset1:99
	ds_read2_b32 v[104:105], v40 offset0:132 offset1:165
	ds_read2_b32 v[106:107], v40 offset0:198 offset1:231
	ds_read2_b32 v[108:109], v40 offset0:8 offset1:41
	ds_read2_b32 v[110:111], v40 offset0:74 offset1:107
	ds_read2_b32 v[112:113], v40 offset0:140 offset1:173
	ds_read2_b32 v[114:115], v40 offset0:206 offset1:239
	ds_read2_b32 v[116:117], v40 offset0:16 offset1:49
	ds_read2_b32 v[118:119], v40 offset0:82 offset1:115
	ds_read2_b32 v[120:121], v40 offset0:148 offset1:181
	ds_read2_b32 v[122:123], v40 offset0:214 offset1:247
	ds_read2_b32 v[124:125], v40 offset0:24 offset1:57
	ds_read2_b32 v[126:127], v40 offset0:90 offset1:123
	ds_read2_b32 v[128:129], v40 offset0:156 offset1:189
	ds_read2_b32 v[130:131], v40 offset0:222 offset1:255
	s_waitcnt lgkmcnt(0)
	s_and_b32 s10, s3, 0xffc0
	s_lshl_b32 s3, s0, 5
	s_and_b32 s3, s3, 0x7e0
	s_waitcnt lgkmcnt(0)
	v_cvt_pk_bf16_f32 v18, v100, v101
	s_lshl_b32 s8, s10, 1
	s_waitcnt lgkmcnt(0)
	v_cvt_pk_bf16_f32 v19, v102, v103
	v_or_b32_e32 v0, s3, v13
	v_lshl_add_u64 v[22:23], v[6:7], 0, s[8:9]
	s_waitcnt lgkmcnt(0)
	v_cvt_pk_bf16_f32 v20, v104, v105
	v_lshlrev_b32_e32 v0, 12, v0
	s_waitcnt lgkmcnt(0)
	v_cvt_pk_bf16_f32 v21, v106, v107
	v_lshl_add_u64 v[24:25], v[22:23], 0, v[0:1]
	global_store_dwordx4 v[24:25], v[18:21], off
	v_or_b32_e32 v0, s3, v41
	s_waitcnt lgkmcnt(0)
	v_cvt_pk_bf16_f32 v18, v108, v109
	s_waitcnt lgkmcnt(0)
	v_cvt_pk_bf16_f32 v19, v110, v111
	s_waitcnt lgkmcnt(0)
	v_cvt_pk_bf16_f32 v20, v112, v113
	v_lshlrev_b32_e32 v0, 12, v0
	s_waitcnt lgkmcnt(0)
	v_cvt_pk_bf16_f32 v21, v114, v115
	v_lshl_add_u64 v[24:25], v[22:23], 0, v[0:1]
	global_store_dwordx4 v[24:25], v[18:21], off
	v_or_b32_e32 v0, s3, v42
	s_waitcnt lgkmcnt(0)
	v_cvt_pk_bf16_f32 v18, v116, v117
	s_waitcnt lgkmcnt(0)
	v_cvt_pk_bf16_f32 v19, v118, v119
	s_waitcnt lgkmcnt(0)
	v_cvt_pk_bf16_f32 v20, v120, v121
	v_lshlrev_b32_e32 v0, 12, v0
	s_waitcnt lgkmcnt(0)
	v_cvt_pk_bf16_f32 v21, v122, v123
	v_lshl_add_u64 v[24:25], v[22:23], 0, v[0:1]
	global_store_dwordx4 v[24:25], v[18:21], off
	v_or_b32_e32 v0, s3, v43
	s_waitcnt lgkmcnt(0)
	v_cvt_pk_bf16_f32 v18, v124, v125
	v_lshlrev_b32_e32 v0, 12, v0
	s_waitcnt lgkmcnt(0)
	v_cvt_pk_bf16_f32 v19, v126, v127
	v_lshl_add_u64 v[22:23], v[22:23], 0, v[0:1]
	s_waitcnt lgkmcnt(0)
	v_cvt_pk_bf16_f32 v20, v128, v129
	s_waitcnt lgkmcnt(0)
	v_cvt_pk_bf16_f32 v21, v130, v131
	global_store_dwordx4 v[22:23], v[18:21], off
	s_waitcnt lgkmcnt(0)

;     const int nblk = N / 32, kb = item / nblk, nb = item % nblk, k0 = 64 * kb, n0 = 32 * nb;
; #pragma unroll 8
;     for (int i = 0; i < 32; ++i) { const int kk = 2 * i + (lane >> 5); float v = __builtin_nontemporal_load(W + (size_t)(k0 + kk) * N + n0 + (lane & 31)); if (gain) v *= gain[k0 + kk]; scr[kk * 33 + (lane & 31)] = v; }
;     asm volatile("s_waitcnt lgkmcnt(0)" ::: "memory");
.LBB0_188:
.LBB0_189:
	s_and_b64 vcc, exec, s[52:53]
	s_cbranch_vccnz .Lcvt_rows_6
	v_mbcnt_lo_u32_b32 v166, -1, 0
	v_mbcnt_hi_u32_b32 v166, -1, v166
	v_lshrrev_b32_e32 v169, 5, v166
	v_lshlrev_b32_e32 v169, 2, v169
	v_lshlrev_b32_e32 v166, 2, v166
	v_sub_u32_e32 v166, v166, v169
	v_mov_b32_e32 v167, 0
	v_lshl_add_u64 v[164:165], s[20:21], 0, v[34:35]
	v_lshl_add_u64 v[164:165], v[164:165], 0, v[166:167]
	global_load_dword v168, v[164:165], off
.Lcvt_rows_6:
	v_lshl_add_u64 v[164:165], v[36:37], 0, s[18:19]
	global_load_dword v100, v[164:165], off nt
	v_lshl_add_u64 v[164:165], v[32:33], 0, s[18:19]
	global_load_dword v101, v[164:165], off nt
	v_lshl_add_u64 v[164:165], v[30:31], 0, s[18:19]
	global_load_dword v102, v[164:165], off nt
	v_lshl_add_u64 v[164:165], v[28:29], 0, s[18:19]
	global_load_dword v103, v[164:165], off nt
	v_lshl_add_u64 v[164:165], v[26:27], 0, s[18:19]
	global_load_dword v104, v[164:165], off nt
	v_lshl_add_u64 v[164:165], v[24:25], 0, s[18:19]
	global_load_dword v105, v[164:165], off nt
	v_lshl_add_u64 v[164:165], v[22:23], 0, s[18:19]
	global_load_dword v106, v[164:165], off nt
	v_lshl_add_u64 v[164:165], v[18:19], 0, s[18:19]
	global_load_dword v107, v[164:165], off nt
	s_add_u32 s18, s18, 0x60000
	s_addc_u32 s19, s19, 0
	v_lshl_add_u64 v[164:165], v[36:37], 0, s[18:19]
	global_load_dword v108, v[164:165], off nt
	v_lshl_add_u64 v[164:165], v[32:33], 0, s[18:19]
	global_load_dword v109, v[164:165], off nt
	v_lshl_add_u64 v[164:165], v[30:31], 0, s[18:19]
	global_load_dword v110, v[164:165], off nt
	v_lshl_add_u64 v[164:165], v[28:29], 0, s[18:19]
	global_load_dword v111, v[164:165], off nt
	v_lshl_add_u64 v[164:165], v[26:27], 0, s[18:19]
	global_load_dword v112, v[164:165], off nt
	v_lshl_add_u64 v[164:165], v[24:25], 0, s[18:19]
	global_load_dword v113, v[164:165], off nt
	v_lshl_add_u64 v[164:165], v[22:23], 0, s[18:19]
	global_load_dword v114, v[164:165], off nt
	v_lshl_add_u64 v[164:165], v[18:19], 0, s[18:19]
	global_load_dword v115, v[164:165], off nt
	s_add_u32 s18, s18, 0x60000
	s_addc_u32 s19, s19, 0
	v_lshl_add_u64 v[164:165], v[36:37], 0, s[18:19]
	global_load_dword v116, v[164:165], off nt
	v_lshl_add_u64 v[164:165], v[32:33], 0, s[18:19]
	global_load_dword v117, v[164:165], off nt
	v_lshl_add_u64 v[164:165], v[30:31], 0, s[18:19]
	global_load_dword v118, v[164:165], off nt
	v_lshl_add_u64 v[164:165], v[28:29], 0, s[18:19]
	global_load_dword v119, v[164:165], off nt
	v_lshl_add_u64 v[164:165], v[26:27], 0, s[18:19]
	global_load_dword v120, v[164:165], off nt
	v_lshl_add_u64 v[164:165], v[24:25], 0, s[18:19]
	global_load_dword v121, v[164:165], off nt
	v_lshl_add_u64 v[164:165], v[22:23], 0, s[18:19]
	global_load_dword v122, v[164:165], off nt
	v_lshl_add_u64 v[164:165], v[18:19], 0, s[18:19]
	global_load_dword v123, v[164:165], off nt
	s_add_u32 s18, s18, 0x60000
	s_addc_u32 s19, s19, 0
	v_lshl_add_u64 v[164:165], v[36:37], 0, s[18:19]
	global_load_dword v124, v[164:165], off nt
	v_lshl_add_u64 v[164:165], v[32:33], 0, s[18:19]
	global_load_dword v125, v[164:165], off nt
	v_lshl_add_u64 v[164:165], v[30:31], 0, s[18:19]
	global_load_dword v126, v[164:165], off nt
	v_lshl_add_u64 v[164:165], v[28:29], 0, s[18:19]
	global_load_dword v127, v[164:165], off nt
	v_lshl_add_u64 v[164:165], v[26:27], 0, s[18:19]
	global_load_dword v128, v[164:165], off nt
	v_lshl_add_u64 v[164:165], v[24:25], 0, s[18:19]
	global_load_dword v129, v[164:165], off nt
	v_lshl_add_u64 v[164:165], v[22:23], 0, s[18:19]
	global_load_dword v130, v[164:165], off nt
	v_lshl_add_u64 v[164:165], v[18:19], 0, s[18:19]
	global_load_dword v131, v[164:165], off nt
	s_add_u32 s18, s18, 0x60000
	s_addc_u32 s19, s19, 0
	s_and_b64 vcc, exec, s[52:53]
	s_cbranch_vccnz .Lcvt_put_6
	s_waitcnt vmcnt(32)
	ds_bpermute_b32 v132, v169, v168
	ds_bpermute_b32 v133, v169, v168 offset:8
	ds_bpermute_b32 v134, v169, v168 offset:16
	ds_bpermute_b32 v135, v169, v168 offset:24
	ds_bpermute_b32 v136, v169, v168 offset:32
	ds_bpermute_b32 v137, v169, v168 offset:40
	ds_bpermute_b32 v138, v169, v168 offset:48
	ds_bpermute_b32 v139, v169, v168 offset:56
	ds_bpermute_b32 v140, v169, v168 offset:64
	ds_bpermute_b32 v141, v169, v168 offset:72
	ds_bpermute_b32 v142, v169, v168 offset:80
	ds_bpermute_b32 v143, v169, v168 offset:88
	ds_bpermute_b32 v144, v169, v168 offset:96
	ds_bpermute_b32 v145, v169, v168 offset:104
	ds_bpermute_b32 v146, v169, v168 offset:112
	ds_bpermute_b32 v147, v169, v168 offset:120
	ds_bpermute_b32 v148, v169, v168 offset:128
	ds_bpermute_b32 v149, v169, v168 offset:136
	ds_bpermute_b32 v150, v169, v168 offset:144
	ds_bpermute_b32 v151, v169, v168 offset:152
	ds_bpermute_b32 v152, v169, v168 offset:160
	ds_bpermute_b32 v153, v169, v168 offset:168
	ds_bpermute_b32 v154, v169, v168 offset:176
	ds_bpermute_b32 v155, v169, v168 offset:184
	ds_bpermute_b32 v156, v169, v168 offset:192
	ds_bpermute_b32 v157, v169, v168 offset:200
	ds_bpermute_b32 v158, v169, v168 offset:208
	ds_bpermute_b32 v159, v169, v168 offset:216
	ds_bpermute_b32 v160, v169, v168 offset:224
	ds_bpermute_b32 v161, v169, v168 offset:232
	ds_bpermute_b32 v162, v169, v168 offset:240
	ds_bpermute_b32 v163, v169, v168 offset:248
	s_waitcnt vmcnt(0) lgkmcnt(0)
	v_mul_f32_e32 v100, v100, v132
	v_mul_f32_e32 v101, v101, v133
	v_mul_f32_e32 v102, v102, v134
	v_mul_f32_e32 v103, v103, v135
	v_mul_f32_e32 v104, v104, v136
	v_mul_f32_e32 v105, v105, v137
	v_mul_f32_e32 v106, v106, v138
	v_mul_f32_e32 v107, v107, v139
	v_mul_f32_e32 v108, v108, v140
	v_mul_f32_e32 v109, v109, v141
	v_mul_f32_e32 v110, v110, v142
	v_mul_f32_e32 v111, v111, v143
	v_mul_f32_e32 v112, v112, v144
	v_mul_f32_e32 v113, v113, v145
	v_mul_f32_e32 v114, v114, v146
	v_mul_f32_e32 v115, v115, v147
	v_mul_f32_e32 v116, v116, v148
	v_mul_f32_e32 v117, v117, v149
	v_mul_f32_e32 v118, v118, v150
	v_mul_f32_e32 v119, v119, v151
	v_mul_f32_e32 v120, v120, v152
	v_mul_f32_e32 v121, v121, v153
	v_mul_f32_e32 v122, v122, v154
	v_mul_f32_e32 v123, v123, v155
	v_mul_f32_e32 v124, v124, v156
	v_mul_f32_e32 v125, v125, v157
	v_mul_f32_e32 v126, v126, v158
	v_mul_f32_e32 v127, v127, v159
	v_mul_f32_e32 v128, v128, v160
	v_mul_f32_e32 v129, v129, v161
	v_mul_f32_e32 v130, v130, v162
	v_mul_f32_e32 v131, v131, v163
;     ...
;     for (int i = 0; i < 32; ++i) { const int kk = 2 * i + (lane >> 5); float v = __builtin_nontemporal_load(W + (size_t)(k0 + kk) * N + n0 + (lane & 31)); if (gain) v *= gain[k0 + kk]; scr[kk * 33 + (lane & 31)] = v; }
;     asm volatile("s_waitcnt lgkmcnt(0)" ::: "memory");
.Lcvt_put_6:
	s_waitcnt vmcnt(0)
	ds_write_b32 v0, v100
	ds_write_b32 v0, v101 offset:264
	ds_write_b32 v0, v102 offset:528
	ds_write_b32 v0, v103 offset:792
	ds_write_b32 v0, v104 offset:1056
	ds_write_b32 v0, v105 offset:1320
	ds_write_b32 v0, v106 offset:1584
	ds_write_b32 v0, v107 offset:1848
	ds_write_b32 v0, v108 offset:2112
	ds_write_b32 v0, v109 offset:2376
	ds_write_b32 v0, v110 offset:2640
	ds_write_b32 v0, v111 offset:2904
	ds_write_b32 v0, v112 offset:3168
	ds_write_b32 v0, v113 offset:3432
	ds_write_b32 v0, v114 offset:3696
	ds_write_b32 v0, v115 offset:3960
	ds_write_b32 v0, v116 offset:4224
	ds_write_b32 v0, v117 offset:4488
	ds_write_b32 v0, v118 offset:4752
	ds_write_b32 v0, v119 offset:5016
	ds_write_b32 v0, v120 offset:5280
	ds_write_b32 v0, v121 offset:5544
	ds_write_b32 v0, v122 offset:5808
	ds_write_b32 v0, v123 offset:6072
	ds_write_b32 v0, v124 offset:6336
	ds_write_b32 v0, v125 offset:6600
	ds_write_b32 v0, v126 offset:6864
	ds_write_b32 v0, v127 offset:7128
	ds_write_b32 v0, v128 offset:7392
	ds_write_b32 v0, v129 offset:7656
	ds_write_b32 v0, v130 offset:7920
	ds_write_b32 v0, v131 offset:8184
	v_add_u32_e32 v0, 0x2100, v0
	s_add_u32 s20, s20, 0x100
	s_addc_u32 s21, s21, 0
	s_branch .LBB0_158

; #define LAS __attribute__((address_space(3)))
; __device__ __forceinline__ unsigned cvt_pk_bf16(float lo, float hi) { unsigned r; asm volatile("v_cvt_pk_bf16_f32 %0, %1, %2" : "=v"(r) : "v"(lo), "v"(hi)); return r; }
; __device__ __forceinline__ float bf_lo(unsigned w) { return __uint_as_float(w << 16); }
; __device__ __forceinline__ float bf_hi(unsigned w) { return __uint_as_float(w & 0xffff0000u); }
; __device__ __forceinline__ void kv_unit(LAS unsigned char* lds, const bf16_t* __restrict__ proj, bf16_t* __restrict__ kvT, int b, int h, int n) {
;     ...
;     __syncthreads();
; #pragma unroll
;     for (int i = 0; i < 4; ++i) {
;         const int j = (tid >> 4) + 32 * i, c = tid & 15;
;         const u32x4 kk = *(const u32x4*)(proj + (row0 + j) * DIN + C_RK + h * 128 + c * 8);
;         const float dec = __builtin_amdgcn_exp2f(l2g * (float)(127 - j)) * 0.08838834764831845f;
;         u32x4 w;
; #pragma unroll
;         for (int k = 0; k < 4; ++k) w[k] = cvt_pk_bf16(bf_lo(kk[k]) * dec, bf_hi(kk[k]) * dec);
;         *(LAS u32x4*)(lds + L_K + j * KSTR + c * 16) = w;
;     }
.LBB0_260:
	s_ashr_i32 s2, s0, 7
	s_and_b32 s1, s0, 31
	s_bfe_u32 s3, s0, 0x20005
	s_mul_i32 s14, s2, 0x1080
	s_lshl_b32 s15, s1, 7
	s_mul_hi_i32 s11, s2, 0x1080
	s_add_u32 s14, s14, s15
	s_addc_u32 s15, s11, 0
	s_add_i32 s11, s3, 5
	v_cvt_f32_ubyte0_e32 v0, s11
	v_exp_f32_e64 v0, -v0
	v_mov_b32_e32 v6, v208
	v_sub_f32_e32 v0, 1.0, v0
	v_cmp_gt_f32_e32 vcc, s63, v0
	s_and_b64 s[16:17], vcc, exec
	s_cselect_b32 s11, 32, 0
	v_ldexp_f32 v0, v0, s11
	v_log_f32_e32 v0, v0
	v_ashrrev_i32_e32 v4, 4, v6
	v_cndmask_b32_e32 v2, 0, v194, vcc
	v_ashrrev_i32_e32 v5, 31, v4
	v_sub_f32_e32 v7, v0, v2
	v_lshl_add_u64 v[8:9], s[14:15], 0, v[4:5]
	v_mov_b64_e32 v[2:3], s[6:7]
	v_mad_u64_u32 v[10:11], s[16:17], v8, s35, v[2:3]
	v_lshlrev_b32_e32 v0, 4, v6
	v_mad_i32_i24 v11, v9, s35, v11
	s_lshl_b32 s8, s3, 8
	v_and_b32_e32 v0, 0xf0, v0
	v_lshl_add_u64 v[8:9], v[10:11], 0, s[8:9]
	v_lshl_add_u64 v[8:9], v[8:9], 0, v[0:1]
	v_add_co_u32_e32 v8, vcc, s89, v8
	s_barrier
	s_nop 0
	v_addc_co_u32_e32 v9, vcc, 0, v9, vcc
	global_load_dwordx4 v[160:163], v[8:9], off offset:3072
	v_add_u32_e32 v8, 32, v4
	v_ashrrev_i32_e32 v9, 31, v8
	v_lshl_add_u64 v[8:9], s[14:15], 0, v[8:9]
	v_mad_u64_u32 v[10:11], s[16:17], v8, s35, v[2:3]
	v_mad_i32_i24 v11, v9, s35, v11
	v_lshl_add_u64 v[8:9], v[10:11], 0, s[8:9]
	v_lshl_add_u64 v[8:9], v[8:9], 0, v[0:1]
	v_add_co_u32_e32 v8, vcc, s89, v8
	s_nop 0
	s_nop 0
	v_addc_co_u32_e32 v9, vcc, 0, v9, vcc
	global_load_dwordx4 v[164:167], v[8:9], off offset:3072
	v_add_u32_e32 v8, 64, v4
	v_ashrrev_i32_e32 v9, 31, v8
	v_lshl_add_u64 v[8:9], s[14:15], 0, v[8:9]
	v_mad_u64_u32 v[10:11], s[16:17], v8, s35, v[2:3]
	v_mad_i32_i24 v11, v9, s35, v11
	v_lshl_add_u64 v[8:9], v[10:11], 0, s[8:9]
	v_lshl_add_u64 v[8:9], v[8:9], 0, v[0:1]
	v_add_co_u32_e32 v8, vcc, s89, v8
	s_nop 0
	s_nop 0
	v_addc_co_u32_e32 v9, vcc, 0, v9, vcc
	global_load_dwordx4 v[168:171], v[8:9], off offset:3072
	v_add_u32_e32 v8, 0x60, v4
	v_ashrrev_i32_e32 v9, 31, v8
	v_lshl_add_u64 v[8:9], s[14:15], 0, v[8:9]
	v_mad_u64_u32 v[10:11], s[16:17], v8, s35, v[2:3]
	v_mad_i32_i24 v11, v9, s35, v11
	v_lshl_add_u64 v[8:9], v[10:11], 0, s[8:9]
	v_lshl_add_u64 v[8:9], v[8:9], 0, v[0:1]
	v_add_co_u32_e32 v8, vcc, s89, v8
	s_nop 0
	s_nop 0
	v_addc_co_u32_e32 v9, vcc, 0, v9, vcc
	global_load_dwordx4 v[172:175], v[8:9], off offset:3072
	v_sub_u32_e32 v5, 0x7f, v4
	v_cvt_f32_i32_e32 v5, v5
	v_and_b32_e32 v67, 31, v6
	v_readfirstlane_b32 s10, v6
	s_ashr_i32 s10, s10, 1
	v_mul_f32_e32 v5, v7, v5
	v_exp_f32_e32 v5, v5
	v_bfe_u32 v66, v6, 5, 1
	s_andn2_b32 s10, s10, 31
	v_mul_f32_e32 v5, 0x3db504f3, v5
	s_waitcnt vmcnt(3)
	v_lshlrev_b32_e32 v12, 16, v160
	v_and_b32_e32 v160, 0xffff0000, v160
	v_mul_f32_e32 v12, v5, v12
	v_mul_f32_e32 v160, v5, v160
	v_cvt_pk_bf16_f32 v160, v12, v160
	v_lshlrev_b32_e32 v12, 16, v161
	v_and_b32_e32 v161, 0xffff0000, v161
	v_mul_f32_e32 v12, v5, v12
	v_mul_f32_e32 v161, v5, v161
	v_cvt_pk_bf16_f32 v161, v12, v161
	v_lshlrev_b32_e32 v12, 16, v162
	v_and_b32_e32 v162, 0xffff0000, v162
	v_mul_f32_e32 v12, v5, v12
	v_mul_f32_e32 v162, v5, v162
	v_cvt_pk_bf16_f32 v162, v12, v162
	v_lshlrev_b32_e32 v12, 16, v163
	v_and_b32_e32 v163, 0xffff0000, v163
	v_mul_f32_e32 v12, v5, v12
	v_mul_f32_e32 v5, v5, v163
	v_cvt_pk_bf16_f32 v163, v12, v5
	v_mul_lo_u32 v5, v4, s75
	v_add3_u32 v5, 0, v0, v5
	ds_write_b128 v5, v[160:163]
	v_sub_u32_e32 v12, 0x5f, v4
	v_cvt_f32_i32_e32 v12, v12
	v_mul_f32_e32 v12, v7, v12
	v_exp_f32_e32 v12, v12
	s_waitcnt vmcnt(2)
	v_lshlrev_b32_e32 v13, 16, v164
	v_mul_f32_e32 v12, 0x3db504f3, v12
	v_and_b32_e32 v164, 0xffff0000, v164
	v_mul_f32_e32 v13, v12, v13
	v_mul_f32_e32 v164, v12, v164
	v_cvt_pk_bf16_f32 v164, v13, v164
	v_lshlrev_b32_e32 v13, 16, v165
	v_and_b32_e32 v165, 0xffff0000, v165
	v_mul_f32_e32 v13, v12, v13
	v_mul_f32_e32 v165, v12, v165
	v_cvt_pk_bf16_f32 v165, v13, v165
	v_lshlrev_b32_e32 v13, 16, v166
	v_and_b32_e32 v166, 0xffff0000, v166
	v_mul_f32_e32 v13, v12, v13
	v_mul_f32_e32 v166, v12, v166
	v_cvt_pk_bf16_f32 v166, v13, v166
	v_lshlrev_b32_e32 v13, 16, v167
	v_and_b32_e32 v167, 0xffff0000, v167
	v_mul_f32_e32 v167, v12, v167
	v_mul_f32_e32 v13, v12, v13
	v_cvt_pk_bf16_f32 v167, v13, v167
	ds_write_b128 v5, v[164:167] offset:10240
	v_sub_u32_e32 v12, 63, v4
	v_cvt_f32_i32_e32 v12, v12
	v_mul_f32_e32 v12, v7, v12
	v_exp_f32_e32 v12, v12
	s_waitcnt vmcnt(1)
	v_lshlrev_b32_e32 v13, 16, v168
	v_mul_f32_e32 v12, 0x3db504f3, v12
	v_and_b32_e32 v168, 0xffff0000, v168
	v_mul_f32_e32 v13, v12, v13
	v_mul_f32_e32 v168, v12, v168
	v_cvt_pk_bf16_f32 v168, v13, v168
	v_lshlrev_b32_e32 v13, 16, v169
	v_and_b32_e32 v169, 0xffff0000, v169
	v_mul_f32_e32 v13, v12, v13
	v_mul_f32_e32 v169, v12, v169
	v_cvt_pk_bf16_f32 v169, v13, v169
	v_lshlrev_b32_e32 v13, 16, v170
	v_and_b32_e32 v170, 0xffff0000, v170
	v_mul_f32_e32 v13, v12, v13
	v_mul_f32_e32 v170, v12, v170
	v_cvt_pk_bf16_f32 v170, v13, v170
	v_lshlrev_b32_e32 v13, 16, v171
	v_and_b32_e32 v171, 0xffff0000, v171
	v_mul_f32_e32 v171, v12, v171
	v_mul_f32_e32 v13, v12, v13
	v_cvt_pk_bf16_f32 v171, v13, v171
	ds_write_b128 v5, v[168:171] offset:20480
	v_sub_u32_e32 v0, 31, v4
	v_cvt_f32_i32_e32 v0, v0
	s_lshl_b32 s8, s3, 9
	v_mul_f32_e32 v0, v7, v0
	v_exp_f32_e32 v0, v0
	s_waitcnt vmcnt(0)
; #define LAS __attribute__((address_space(3)))
; __device__ __forceinline__ unsigned cvt_pk_bf16(float lo, float hi) { unsigned r; asm volatile("v_cvt_pk_bf16_f32 %0, %1, %2" : "=v"(r) : "v"(lo), "v"(hi)); return r; }
; __device__ __forceinline__ float bf_lo(unsigned w) { return __uint_as_float(w << 16); }
; __device__ __forceinline__ float bf_hi(unsigned w) { return __uint_as_float(w & 0xffff0000u); }
; __device__ __forceinline__ void kv_unit(LAS unsigned char* lds, const bf16_t* __restrict__ proj, bf16_t* __restrict__ kvT, int b, int h, int n) {
;     ...
; #pragma unroll
;     for (int i = 0; i < 4; ++i) {
;         const int j = (tid >> 4) + 32 * i, c = tid & 15;
;         const u32x4 kk = *(const u32x4*)(proj + (row0 + j) * DIN + C_RK + h * 128 + c * 8);
;         const float dec = __builtin_amdgcn_exp2f(l2g * (float)(127 - j)) * 0.08838834764831845f;
;         u32x4 w;
; #pragma unroll
;         for (int k = 0; k < 4; ++k) w[k] = cvt_pk_bf16(bf_lo(kk[k]) * dec, bf_hi(kk[k]) * dec);
;         *(LAS u32x4*)(lds + L_K + j * KSTR + c * 16) = w;
;     }
; #pragma unroll
;     for (int i = 0; i < 8; ++i) {
;         const int j = (tid >> 5) + 16 * i, c = tid & 31;
;         const u32x4 vv = *(const u32x4*)(proj + (row0 + j) * DIN + C_RV + h * 256 + c * 8);
;         *(LAS u32x4*)(lds + L_V + j * VSTR + c * 16) = vv;
;     }
;     __syncthreads();
	v_lshlrev_b32_e32 v4, 16, v172
	v_mul_f32_e32 v0, 0x3db504f3, v0
	v_mul_f32_e32 v4, v0, v4
	v_and_b32_e32 v7, 0xffff0000, v172
	v_mul_f32_e32 v7, v0, v7
	v_cvt_pk_bf16_f32 v172, v4, v7
	v_lshlrev_b32_e32 v4, 16, v173
	v_mul_f32_e32 v4, v0, v4
	v_and_b32_e32 v7, 0xffff0000, v173
	v_mul_f32_e32 v7, v0, v7
	v_cvt_pk_bf16_f32 v173, v4, v7
	v_lshlrev_b32_e32 v4, 16, v174
	v_mul_f32_e32 v4, v0, v4
	v_and_b32_e32 v7, 0xffff0000, v174
	v_mul_f32_e32 v7, v0, v7
	v_cvt_pk_bf16_f32 v174, v4, v7
	v_lshlrev_b32_e32 v4, 16, v175
	v_mul_f32_e32 v4, v0, v4
	v_and_b32_e32 v7, 0xffff0000, v175
	v_mul_f32_e32 v0, v0, v7
	v_cvt_pk_bf16_f32 v175, v4, v0
	v_ashrrev_i32_e32 v4, 5, v6
	ds_write_b128 v5, v[172:175] offset:30720
	v_ashrrev_i32_e32 v5, 31, v4
	v_lshl_add_u64 v[8:9], s[14:15], 0, v[4:5]
	v_mad_u64_u32 v[10:11], s[16:17], v8, s35, v[2:3]
	v_mad_i32_i24 v11, v9, s35, v11
	v_lshlrev_b32_e32 v0, 4, v67
	v_lshl_add_u64 v[8:9], v[10:11], 0, s[8:9]
	v_lshl_add_u64 v[8:9], v[8:9], 0, v[0:1]
	v_add_co_u32_e32 v8, vcc, s68, v8
	v_mul_lo_u32 v5, v4, s46
	s_nop 0
	v_addc_co_u32_e32 v9, vcc, 0, v9, vcc
	global_load_dwordx4 v[110:113], v[8:9], off
	v_add3_u32 v5, 0, v0, v5
	v_add_u32_e32 v150, 0x10c00, v5
	v_and_b32_e32 v7, 16, v6
	v_add_u32_e32 v8, 16, v4
	v_ashrrev_i32_e32 v9, 31, v8
	v_lshl_add_u64 v[8:9], s[14:15], 0, v[8:9]
	v_mad_u64_u32 v[10:11], s[16:17], v8, s35, v[2:3]
	v_mad_i32_i24 v11, v9, s35, v11
	v_lshl_add_u64 v[8:9], v[10:11], 0, s[8:9]
	v_lshl_add_u64 v[8:9], v[8:9], 0, v[0:1]
	v_add_co_u32_e32 v8, vcc, s68, v8
	s_nop 1
	v_addc_co_u32_e32 v9, vcc, 0, v9, vcc
	global_load_dwordx4 v[114:117], v[8:9], off
	v_add_u32_e32 v8, 32, v4
	v_ashrrev_i32_e32 v9, 31, v8
	v_lshl_add_u64 v[8:9], s[14:15], 0, v[8:9]
	v_mad_u64_u32 v[10:11], s[16:17], v8, s35, v[2:3]
	v_mad_i32_i24 v11, v9, s35, v11
	v_lshl_add_u64 v[8:9], v[10:11], 0, s[8:9]
	v_lshl_add_u64 v[8:9], v[8:9], 0, v[0:1]
	v_add_co_u32_e32 v8, vcc, s68, v8
	s_nop 1
	v_addc_co_u32_e32 v9, vcc, 0, v9, vcc
	global_load_dwordx4 v[118:121], v[8:9], off
	v_add_u32_e32 v8, 48, v4
	v_ashrrev_i32_e32 v9, 31, v8
	v_lshl_add_u64 v[8:9], s[14:15], 0, v[8:9]
	v_mad_u64_u32 v[10:11], s[16:17], v8, s35, v[2:3]
	v_mad_i32_i24 v11, v9, s35, v11
	v_lshl_add_u64 v[8:9], v[10:11], 0, s[8:9]
	v_lshl_add_u64 v[8:9], v[8:9], 0, v[0:1]
	v_add_co_u32_e32 v8, vcc, s68, v8
	s_nop 1
	v_addc_co_u32_e32 v9, vcc, 0, v9, vcc
	global_load_dwordx4 v[122:125], v[8:9], off
	v_add_u32_e32 v8, 64, v4
	v_ashrrev_i32_e32 v9, 31, v8
	v_lshl_add_u64 v[8:9], s[14:15], 0, v[8:9]
	v_mad_u64_u32 v[10:11], s[16:17], v8, s35, v[2:3]
	v_mad_i32_i24 v11, v9, s35, v11
	v_lshl_add_u64 v[8:9], v[10:11], 0, s[8:9]
	v_lshl_add_u64 v[8:9], v[8:9], 0, v[0:1]
	v_add_co_u32_e32 v8, vcc, s68, v8
	v_add_u32_e32 v151, 0x13000, v5
	s_nop 0
	v_addc_co_u32_e32 v9, vcc, 0, v9, vcc
	global_load_dwordx4 v[126:129], v[8:9], off
	v_add_u32_e32 v8, 0x50, v4
	v_ashrrev_i32_e32 v9, 31, v8
	v_lshl_add_u64 v[8:9], s[14:15], 0, v[8:9]
	v_mad_u64_u32 v[10:11], s[16:17], v8, s35, v[2:3]
	v_mad_i32_i24 v11, v9, s35, v11
	v_lshl_add_u64 v[8:9], v[10:11], 0, s[8:9]
	v_lshl_add_u64 v[8:9], v[8:9], 0, v[0:1]
	v_add_co_u32_e32 v8, vcc, s68, v8
	v_add_u32_e32 v152, 0x15400, v5
	s_nop 0
	v_addc_co_u32_e32 v9, vcc, 0, v9, vcc
	global_load_dwordx4 v[130:133], v[8:9], off
	v_add_u32_e32 v8, 0x60, v4
	v_ashrrev_i32_e32 v9, 31, v8
	v_lshl_add_u64 v[8:9], s[14:15], 0, v[8:9]
	v_mad_u64_u32 v[10:11], s[16:17], v8, s35, v[2:3]
	v_mad_i32_i24 v11, v9, s35, v11
	v_lshl_add_u64 v[8:9], v[10:11], 0, s[8:9]
	v_lshl_add_u64 v[8:9], v[8:9], 0, v[0:1]
	v_add_co_u32_e32 v8, vcc, s68, v8
	v_add_u32_e32 v153, 0x17800, v5
	s_nop 0
	v_addc_co_u32_e32 v9, vcc, 0, v9, vcc
	global_load_dwordx4 v[134:137], v[8:9], off
	v_add_u32_e32 v8, 0x70, v4
	v_ashrrev_i32_e32 v9, 31, v8
	v_lshl_add_u64 v[8:9], s[14:15], 0, v[8:9]
	v_mad_u64_u32 v[2:3], s[14:15], v8, s35, v[2:3]
	v_mad_i32_i24 v3, v9, s35, v3
	v_lshl_add_u64 v[2:3], v[2:3], 0, s[8:9]
	v_lshl_add_u64 v[2:3], v[2:3], 0, v[0:1]
	v_add_co_u32_e32 v2, vcc, s68, v2
	v_add_u32_e32 v0, 0x19c00, v5
	s_nop 0
	v_addc_co_u32_e32 v3, vcc, 0, v3, vcc
	global_load_dwordx4 v[138:141], v[2:3], off
	v_or_b32_e32 v3, s10, v7
	v_lshlrev_b32_e32 v4, 3, v6
	v_lshlrev_b32_e32 v3, 1, v3
	v_and_b32_e32 v4, 24, v4
	s_waitcnt vmcnt(7)
	ds_write_b128 v5, v[110:113] offset:40960
	s_waitcnt vmcnt(6)
	ds_write_b128 v5, v[114:117] offset:50176
	s_waitcnt vmcnt(5)
	ds_write_b128 v5, v[118:121] offset:59392
	s_waitcnt vmcnt(4)
	ds_write_b128 v150, v[122:125]
	s_waitcnt vmcnt(3)
	ds_write_b128 v151, v[126:129]
	s_waitcnt vmcnt(2)
	ds_write_b128 v152, v[130:133]
	s_waitcnt vmcnt(1)
	ds_write_b128 v153, v[134:137]
	s_waitcnt vmcnt(0)
	ds_write_b128 v0, v[138:141]
	v_bfe_u32 v0, v6, 2, 2
	v_lshl_or_b32 v0, v66, 3, v0
	v_mad_u32_u24 v2, v0, s46, 0
	v_lshlrev_b32_e32 v0, 8, v0
	v_add3_u32 v108, v2, v3, v4
	v_sub_u32_e32 v0, v2, v0
	v_lshlrev_b32_e32 v2, 1, v7
	s_waitcnt lgkmcnt(0)
	s_barrier
; #define LAS __attribute__((address_space(3)))
; #define MFMA32(a, b, c) __builtin_amdgcn_mfma_f32_32x32x16_bf16((a), (b), (c), 0, 0, 0)
; #define KV_FRAGS(s, buf) do { fa[buf] = cat8(tr_read(va + (16 * (s)) * VSTR), tr_read(va + (16 * (s) + 4) * VSTR)); \
;         _Pragma("unroll") for (int t_ = 0; t_ < 4; ++t_) fb[buf][t_] = cat8(tr_read(ka + (16 * (s)) * KSTR + t_ * 64), tr_read(ka + (16 * (s) + 4) * KSTR + t_ * 64)); } while (0)
; __device__ __forceinline__ void kv_unit(LAS unsigned char* lds, const bf16_t* __restrict__ proj, bf16_t* __restrict__ kvT, int b, int h, int n) {
;     ...
;     const LAS unsigned char* va = lds + L_V + (8 * hh + q4) * VSTR + (32 * wid + 16 * g16) * 2 + 8 * p4;
;     const LAS unsigned char* ka = lds + L_K + (8 * hh + q4) * KSTR + (16 * g16) * 2 + 8 * p4;
;     bf16x8 fa[2], fb[2][4];
;     ...
;     KV_FRAGS(0, 0);
; #pragma unroll
;     for (int s = 0; s < 8; ++s) {
;         if (s + 1 < 8) KV_FRAGS(s + 1, (s + 1) & 1);
;         __builtin_amdgcn_sched_barrier(0);
; #pragma unroll
;         for (int t = 0; t < 4; ++t) acc[t] = MFMA32(fa[s & 1], fb[s & 1][t], acc[t]);
;         __builtin_amdgcn_sched_barrier(0);
;     }
	v_add3_u32 v0, v0, v2, v4
	ds_read_b64_tr_b16 v[2:3], v108 offset:40960
	ds_read_b64_tr_b16 v[4:5], v108 offset:43264
	ds_read_b64_tr_b16 v[6:7], v0
	ds_read_b64_tr_b16 v[8:9], v0 offset:1280
	ds_read_b64_tr_b16 v[10:11], v0 offset:64
	ds_read_b64_tr_b16 v[12:13], v0 offset:1344
	ds_read_b64_tr_b16 v[14:15], v0 offset:128
	ds_read_b64_tr_b16 v[16:17], v0 offset:1408
	ds_read_b64_tr_b16 v[68:69], v0 offset:192
	ds_read_b64_tr_b16 v[70:71], v0 offset:1472
	ds_read_b64_tr_b16 v[72:73], v108 offset:50176
	ds_read_b64_tr_b16 v[74:75], v108 offset:52480
	ds_read_b64_tr_b16 v[76:77], v0 offset:5120
	ds_read_b64_tr_b16 v[78:79], v0 offset:6400
	ds_read_b64_tr_b16 v[80:81], v0 offset:5184
	ds_read_b64_tr_b16 v[82:83], v0 offset:6464
	ds_read_b64_tr_b16 v[84:85], v0 offset:5248
	ds_read_b64_tr_b16 v[86:87], v0 offset:6528
	ds_read_b64_tr_b16 v[88:89], v0 offset:5312
	ds_read_b64_tr_b16 v[90:91], v0 offset:6592
	v_add_u32_e32 v109, 0xa000, v108
	s_waitcnt lgkmcnt(14)
	v_mfma_f32_32x32x16_bf16 v[50:65], v[2:5], v[6:9], 0
	v_mfma_f32_32x32x16_bf16 v[34:49], v[2:5], v[10:13], 0
	s_waitcnt lgkmcnt(12)
	v_mfma_f32_32x32x16_bf16 v[18:33], v[2:5], v[14:17], 0
	s_waitcnt lgkmcnt(10)
	v_mfma_f32_32x32x16_bf16 v[2:17], v[2:5], v[68:71], 0
	ds_read_b64_tr_b16 v[68:69], v108 offset:59392
	ds_read_b64_tr_b16 v[70:71], v108 offset:61696
	ds_read_b64_tr_b16 v[92:93], v0 offset:10240
	ds_read_b64_tr_b16 v[96:97], v0 offset:10304
	ds_read_b64_tr_b16 v[94:95], v0 offset:11520
	ds_read_b64_tr_b16 v[98:99], v0 offset:11584
	ds_read_b64_tr_b16 v[100:101], v0 offset:10368
	ds_read_b64_tr_b16 v[104:105], v0 offset:10432
	ds_read_b64_tr_b16 v[102:103], v0 offset:11648
	ds_read_b64_tr_b16 v[106:107], v0 offset:11712
	s_waitcnt lgkmcnt(14)
	v_mfma_f32_32x32x16_bf16 v[50:65], v[72:75], v[76:79], v[50:65]
	v_mfma_f32_32x32x16_bf16 v[34:49], v[72:75], v[80:83], v[34:49]
	s_waitcnt lgkmcnt(12)
	v_mfma_f32_32x32x16_bf16 v[18:33], v[72:75], v[84:87], v[18:33]
	s_waitcnt lgkmcnt(10)
	v_mfma_f32_32x32x16_bf16 v[2:17], v[72:75], v[88:91], v[2:17]
	ds_read_b64_tr_b16 v[72:73], v109 offset:27648
	ds_read_b64_tr_b16 v[74:75], v109 offset:29952
	ds_read_b64_tr_b16 v[76:77], v0 offset:15360
	ds_read_b64_tr_b16 v[80:81], v0 offset:15424
	ds_read_b64_tr_b16 v[78:79], v0 offset:16640
	ds_read_b64_tr_b16 v[82:83], v0 offset:16704
	ds_read_b64_tr_b16 v[84:85], v0 offset:15488
	ds_read_b64_tr_b16 v[88:89], v0 offset:15552
	ds_read_b64_tr_b16 v[86:87], v0 offset:16768
	ds_read_b64_tr_b16 v[90:91], v0 offset:16832
	s_waitcnt lgkmcnt(14)
	v_mfma_f32_32x32x16_bf16 v[50:65], v[68:71], v[92:95], v[50:65]
	v_mfma_f32_32x32x16_bf16 v[34:49], v[68:71], v[96:99], v[34:49]
	s_waitcnt lgkmcnt(11)
	v_mfma_f32_32x32x16_bf16 v[18:33], v[68:71], v[100:103], v[18:33]
	s_waitcnt lgkmcnt(10)
	v_mfma_f32_32x32x16_bf16 v[2:17], v[68:71], v[104:107], v[2:17]
	ds_read_b64_tr_b16 v[68:69], v109 offset:36864
	ds_read_b64_tr_b16 v[70:71], v109 offset:39168
	ds_read_b64_tr_b16 v[92:93], v0 offset:20480
	ds_read_b64_tr_b16 v[96:97], v0 offset:20544
	ds_read_b64_tr_b16 v[94:95], v0 offset:21760
	ds_read_b64_tr_b16 v[98:99], v0 offset:21824
	ds_read_b64_tr_b16 v[100:101], v0 offset:20608
	ds_read_b64_tr_b16 v[104:105], v0 offset:20672
	ds_read_b64_tr_b16 v[102:103], v0 offset:21888
	ds_read_b64_tr_b16 v[106:107], v0 offset:21952
	s_waitcnt lgkmcnt(14)
	v_mfma_f32_32x32x16_bf16 v[50:65], v[72:75], v[76:79], v[50:65]
	v_mfma_f32_32x32x16_bf16 v[34:49], v[72:75], v[80:83], v[34:49]
	s_waitcnt lgkmcnt(11)
	v_mfma_f32_32x32x16_bf16 v[18:33], v[72:75], v[84:87], v[18:33]
	s_waitcnt lgkmcnt(10)
	v_mfma_f32_32x32x16_bf16 v[2:17], v[72:75], v[88:91], v[2:17]
	ds_read_b64_tr_b16 v[72:73], v109 offset:46080
	ds_read_b64_tr_b16 v[74:75], v109 offset:48384
	ds_read_b64_tr_b16 v[76:77], v0 offset:25600
	ds_read_b64_tr_b16 v[80:81], v0 offset:25664
	ds_read_b64_tr_b16 v[78:79], v0 offset:26880
	ds_read_b64_tr_b16 v[82:83], v0 offset:26944
	ds_read_b64_tr_b16 v[84:85], v0 offset:25728
	ds_read_b64_tr_b16 v[88:89], v0 offset:25792
	ds_read_b64_tr_b16 v[86:87], v0 offset:27008
	ds_read_b64_tr_b16 v[90:91], v0 offset:27072
	s_waitcnt lgkmcnt(14)
	v_mfma_f32_32x32x16_bf16 v[50:65], v[68:71], v[92:95], v[50:65]
	v_mfma_f32_32x32x16_bf16 v[34:49], v[68:71], v[96:99], v[34:49]
	s_waitcnt lgkmcnt(11)
	v_mfma_f32_32x32x16_bf16 v[18:33], v[68:71], v[100:103], v[18:33]
	s_waitcnt lgkmcnt(10)
	v_mfma_f32_32x32x16_bf16 v[2:17], v[68:71], v[104:107], v[2:17]
	ds_read_b64_tr_b16 v[68:69], v109 offset:55296
	ds_read_b64_tr_b16 v[70:71], v109 offset:57600
	ds_read_b64_tr_b16 v[92:93], v0 offset:30720
	ds_read_b64_tr_b16 v[96:97], v0 offset:30784
	ds_read_b64_tr_b16 v[94:95], v0 offset:32000
	ds_read_b64_tr_b16 v[98:99], v0 offset:32064
	ds_read_b64_tr_b16 v[100:101], v0 offset:30848
	ds_read_b64_tr_b16 v[104:105], v0 offset:30912
	ds_read_b64_tr_b16 v[102:103], v0 offset:32128
	ds_read_b64_tr_b16 v[106:107], v0 offset:32192
	s_waitcnt lgkmcnt(14)
	v_mfma_f32_32x32x16_bf16 v[50:65], v[72:75], v[76:79], v[50:65]
	v_mfma_f32_32x32x16_bf16 v[34:49], v[72:75], v[80:83], v[34:49]
	s_waitcnt lgkmcnt(11)
	v_mfma_f32_32x32x16_bf16 v[18:33], v[72:75], v[84:87], v[18:33]
	s_waitcnt lgkmcnt(10)
	v_mfma_f32_32x32x16_bf16 v[2:17], v[72:75], v[88:91], v[2:17]
	v_add_u32_e32 v74, 0x1a500, v108
	ds_read_b64_tr_b16 v[72:73], v109 offset:64512
	ds_read_b64_tr_b16 v[76:77], v0 offset:35840
	ds_read_b64_tr_b16 v[80:81], v0 offset:35904
	ds_read_b64_tr_b16 v[84:85], v0 offset:35968
	ds_read_b64_tr_b16 v[78:79], v0 offset:37120
	ds_read_b64_tr_b16 v[82:83], v0 offset:37184
	ds_read_b64_tr_b16 v[86:87], v0 offset:37248
	ds_read_b64_tr_b16 v[88:89], v0 offset:36032
	ds_read_b64_tr_b16 v[74:75], v74
	ds_read_b64_tr_b16 v[90:91], v0 offset:37312
	s_waitcnt lgkmcnt(14)
; __device__ __forceinline__ unsigned cvt_pk_bf16(float lo, float hi) { unsigned r; asm volatile("v_cvt_pk_bf16_f32 %0, %1, %2" : "=v"(r) : "v"(lo), "v"(hi)); return r; }
; #define MFMA32(a, b, c) __builtin_amdgcn_mfma_f32_32x32x16_bf16((a), (b), (c), 0, 0, 0)
; __device__ __forceinline__ int crow(int reg, int h) { return (reg & 3) + 8 * (reg >> 2) + 4 * h; }
; #define KV_FRAGS(s, buf) do { fa[buf] = cat8(tr_read(va + (16 * (s)) * VSTR), tr_read(va + (16 * (s) + 4) * VSTR)); \
;         _Pragma("unroll") for (int t_ = 0; t_ < 4; ++t_) fb[buf][t_] = cat8(tr_read(ka + (16 * (s)) * KSTR + t_ * 64), tr_read(ka + (16 * (s) + 4) * KSTR + t_ * 64)); } while (0)
; __device__ __forceinline__ void kv_unit(LAS unsigned char* lds, const bf16_t* __restrict__ proj, bf16_t* __restrict__ kvT, int b, int h, int n) {
;     ...
;     for (int s = 0; s < 8; ++s) {
;         if (s + 1 < 8) KV_FRAGS(s + 1, (s + 1) & 1);
;         __builtin_amdgcn_sched_barrier(0);
; #pragma unroll
;         for (int t = 0; t < 4; ++t) acc[t] = MFMA32(fa[s & 1], fb[s & 1][t], acc[t]);
;         __builtin_amdgcn_sched_barrier(0);
;     }
;     ...
;     bf16_t* outp = kvT + ((size_t)((b * 4 + h) * NCH + n)) * 32768;
; #pragma unroll
;     for (int t = 0; t < 4; ++t)
; #pragma unroll
;         for (int i = 0; i < 16; ++i) outp[(size_t)(32 * wid + crow(i, hh)) * 128 + t * 32 + r] = (bf16_t)(cvt_pk_bf16(acc[t][i], 0.f) & 0xffffu);
	v_mfma_f32_32x32x16_bf16 v[50:65], v[68:71], v[92:95], v[50:65]
	v_mfma_f32_32x32x16_bf16 v[34:49], v[68:71], v[96:99], v[34:49]
	s_waitcnt lgkmcnt(11)
	v_mfma_f32_32x32x16_bf16 v[18:33], v[68:71], v[100:103], v[18:33]
	s_waitcnt lgkmcnt(10)
	v_mfma_f32_32x32x16_bf16 v[2:17], v[68:71], v[104:107], v[2:17]
	s_waitcnt lgkmcnt(1)
	v_mfma_f32_32x32x16_bf16 v[50:65], v[72:75], v[76:79], v[50:65]
	v_mfma_f32_32x32x16_bf16 v[34:49], v[72:75], v[80:83], v[34:49]
	v_mfma_f32_32x32x16_bf16 v[18:33], v[72:75], v[84:87], v[18:33]
	s_waitcnt lgkmcnt(0)
	v_mfma_f32_32x32x16_bf16 v[2:17], v[72:75], v[88:91], v[2:17]
	s_lshl_b32 s2, s2, 2
	s_or_b32 s2, s2, s3
	s_mul_i32 s2, s2, 33
	s_add_i32 s2, s2, s1
	s_ashr_i32 s3, s2, 31
	s_lshl_b64 s[2:3], s[2:3], 16
	s_add_u32 s2, s69, s2
	v_lshl_or_b32 v66, v66, 2, s10
	s_addc_u32 s3, s73, s3
	v_lshlrev_b32_e32 v0, 1, v67
	v_ashrrev_i32_e32 v67, 31, v66
	v_lshl_add_u64 v[68:69], s[2:3], 0, v[0:1]
	v_lshlrev_b64 v[70:71], 8, v[66:67]
	v_cvt_pk_bf16_f32 v0, v50, v1
	v_lshl_add_u64 v[70:71], v[68:69], 0, v[70:71]
	v_or_b32_e32 v50, 1, v66
	global_store_short v[70:71], v0, off
	v_cvt_pk_bf16_f32 v0, v51, v1
	v_ashrrev_i32_e32 v51, 31, v50
	v_or_b32_e32 v72, 2, v66
	v_lshlrev_b64 v[50:51], 8, v[50:51]
	v_ashrrev_i32_e32 v73, 31, v72
	v_lshl_add_u64 v[50:51], v[68:69], 0, v[50:51]
	v_lshlrev_b64 v[72:73], 8, v[72:73]
	global_store_short v[50:51], v0, off
	v_cvt_pk_bf16_f32 v0, v52, v1
	v_lshl_add_u64 v[72:73], v[68:69], 0, v[72:73]
	v_or_b32_e32 v52, 3, v66
	global_store_short v[72:73], v0, off
	v_cvt_pk_bf16_f32 v0, v53, v1
	v_ashrrev_i32_e32 v53, 31, v52
	v_or_b32_e32 v74, 8, v66
	v_lshlrev_b64 v[52:53], 8, v[52:53]
	v_ashrrev_i32_e32 v75, 31, v74
	v_lshl_add_u64 v[52:53], v[68:69], 0, v[52:53]
	v_lshlrev_b64 v[74:75], 8, v[74:75]
	global_store_short v[52:53], v0, off
	v_cvt_pk_bf16_f32 v0, v54, v1
	v_lshl_add_u64 v[74:75], v[68:69], 0, v[74:75]
	v_or_b32_e32 v54, 9, v66
	global_store_short v[74:75], v0, off
	v_cvt_pk_bf16_f32 v0, v55, v1
	v_ashrrev_i32_e32 v55, 31, v54
	v_or_b32_e32 v76, 10, v66
	v_lshlrev_b64 v[54:55], 8, v[54:55]
	v_ashrrev_i32_e32 v77, 31, v76
	v_lshl_add_u64 v[54:55], v[68:69], 0, v[54:55]
	v_lshlrev_b64 v[76:77], 8, v[76:77]
	global_store_short v[54:55], v0, off
	v_cvt_pk_bf16_f32 v0, v56, v1
	v_lshl_add_u64 v[76:77], v[68:69], 0, v[76:77]
	v_or_b32_e32 v56, 11, v66
	global_store_short v[76:77], v0, off
	v_cvt_pk_bf16_f32 v0, v57, v1
	v_ashrrev_i32_e32 v57, 31, v56
	v_or_b32_e32 v78, 16, v66
	v_lshlrev_b64 v[56:57], 8, v[56:57]
	v_ashrrev_i32_e32 v79, 31, v78
	v_lshl_add_u64 v[56:57], v[68:69], 0, v[56:57]
	v_lshlrev_b64 v[78:79], 8, v[78:79]
	global_store_short v[56:57], v0, off
	v_cvt_pk_bf16_f32 v0, v58, v1
	v_lshl_add_u64 v[78:79], v[68:69], 0, v[78:79]
	v_or_b32_e32 v58, 17, v66
	global_store_short v[78:79], v0, off
	v_cvt_pk_bf16_f32 v0, v59, v1
	v_ashrrev_i32_e32 v59, 31, v58
	v_or_b32_e32 v80, 18, v66
	v_lshlrev_b64 v[58:59], 8, v[58:59]
	v_ashrrev_i32_e32 v81, 31, v80
	v_lshl_add_u64 v[58:59], v[68:69], 0, v[58:59]
	v_lshlrev_b64 v[80:81], 8, v[80:81]
	global_store_short v[58:59], v0, off
	v_cvt_pk_bf16_f32 v0, v60, v1
	v_lshl_add_u64 v[80:81], v[68:69], 0, v[80:81]
	v_or_b32_e32 v60, 19, v66
	global_store_short v[80:81], v0, off
	v_cvt_pk_bf16_f32 v0, v61, v1
	v_ashrrev_i32_e32 v61, 31, v60
	v_or_b32_e32 v82, 24, v66
	v_lshlrev_b64 v[60:61], 8, v[60:61]
	v_ashrrev_i32_e32 v83, 31, v82
	v_lshl_add_u64 v[60:61], v[68:69], 0, v[60:61]
	v_lshlrev_b64 v[82:83], 8, v[82:83]
	global_store_short v[60:61], v0, off
	v_cvt_pk_bf16_f32 v0, v62, v1
	v_lshl_add_u64 v[82:83], v[68:69], 0, v[82:83]
	v_or_b32_e32 v62, 25, v66
	global_store_short v[82:83], v0, off
	v_cvt_pk_bf16_f32 v0, v63, v1
	v_ashrrev_i32_e32 v63, 31, v62
	v_or_b32_e32 v84, 26, v66
	v_lshlrev_b64 v[62:63], 8, v[62:63]
	v_ashrrev_i32_e32 v85, 31, v84
	v_lshl_add_u64 v[62:63], v[68:69], 0, v[62:63]
	v_lshlrev_b64 v[84:85], 8, v[84:85]
	global_store_short v[62:63], v0, off
	v_cvt_pk_bf16_f32 v0, v64, v1
	v_lshl_add_u64 v[84:85], v[68:69], 0, v[84:85]
	v_or_b32_e32 v64, 27, v66
	global_store_short v[84:85], v0, off
; __device__ __forceinline__ unsigned cvt_pk_bf16(float lo, float hi) { unsigned r; asm volatile("v_cvt_pk_bf16_f32 %0, %1, %2" : "=v"(r) : "v"(lo), "v"(hi)); return r; }
; __device__ __forceinline__ int crow(int reg, int h) { return (reg & 3) + 8 * (reg >> 2) + 4 * h; }
; __device__ __forceinline__ void kv_unit(LAS unsigned char* lds, const bf16_t* __restrict__ proj, bf16_t* __restrict__ kvT, int b, int h, int n) {
;     ...
;     bf16_t* outp = kvT + ((size_t)((b * 4 + h) * NCH + n)) * 32768;
; #pragma unroll
;     for (int t = 0; t < 4; ++t)
; #pragma unroll
;         for (int i = 0; i < 16; ++i) outp[(size_t)(32 * wid + crow(i, hh)) * 128 + t * 32 + r] = (bf16_t)(cvt_pk_bf16(acc[t][i], 0.f) & 0xffffu);
; __global__ void __launch_bounds__(512, 2) hymba_fwd(Args a) {
;     ...
;         for (int u = bx; u < 16 * 32; u += G) ret::kv_unit(lds, proj, kvT, u >> 7, (u >> 5) & 3, u & 31);
	v_cvt_pk_bf16_f32 v0, v65, v1
	v_ashrrev_i32_e32 v65, 31, v64
	v_lshlrev_b64 v[64:65], 8, v[64:65]
	v_lshl_add_u64 v[64:65], v[68:69], 0, v[64:65]
	global_store_short v[64:65], v0, off
	v_cvt_pk_bf16_f32 v0, v34, v1
	global_store_short v[70:71], v0, off offset:64
	v_cvt_pk_bf16_f32 v0, v35, v1
	global_store_short v[50:51], v0, off offset:64
	v_cvt_pk_bf16_f32 v0, v36, v1
	global_store_short v[72:73], v0, off offset:64
	v_cvt_pk_bf16_f32 v0, v37, v1
	global_store_short v[52:53], v0, off offset:64
	v_cvt_pk_bf16_f32 v0, v38, v1
	global_store_short v[74:75], v0, off offset:64
	v_cvt_pk_bf16_f32 v0, v39, v1
	global_store_short v[54:55], v0, off offset:64
	v_cvt_pk_bf16_f32 v0, v40, v1
	global_store_short v[76:77], v0, off offset:64
	v_cvt_pk_bf16_f32 v0, v41, v1
	global_store_short v[56:57], v0, off offset:64
	v_cvt_pk_bf16_f32 v0, v42, v1
	global_store_short v[78:79], v0, off offset:64
	v_cvt_pk_bf16_f32 v0, v43, v1
	global_store_short v[58:59], v0, off offset:64
	v_cvt_pk_bf16_f32 v0, v44, v1
	global_store_short v[80:81], v0, off offset:64
	v_cvt_pk_bf16_f32 v0, v45, v1
	global_store_short v[60:61], v0, off offset:64
	v_cvt_pk_bf16_f32 v0, v46, v1
	global_store_short v[82:83], v0, off offset:64
	v_cvt_pk_bf16_f32 v0, v47, v1
	global_store_short v[62:63], v0, off offset:64
	v_cvt_pk_bf16_f32 v0, v48, v1
	global_store_short v[84:85], v0, off offset:64
	v_cvt_pk_bf16_f32 v0, v49, v1
	global_store_short v[64:65], v0, off offset:64
	v_cvt_pk_bf16_f32 v0, v18, v1
	global_store_short v[70:71], v0, off offset:128
	v_cvt_pk_bf16_f32 v0, v19, v1
	global_store_short v[50:51], v0, off offset:128
	v_cvt_pk_bf16_f32 v0, v20, v1
	global_store_short v[72:73], v0, off offset:128
	v_cvt_pk_bf16_f32 v0, v21, v1
	global_store_short v[52:53], v0, off offset:128
	v_cvt_pk_bf16_f32 v0, v22, v1
	global_store_short v[74:75], v0, off offset:128
	v_cvt_pk_bf16_f32 v0, v23, v1
	global_store_short v[54:55], v0, off offset:128
	v_cvt_pk_bf16_f32 v0, v24, v1
	global_store_short v[76:77], v0, off offset:128
	v_cvt_pk_bf16_f32 v0, v25, v1
	global_store_short v[56:57], v0, off offset:128
	v_cvt_pk_bf16_f32 v0, v26, v1
	global_store_short v[78:79], v0, off offset:128
	v_cvt_pk_bf16_f32 v0, v27, v1
	global_store_short v[58:59], v0, off offset:128
	v_cvt_pk_bf16_f32 v0, v28, v1
	global_store_short v[80:81], v0, off offset:128
	v_cvt_pk_bf16_f32 v0, v29, v1
	global_store_short v[60:61], v0, off offset:128
	v_cvt_pk_bf16_f32 v0, v30, v1
	global_store_short v[82:83], v0, off offset:128
	v_cvt_pk_bf16_f32 v0, v31, v1
	global_store_short v[62:63], v0, off offset:128
	v_cvt_pk_bf16_f32 v0, v32, v1
	global_store_short v[84:85], v0, off offset:128
	v_cvt_pk_bf16_f32 v0, v33, v1
	global_store_short v[64:65], v0, off offset:128
	v_cvt_pk_bf16_f32 v0, v2, v1
	global_store_short v[70:71], v0, off offset:192
	v_cvt_pk_bf16_f32 v0, v3, v1
	global_store_short v[50:51], v0, off offset:192
	v_cvt_pk_bf16_f32 v0, v4, v1
	global_store_short v[72:73], v0, off offset:192
	v_cvt_pk_bf16_f32 v0, v5, v1
	global_store_short v[52:53], v0, off offset:192
	v_cvt_pk_bf16_f32 v0, v6, v1
	global_store_short v[74:75], v0, off offset:192
	v_cvt_pk_bf16_f32 v0, v7, v1
	global_store_short v[54:55], v0, off offset:192
	v_cvt_pk_bf16_f32 v0, v8, v1
	global_store_short v[76:77], v0, off offset:192
	v_cvt_pk_bf16_f32 v0, v9, v1
	global_store_short v[56:57], v0, off offset:192
	v_cvt_pk_bf16_f32 v0, v10, v1
	global_store_short v[78:79], v0, off offset:192
	v_cvt_pk_bf16_f32 v0, v11, v1
	global_store_short v[58:59], v0, off offset:192
	v_cvt_pk_bf16_f32 v0, v12, v1
	global_store_short v[80:81], v0, off offset:192
	v_cvt_pk_bf16_f32 v0, v13, v1
	global_store_short v[60:61], v0, off offset:192
	v_cvt_pk_bf16_f32 v0, v14, v1
	global_store_short v[82:83], v0, off offset:192
	v_cvt_pk_bf16_f32 v0, v15, v1
	s_add_i32 s0, s0, s88
	global_store_short v[62:63], v0, off offset:192
	v_cvt_pk_bf16_f32 v0, v16, v1
	s_cmpk_gt_i32 s0, 0x1ff
	global_store_short v[84:85], v0, off offset:192
	v_cvt_pk_bf16_f32 v0, v17, v1
	global_store_short v[64:65], v0, off offset:192
	s_cbranch_scc0 .LBB0_260

; #define LAS __attribute__((address_space(3)))
; __device__ __forceinline__ float bf_lo(unsigned w) { return __uint_as_float(w << 16); }
; __device__ __forceinline__ float bf_hi(unsigned w) { return __uint_as_float(w & 0xffff0000u); }
; __device__ __forceinline__ unsigned scale_pk(unsigned w, float c) { return cvt_pk_bf16(bf_lo(w) * c, bf_hi(w) * c); }
; __device__ __forceinline__ void attn_unit(LAS unsigned char* lds, const bf16_t* __restrict__ proj, bf16_t* __restrict__ y, int b, int h, int qb,
;                                           float lam, const float* __restrict__ subln, float post_scale, const unsigned* __restrict__ kmax2) {
;     int tid = threadIdx.x; asm volatile("" : "+v"(tid));
;     const int lane = tid & 63, wid = __builtin_amdgcn_readfirstlane(tid >> 6);
;     const int map = wid & 1, g = wid >> 1, r = lane & 31, hh = lane >> 5;
;     const int g16 = (lane >> 4) & 1, q4 = (lane & 15) >> 2, p4 = lane & 3;
;     const size_t rowbase = (size_t)b * LTOK; const int q0 = qb * CH;
;     const int qpos = q0 + g * 32 + r;
;     const float slope = __builtin_amdgcn_exp2f(-(float)(h + 1));
;     const float c1 = 0.125f * LOG2E, c2 = slope * LOG2E;
;     bf16x8 qf[4];
;     float qn2 = 0.f;
;     { const bf16_t* qp = proj + (rowbase + qpos) * DIN + C_AQ + h * 128 + map * 64 + hh * 8;
; #pragma unroll
;       for (int s = 0; s < 4; ++s) { u32x4 w = *(const u32x4*)(qp + s * 16); w.x = scale_pk(w.x, c1); w.y = scale_pk(w.y, c1); w.z = scale_pk(w.z, c1); w.w = scale_pk(w.w, c1); qf[s] = __builtin_bit_cast(bf16x8, w);
; #pragma unroll
;           for (int k = 0; k < 4; ++k) { const float lo = bf_lo(w[k]), hi = bf_hi(w[k]); qn2 += lo * lo + hi * hi; } } }
; __global__ void __launch_bounds__(512, 2) hymba_fwd(Args a) {
;     ...
;                     if (u < 256 || u >= 256 + 528) { const int w = u < 256 ? u : u - 528; att::attn_unit(lds, proj, ybuf, w & 3, (w >> 2) & 7, 32 - (w >> 5), lam, a.attn_subln + l * 128, 1.0f - lam_init, ctl + 1536 + l * 64); }
.LBB0_396:
	s_and_b64 vcc, exec, s[14:15]
	s_cbranch_vccz .LBB0_383
	s_add_i32 s1, s0, 0xfffffdf0
	s_cmpk_lt_i32 s0, 0x100
	s_cselect_b32 s0, s0, s1
	v_mov_b32_e32 v34, v208
	s_and_b32 s11, s0, 3
	s_bfe_u32 s20, s0, 0x30002
	s_ashr_i32 s21, s0, 5
	s_sub_i32 s10, 32, s21
	v_readfirstlane_b32 s0, v34
	s_ashr_i32 s3, s0, 7
	s_ashr_i32 s22, s0, 6
	s_lshl_b32 s1, s10, 7
	s_lshl_b32 s0, s3, 5
	v_and_b32_e32 v185, 31, v34
	s_add_i32 s14, s0, s1
	v_or_b32_e32 v162, s14, v185
	s_mul_i32 s8, s11, 0x1080
	v_ashrrev_i32_e32 v163, 31, v162
	v_lshl_add_u64 v[4:5], v[162:163], 0, s[8:9]
	v_mov_b64_e32 v[2:3], s[6:7]
	v_mad_u64_u32 v[8:9], s[14:15], v4, s35, v[2:3]
	s_and_b32 s2, s22, 1
	v_mad_i32_i24 v9, v5, s35, v9
	s_lshl_b32 s16, s20, 8
	s_mov_b32 s17, s9
	v_bfe_u32 v6, v34, 5, 1
	v_lshl_add_u64 v[4:5], v[8:9], 0, s[16:17]
	s_lshl_b32 s14, s2, 7
	s_mov_b32 s15, s9
	v_lshl_add_u64 v[4:5], v[4:5], 0, s[14:15]
	v_lshlrev_b32_e32 v0, 4, v6
	v_lshl_add_u64 v[4:5], v[4:5], 0, v[0:1]
	global_load_dwordx4 v[8:11], v[4:5], off
	global_load_dwordx4 v[228:231], v[4:5], off offset:32
	global_load_dwordx4 v[232:235], v[4:5], off offset:64
	global_load_dwordx4 v[236:239], v[4:5], off offset:96
	s_lshl_b32 s11, s11, 4
	s_lshl_b32 s15, s20, 1
	s_or_b32 s11, s15, s11
	s_or_b32 s11, s2, s11
	s_lshl_b32 s11, s11, 2
	v_and_b32_e32 v35, 15, v34
	s_lshl_b32 s10, s10, 1
	s_waitcnt vmcnt(3)
	v_lshlrev_b32_e32 v7, 16, v8
	v_and_b32_e32 v8, 0xffff0000, v8
	v_mul_f32_e32 v8, 0x3e38aa3b, v8
	v_mul_f32_e32 v7, 0x3e38aa3b, v7
	v_cvt_pk_bf16_f32 v112, v7, v8
	v_and_b32_e32 v8, 0xffff0000, v9
	v_lshlrev_b32_e32 v7, 16, v9
	v_mul_f32_e32 v8, 0x3e38aa3b, v8
	v_mul_f32_e32 v7, 0x3e38aa3b, v7
	v_cvt_pk_bf16_f32 v113, v7, v8
	v_and_b32_e32 v8, 0xffff0000, v10
	v_lshlrev_b32_e32 v7, 16, v10
	v_mul_f32_e32 v8, 0x3e38aa3b, v8
	v_mul_f32_e32 v7, 0x3e38aa3b, v7
	v_cvt_pk_bf16_f32 v114, v7, v8
	v_and_b32_e32 v8, 0xffff0000, v11
	v_lshlrev_b32_e32 v7, 16, v11
	v_mul_f32_e32 v8, 0x3e38aa3b, v8
	v_mul_f32_e32 v7, 0x3e38aa3b, v7
	v_cvt_pk_bf16_f32 v115, v7, v8
	v_and_b32_e32 v8, 0xffff0000, v112
	v_lshlrev_b32_e32 v7, 16, v112
	v_mul_f32_e32 v8, v8, v8
	v_and_b32_e32 v9, 0xffff0000, v113
	v_fmac_f32_e32 v8, v7, v7
	v_lshlrev_b32_e32 v7, 16, v113
	v_mul_f32_e32 v9, v9, v9
	v_fmac_f32_e32 v9, v7, v7
	v_add_f32_e32 v7, v8, v9
	v_and_b32_e32 v9, 0xffff0000, v114
	v_lshlrev_b32_e32 v8, 16, v114
	v_mul_f32_e32 v9, v9, v9
	v_fmac_f32_e32 v9, v8, v8
	v_add_f32_e32 v7, v7, v9
	v_and_b32_e32 v9, 0xffff0000, v115
	v_lshlrev_b32_e32 v8, 16, v115
	v_mul_f32_e32 v9, v9, v9
	v_fmac_f32_e32 v9, v8, v8
	v_add_f32_e32 v7, v7, v9
	s_waitcnt vmcnt(2)
	v_mov_b32_e32 v8, v228
	v_mov_b32_e32 v9, v229
	v_mov_b32_e32 v10, v230
	v_mov_b32_e32 v11, v231
	v_lshlrev_b32_e32 v12, 16, v8
	v_and_b32_e32 v8, 0xffff0000, v8
	v_mul_f32_e32 v8, 0x3e38aa3b, v8
	v_mul_f32_e32 v12, 0x3e38aa3b, v12
	v_cvt_pk_bf16_f32 v116, v12, v8
	v_lshlrev_b32_e32 v8, 16, v9
	v_and_b32_e32 v9, 0xffff0000, v9
	v_mul_f32_e32 v9, 0x3e38aa3b, v9
	v_mul_f32_e32 v8, 0x3e38aa3b, v8
	v_cvt_pk_bf16_f32 v117, v8, v9
	v_and_b32_e32 v9, 0xffff0000, v10
	v_lshlrev_b32_e32 v8, 16, v10
	v_mul_f32_e32 v9, 0x3e38aa3b, v9
	v_mul_f32_e32 v8, 0x3e38aa3b, v8
	v_cvt_pk_bf16_f32 v118, v8, v9
	v_and_b32_e32 v9, 0xffff0000, v11
	v_lshlrev_b32_e32 v8, 16, v11
	v_mul_f32_e32 v9, 0x3e38aa3b, v9
	v_mul_f32_e32 v8, 0x3e38aa3b, v8
	v_cvt_pk_bf16_f32 v119, v8, v9
	v_and_b32_e32 v9, 0xffff0000, v116
	v_lshlrev_b32_e32 v8, 16, v116
	v_mul_f32_e32 v9, v9, v9
	v_fmac_f32_e32 v9, v8, v8
	v_add_f32_e32 v7, v7, v9
	v_and_b32_e32 v9, 0xffff0000, v117
	v_lshlrev_b32_e32 v8, 16, v117
	v_mul_f32_e32 v9, v9, v9
	v_fmac_f32_e32 v9, v8, v8
	v_add_f32_e32 v7, v7, v9
	v_and_b32_e32 v9, 0xffff0000, v118
	v_lshlrev_b32_e32 v8, 16, v118
	v_mul_f32_e32 v9, v9, v9
	v_fmac_f32_e32 v9, v8, v8
	v_add_f32_e32 v7, v7, v9
	v_and_b32_e32 v9, 0xffff0000, v119
	v_lshlrev_b32_e32 v8, 16, v119
	v_mul_f32_e32 v9, v9, v9
	v_fmac_f32_e32 v9, v8, v8
	v_add_f32_e32 v7, v7, v9
	s_waitcnt vmcnt(1)
; #define LAS __attribute__((address_space(3)))
; __device__ __forceinline__ float bf_lo(unsigned w) { return __uint_as_float(w << 16); }
; __device__ __forceinline__ float bf_hi(unsigned w) { return __uint_as_float(w & 0xffff0000u); }
; #define ATT_BAR() asm volatile("s_waitcnt lgkmcnt(0)\n\ts_barrier" ::: "memory")
; __device__ __forceinline__ unsigned scale_pk(unsigned w, float c) { return cvt_pk_bf16(bf_lo(w) * c, bf_hi(w) * c); }
; #define LOADK(j) do { _Pragma("unroll") for (int i_ = 0; i_ < 2; ++i_) kreg[i_] = *(const u32x4*)(kg + (size_t)((j) * 64 + 32 * i_) * DIN); } while (0)
; __device__ __forceinline__ void attn_unit(LAS unsigned char* lds, const bf16_t* __restrict__ proj, bf16_t* __restrict__ y, int b, int h, int qb,
;                                           float lam, const float* __restrict__ subln, float post_scale, const unsigned* __restrict__ kmax2) {
;     ...
;     { const bf16_t* qp = proj + (rowbase + qpos) * DIN + C_AQ + h * 128 + map * 64 + hh * 8;
; #pragma unroll
;       for (int s = 0; s < 4; ++s) { u32x4 w = *(const u32x4*)(qp + s * 16); w.x = scale_pk(w.x, c1); w.y = scale_pk(w.y, c1); w.z = scale_pk(w.z, c1); w.w = scale_pk(w.w, c1); qf[s] = __builtin_bit_cast(bf16x8, w);
; #pragma unroll
;           for (int k = 0; k < 4; ++k) { const float lo = bf_lo(w[k]), hi = bf_hi(w[k]); qn2 += lo * lo + hi * hi; } } }
;     qn2 += __shfl_xor(qn2, 32);
;     const float ub0 = sqrtf(qn2) * sqrtf(__uint_as_float(kmax2[(b * 8 + h) * 2 + map])) * 1.002f + 1.0f + c2 * (float)(63 - qpos) + 160.0f;
;     LAS volatile unsigned char* FLG = (LAS volatile unsigned char*)(lds + LDS_MISC + 96);
;     f32x16 o[4];
; #pragma unroll
;     for (int t = 0; t < 4; ++t) o[t] = zero16();
;     float m_ref = 0.f, l_run = 0.f;
;     const int jend = 2 * qb + 1;
;     const int skey = tid >> 4, sc = tid & 15;
;     const bf16_t* kg = proj + (rowbase + skey) * DIN + C_AK + h * 128 + sc * 8;
;     const bf16_t* vg = proj + (rowbase + skey) * DIN + C_AV + h * 128 + sc * 8;
;     u32x4 kreg[2], vreg[2];
;     ...
;     const int kAo = r * KSTR + map * 128 + hh * 16;
;     const int vAo = L_VRING + (4 * hh + q4) * VSTR + 32 * g16 + 8 * p4;
;     f32x16 s0, s1; float mx;
;     ...
;     bf16x8 pb[4];
;     LOADK(jend); LOADV(jend);
;     ATT_BAR();
;     STOREK(jend); STOREV(jend);
;     if (jend >= 2) LOADK(jend - 1);
	v_mov_b32_e32 v8, v232
	v_mov_b32_e32 v9, v233
	v_mov_b32_e32 v10, v234
	v_mov_b32_e32 v11, v235
	v_lshlrev_b32_e32 v12, 16, v8
	v_and_b32_e32 v8, 0xffff0000, v8
	v_mul_f32_e32 v8, 0x3e38aa3b, v8
	v_mul_f32_e32 v12, 0x3e38aa3b, v12
	v_cvt_pk_bf16_f32 v120, v12, v8
	v_lshlrev_b32_e32 v8, 16, v9
	v_and_b32_e32 v9, 0xffff0000, v9
	v_mul_f32_e32 v9, 0x3e38aa3b, v9
	v_mul_f32_e32 v8, 0x3e38aa3b, v8
	v_cvt_pk_bf16_f32 v121, v8, v9
	v_and_b32_e32 v9, 0xffff0000, v10
	v_lshlrev_b32_e32 v8, 16, v10
	v_mul_f32_e32 v9, 0x3e38aa3b, v9
	v_mul_f32_e32 v8, 0x3e38aa3b, v8
	v_cvt_pk_bf16_f32 v122, v8, v9
	v_and_b32_e32 v9, 0xffff0000, v11
	v_lshlrev_b32_e32 v8, 16, v11
	v_mul_f32_e32 v9, 0x3e38aa3b, v9
	v_mul_f32_e32 v8, 0x3e38aa3b, v8
	v_cvt_pk_bf16_f32 v123, v8, v9
	v_and_b32_e32 v9, 0xffff0000, v120
	v_lshlrev_b32_e32 v8, 16, v120
	v_mul_f32_e32 v9, v9, v9
	v_fmac_f32_e32 v9, v8, v8
	v_add_f32_e32 v7, v7, v9
	v_and_b32_e32 v9, 0xffff0000, v121
	v_lshlrev_b32_e32 v8, 16, v121
	v_mul_f32_e32 v9, v9, v9
	v_fmac_f32_e32 v9, v8, v8
	v_add_f32_e32 v7, v7, v9
	v_and_b32_e32 v9, 0xffff0000, v122
	v_lshlrev_b32_e32 v8, 16, v122
	v_mul_f32_e32 v9, v9, v9
	v_fmac_f32_e32 v9, v8, v8
	v_add_f32_e32 v7, v7, v9
	v_and_b32_e32 v9, 0xffff0000, v123
	v_lshlrev_b32_e32 v8, 16, v123
	v_mul_f32_e32 v9, v9, v9
	v_fmac_f32_e32 v9, v8, v8
	v_add_f32_e32 v7, v7, v9
	s_waitcnt vmcnt(0)
	v_mov_b32_e32 v8, v236
	v_mov_b32_e32 v9, v237
	v_mov_b32_e32 v10, v238
	v_mov_b32_e32 v11, v239
	v_and_b32_e32 v5, 0xffff0000, v8
	v_lshlrev_b32_e32 v4, 16, v8
	v_mul_f32_e32 v5, 0x3e38aa3b, v5
	v_mul_f32_e32 v4, 0x3e38aa3b, v4
	v_cvt_pk_bf16_f32 v124, v4, v5
	v_and_b32_e32 v5, 0xffff0000, v9
	v_lshlrev_b32_e32 v4, 16, v9
	v_mul_f32_e32 v5, 0x3e38aa3b, v5
	v_mul_f32_e32 v4, 0x3e38aa3b, v4
	v_cvt_pk_bf16_f32 v125, v4, v5
	v_and_b32_e32 v5, 0xffff0000, v10
	v_lshlrev_b32_e32 v4, 16, v10
	v_mul_f32_e32 v5, 0x3e38aa3b, v5
	v_mul_f32_e32 v4, 0x3e38aa3b, v4
	v_cvt_pk_bf16_f32 v126, v4, v5
	v_and_b32_e32 v5, 0xffff0000, v11
	v_lshlrev_b32_e32 v4, 16, v11
	v_mul_f32_e32 v5, 0x3e38aa3b, v5
	v_mul_f32_e32 v4, 0x3e38aa3b, v4
	v_cvt_pk_bf16_f32 v127, v4, v5
	v_and_b32_e32 v5, 0xffff0000, v124
	v_lshlrev_b32_e32 v4, 16, v124
	v_mul_f32_e32 v5, v5, v5
	v_fmac_f32_e32 v5, v4, v4
	v_add_f32_e32 v4, v7, v5
	v_and_b32_e32 v7, 0xffff0000, v125
	v_lshlrev_b32_e32 v5, 16, v125
	v_mul_f32_e32 v7, v7, v7
	v_fmac_f32_e32 v7, v5, v5
	v_add_f32_e32 v4, v4, v7
	v_and_b32_e32 v7, 0xffff0000, v126
	v_lshlrev_b32_e32 v5, 16, v126
	v_mul_f32_e32 v7, v7, v7
	v_fmac_f32_e32 v7, v5, v5
	v_add_f32_e32 v4, v4, v7
	v_and_b32_e32 v7, 0xffff0000, v127
	v_lshlrev_b32_e32 v5, 16, v127
	v_mul_f32_e32 v7, v7, v7
	v_fmac_f32_e32 v7, v5, v5
	v_add_f32_e32 v37, v4, v7
	v_mov_b32_e32 v4, s11
	v_ashrrev_i32_e32 v7, 4, v34
	global_load_dword v36, v4, s[54:55]
	v_add_u32_e32 v4, s8, v7
	v_mad_i64_i32 v[2:3], s[18:19], v4, s35, v[2:3]
	s_or_b32 s11, s10, 1
	v_lshl_add_u64 v[2:3], v[2:3], 0, s[16:17]
	v_lshlrev_b32_e32 v4, 4, v35
	v_mov_b32_e32 v5, v1
	v_lshl_add_u64 v[164:165], v[2:3], 0, v[4:5]
	s_lshl_b32 s15, s11, 6
	v_mad_i64_i32 v[2:3], s[16:17], s15, v213, v[164:165]
	s_or_b32 s18, s15, 32
	global_load_dwordx4 v[128:131], v[2:3], off offset:2048
	v_mad_i64_i32 v[2:3], s[16:17], s18, v213, v[164:165]
	s_mov_b64 s[16:17], 0x1000
	s_nop 0
	v_lshl_add_u64 v[166:167], v[164:165], 0, s[16:17]
	global_load_dwordx4 v[132:135], v[2:3], off offset:2048
	v_mad_i64_i32 v[2:3], s[16:17], s15, v213, v[166:167]
	global_load_dwordx4 v[136:139], v[2:3], off
	v_mad_i64_i32 v[2:3], s[16:17], s18, v213, v[166:167]
	global_load_dwordx4 v[140:143], v[2:3], off
	ds_bpermute_b32 v38, v215, v37
	s_movk_i32 s16, 0x110
	s_waitcnt lgkmcnt(0)
	s_barrier
	v_add_u32_e32 v186, 0, v4
	v_mul_lo_u32 v187, v7, s16
	v_mul_lo_u32 v188, v7, s75
	v_add_u32_e32 v39, v186, v187
	v_add_u32_e32 v2, v186, v188
	s_cmp_lt_i32 s21, 32
	s_waitcnt vmcnt(3)
	ds_write_b128 v39, v[128:131] offset:17408
	s_waitcnt vmcnt(2)
	ds_write_b128 v39, v[132:135] offset:26112
	s_cselect_b64 s[16:17], -1, 0
	s_cmp_gt_i32 s21, 31
	s_waitcnt vmcnt(1)
	ds_write_b128 v2, v[136:139] offset:55296
	v_add_u32_e32 v2, 0x10000, v2
	s_waitcnt vmcnt(0)
	ds_write_b128 v2, v[140:143]
	s_cbranch_scc1 .LBB0_399
	v_mad_u64_u32 v[2:3], s[18:19], s1, v213, v[164:165]
	s_or_b32 s18, s1, 32
	s_nop 0
	v_mad_u64_u32 v[4:5], s[18:19], s18, v213, v[164:165]
	global_load_dwordx4 v[128:131], v[2:3], off offset:2048
	global_load_dwordx4 v[132:135], v[4:5], off offset:2048

;     __device__ __forceinline__ void fused(f32x4 (&acc)[2][2][4][2], const Unit& u, int wr, int wc, int fr, int fq, PG8_LAS unsigned char* lds, int tid) const {
;     ...
;         const int qa = u.ks >> 1, qm = (u.ks & 1) * 2;
;         const f32x4* base = (const f32x4*)(partials + (size_t)slot * 4 * 65536) + tid;
; #pragma unroll
;         for (int bj = 0; bj < 2; ++bj) {
;             f32x4 pp[2][2][4];
; #pragma unroll
;             for (int mm = 0; mm < 2; ++mm)
; #pragma unroll
;                 for (int n = 0; n < 2; ++n)
; #pragma unroll
;                     for (int sl = 0; sl < 4; ++sl) pp[mm][n][sl] = base[(size_t)sl * 16384 + (size_t)(((qa * 2 + bj) * 4 + qm + mm) * 2 + n) * 512];
; #pragma unroll
;             for (int ai = 0; ai < 2; ++ai)
; #pragma unroll
;                 for (int mh = 0; mh < 2; ++mh)
;                     if (ai == qa && mh * 2 == qm) {
; #pragma unroll
;                         for (int mm = 0; mm < 2; ++mm)
; #pragma unroll
;                             for (int n = 0; n < 2; ++n) acc[ai][bj][mh * 2 + mm][n] = ((pp[mm][n][0] + pp[mm][n][1]) + pp[mm][n][2]) + pp[mm][n][3];
;                     }
;             asm volatile("" ::: "memory");
;         }
.LBB0_531:
	s_or_b64 exec, exec, s[14:15]
	v_readlane_b32 s2, v254, 52
	v_readlane_b32 s3, v254, 53
	s_movk_i32 s1, 0x4000
	s_barrier
	v_lshl_add_u64 v[204:205], v[130:131], 4, s[2:3]
	v_readlane_b32 s2, v255, 15
	v_readlane_b32 s3, v255, 16
	s_nop 1
	v_lshl_add_u64 v[186:187], v[204:205], 0, s[2:3]
	v_add_co_u32_e32 v134, vcc, 0x40000, v186
	v_readlane_b32 s2, v254, 56
	s_nop 0
	v_addc_co_u32_e32 v135, vcc, 0, v187, vcc
	v_add_co_u32_e32 v138, vcc, 0x80000, v186
	global_load_dwordx4 v[130:133], v[186:187], off
	s_nop 0
	global_load_dwordx4 v[134:137], v[134:135], off
	v_addc_co_u32_e32 v139, vcc, 0, v187, vcc
	v_add_co_u32_e32 v140, vcc, 0xc0000, v186
	v_readlane_b32 s3, v254, 57
	s_nop 0
	v_addc_co_u32_e32 v141, vcc, 0, v187, vcc
	v_add_co_u32_e32 v146, vcc, s68, v186
	global_load_dwordx4 v[142:145], v[138:139], off
	s_nop 0
	global_load_dwordx4 v[138:141], v[140:141], off
	v_addc_co_u32_e32 v147, vcc, 0, v187, vcc
	v_add_co_u32_e32 v150, vcc, 0x42000, v186
	v_addc_co_u32_e32 v151, vcc, 0, v187, vcc
	v_add_co_u32_e32 v154, vcc, 0x82000, v186
	global_load_dwordx4 v[146:149], v[146:147], off
	s_nop 0
	global_load_dwordx4 v[150:153], v[150:151], off
	v_addc_co_u32_e32 v155, vcc, 0, v187, vcc
	v_add_co_u32_e32 v156, vcc, 0xc2000, v186
	v_addc_co_u32_e32 v157, vcc, 0, v187, vcc
	v_add_co_u32_e32 v162, vcc, s1, v186
	s_movk_i32 s1, 0x6000
	s_nop 0
	v_addc_co_u32_e32 v163, vcc, 0, v187, vcc
	v_add_co_u32_e32 v166, vcc, 0x44000, v186
	global_load_dwordx4 v[158:161], v[154:155], off
	s_nop 0
	global_load_dwordx4 v[154:157], v[156:157], off
	v_addc_co_u32_e32 v167, vcc, 0, v187, vcc
	v_add_co_u32_e32 v170, vcc, 0x84000, v186
	global_load_dwordx4 v[162:165], v[162:163], off
	s_nop 0
	global_load_dwordx4 v[166:169], v[166:167], off
	v_addc_co_u32_e32 v171, vcc, 0, v187, vcc
	v_add_co_u32_e32 v172, vcc, 0xc4000, v186
	v_addc_co_u32_e32 v173, vcc, 0, v187, vcc
	v_add_co_u32_e32 v178, vcc, s1, v186
	global_load_dwordx4 v[174:177], v[170:171], off
	s_nop 0
	global_load_dwordx4 v[170:173], v[172:173], off
	v_addc_co_u32_e32 v179, vcc, 0, v187, vcc
	v_add_co_u32_e32 v182, vcc, 0x46000, v186
	s_nop 1
	v_addc_co_u32_e32 v183, vcc, 0, v187, vcc
	v_add_co_u32_e32 v188, vcc, 0x86000, v186
	global_load_dwordx4 v[178:181], v[178:179], off
	s_nop 0
	global_load_dwordx4 v[182:185], v[182:183], off
	v_addc_co_u32_e32 v189, vcc, 0, v187, vcc
	v_add_co_u32_e32 v186, vcc, 0xc6000, v186
	v_addc_co_u32_e32 v187, vcc, 0, v187, vcc
	global_load_dwordx4 v[190:193], v[188:189], off
	s_nop 0
	global_load_dwordx4 v[186:189], v[186:187], off
	s_waitcnt vmcnt(0)
	v_pk_add_f32 v[206:207], v[130:131], v[134:135]
	v_pk_add_f32 v[146:147], v[146:147], v[150:151]
	v_pk_add_f32 v[134:135], v[162:163], v[166:167]
	v_pk_add_f32 v[130:131], v[178:179], v[182:183]
	s_and_b64 vcc, exec, s[2:3]
	s_cbranch_vccz .LBB0_533
	v_pk_add_f32 v[42:43], v[132:133], v[136:137]
	v_pk_add_f32 v[44:45], v[206:207], v[142:143]
	v_pk_add_f32 v[42:43], v[42:43], v[144:145]
	v_pk_add_f32 v[58:59], v[44:45], v[138:139]
	v_pk_add_f32 v[60:61], v[42:43], v[140:141]
	v_pk_add_f32 v[42:43], v[148:149], v[152:153]
	v_pk_add_f32 v[44:45], v[146:147], v[158:159]
	v_pk_add_f32 v[42:43], v[42:43], v[160:161]
	v_pk_add_f32 v[46:47], v[134:135], v[174:175]
	v_pk_add_f32 v[64:65], v[42:43], v[156:157]
	v_pk_add_f32 v[42:43], v[164:165], v[168:169]
	v_pk_add_f32 v[62:63], v[44:45], v[154:155]
	v_pk_add_f32 v[42:43], v[42:43], v[176:177]
	s_waitcnt vmcnt(1)
	v_pk_add_f32 v[150:151], v[130:131], v[190:191]
	v_pk_add_f32 v[44:45], v[42:43], v[172:173]
	v_pk_add_f32 v[42:43], v[46:47], v[170:171]
	v_pk_add_f32 v[46:47], v[180:181], v[184:185]
	s_nop 0
	v_pk_add_f32 v[46:47], v[46:47], v[192:193]
	s_waitcnt vmcnt(0)
	v_pk_add_f32 v[48:49], v[46:47], v[188:189]
	v_pk_add_f32 v[46:47], v[150:151], v[186:187]

; #define LAS __attribute__((address_space(3)))
; __device__ __forceinline__ unsigned cvt_pk_bf16(float lo, float hi) { unsigned r; asm volatile("v_cvt_pk_bf16_f32 %0, %1, %2" : "=v"(r) : "v"(lo), "v"(hi)); return r; }
;     ...
;     asm volatile("s_waitcnt lgkmcnt(0)" ::: "memory");
;     const int c = lane & 7;
; #pragma unroll
;     for (int j = 0; j < 4; ++j) { const int n = (lane >> 3) + 8 * j; const LAS float* s = scr + (8 * c) * 33 + n;
;         u32x4 o; o.x = cvt_pk_bf16(s[0 * 33], s[1 * 33]); o.y = cvt_pk_bf16(s[2 * 33], s[3 * 33]); o.z = cvt_pk_bf16(s[4 * 33], s[5 * 33]); o.w = cvt_pk_bf16(s[6 * 33], s[7 * 33]);
;         const int nn = n0 + n; const int orow = mode ? ((nn >> 7) * 256 + (nn & 127) + (mode == 2 ? 128 : 0)) : nn;
;         *(u32x4*)(WT + (size_t)orow * K + k0 + 8 * c) = o; }
;     asm volatile("s_waitcnt lgkmcnt(0)" ::: "memory");
.LBB0_908:
	s_waitcnt lgkmcnt(0)
	ds_read2_b32 v[100:101], v44 offset1:33
	ds_read2_b32 v[102:103], v44 offset0:66 offset1:99
	ds_read2_b32 v[104:105], v44 offset0:132 offset1:165
	ds_read2_b32 v[106:107], v44 offset0:198 offset1:231
	ds_read2_b32 v[108:109], v44 offset0:8 offset1:41
	ds_read2_b32 v[110:111], v44 offset0:74 offset1:107
	ds_read2_b32 v[112:113], v44 offset0:140 offset1:173
	ds_read2_b32 v[114:115], v44 offset0:206 offset1:239
	ds_read2_b32 v[116:117], v44 offset0:16 offset1:49
	ds_read2_b32 v[118:119], v44 offset0:82 offset1:115
	ds_read2_b32 v[120:121], v44 offset0:148 offset1:181
	ds_read2_b32 v[122:123], v44 offset0:214 offset1:247
	ds_read2_b32 v[124:125], v44 offset0:24 offset1:57
	ds_read2_b32 v[126:127], v44 offset0:90 offset1:123
	ds_read2_b32 v[128:129], v44 offset0:156 offset1:189
	ds_read2_b32 v[130:131], v44 offset0:222 offset1:255
	s_waitcnt lgkmcnt(0)
	s_waitcnt lgkmcnt(0)
	v_cvt_pk_bf16_f32 v24, v100, v101
	s_waitcnt lgkmcnt(0)
	v_cvt_pk_bf16_f32 v25, v102, v103
	s_waitcnt lgkmcnt(0)
	v_cvt_pk_bf16_f32 v26, v104, v105
	s_waitcnt lgkmcnt(0)
	v_cvt_pk_bf16_f32 v27, v106, v107
	v_or_b32_e32 v30, s14, v3
	v_ashrrev_i32_e32 v31, 31, v30
	v_lshl_add_u64 v[28:29], s[16:17], 1, v[4:5]
	v_lshlrev_b64 v[30:31], 12, v[30:31]
	v_lshl_add_u64 v[30:31], v[28:29], 0, v[30:31]
	global_store_dwordx4 v[30:31], v[24:27], off
	s_waitcnt lgkmcnt(0)
	v_cvt_pk_bf16_f32 v24, v108, v109
	s_waitcnt lgkmcnt(0)
	v_cvt_pk_bf16_f32 v25, v110, v111
	s_waitcnt lgkmcnt(0)
	v_cvt_pk_bf16_f32 v26, v112, v113
	s_waitcnt lgkmcnt(0)
	v_cvt_pk_bf16_f32 v27, v114, v115
	v_or_b32_e32 v30, s14, v45
	v_ashrrev_i32_e32 v31, 31, v30
	v_lshlrev_b64 v[30:31], 12, v[30:31]
	v_lshl_add_u64 v[30:31], v[28:29], 0, v[30:31]
	global_store_dwordx4 v[30:31], v[24:27], off
	s_waitcnt lgkmcnt(0)
	v_cvt_pk_bf16_f32 v24, v116, v117
	s_waitcnt lgkmcnt(0)
	v_cvt_pk_bf16_f32 v25, v118, v119
	s_waitcnt lgkmcnt(0)
	v_cvt_pk_bf16_f32 v26, v120, v121
	s_waitcnt lgkmcnt(0)
	v_cvt_pk_bf16_f32 v27, v122, v123
	v_or_b32_e32 v30, s14, v46
	v_ashrrev_i32_e32 v31, 31, v30
	v_lshlrev_b64 v[30:31], 12, v[30:31]
	v_lshl_add_u64 v[30:31], v[28:29], 0, v[30:31]
	global_store_dwordx4 v[30:31], v[24:27], off
	s_waitcnt lgkmcnt(0)
	v_cvt_pk_bf16_f32 v24, v124, v125
	s_waitcnt lgkmcnt(0)
	v_cvt_pk_bf16_f32 v25, v126, v127
	s_waitcnt lgkmcnt(0)
	v_cvt_pk_bf16_f32 v26, v128, v129
	s_waitcnt lgkmcnt(0)
	v_cvt_pk_bf16_f32 v27, v130, v131
	v_or_b32_e32 v30, s14, v47
	v_ashrrev_i32_e32 v31, 31, v30
	v_lshlrev_b64 v[30:31], 12, v[30:31]
	v_lshl_add_u64 v[28:29], v[28:29], 0, v[30:31]
	global_store_dwordx4 v[28:29], v[24:27], off
	s_waitcnt lgkmcnt(0)

;     ...
;     for (int i = 0; i < 32; ++i) { const int kk = 2 * i + (lane >> 5); float v = __builtin_nontemporal_load(W + (size_t)(k0 + kk) * N + n0 + (lane & 31)); if (gain) v *= gain[k0 + kk]; scr[kk * 33 + (lane & 31)] = v; }
.LBB0_915:
	v_lshl_add_u64 v[164:165], v[38:39], 0, s[14:15]
	global_load_dword v100, v[164:165], off nt
	v_lshl_add_u64 v[164:165], v[36:37], 0, s[14:15]
	global_load_dword v101, v[164:165], off nt
	v_lshl_add_u64 v[164:165], v[34:35], 0, s[14:15]
	global_load_dword v102, v[164:165], off nt
	v_lshl_add_u64 v[164:165], v[32:33], 0, s[14:15]
	global_load_dword v103, v[164:165], off nt
	v_lshl_add_u64 v[164:165], v[30:31], 0, s[14:15]
	global_load_dword v104, v[164:165], off nt
	v_lshl_add_u64 v[164:165], v[28:29], 0, s[14:15]
	global_load_dword v105, v[164:165], off nt
	v_lshl_add_u64 v[164:165], v[26:27], 0, s[14:15]
	global_load_dword v106, v[164:165], off nt
	v_lshl_add_u64 v[164:165], v[24:25], 0, s[14:15]
	global_load_dword v107, v[164:165], off nt
	s_add_u32 s14, s14, 0x20000
	s_addc_u32 s15, s15, 0
	v_lshl_add_u64 v[164:165], v[38:39], 0, s[14:15]
	global_load_dword v108, v[164:165], off nt
	v_lshl_add_u64 v[164:165], v[36:37], 0, s[14:15]
	global_load_dword v109, v[164:165], off nt
	v_lshl_add_u64 v[164:165], v[34:35], 0, s[14:15]
	global_load_dword v110, v[164:165], off nt
	v_lshl_add_u64 v[164:165], v[32:33], 0, s[14:15]
	global_load_dword v111, v[164:165], off nt
	v_lshl_add_u64 v[164:165], v[30:31], 0, s[14:15]
	global_load_dword v112, v[164:165], off nt
	v_lshl_add_u64 v[164:165], v[28:29], 0, s[14:15]
	global_load_dword v113, v[164:165], off nt
	v_lshl_add_u64 v[164:165], v[26:27], 0, s[14:15]
	global_load_dword v114, v[164:165], off nt
	v_lshl_add_u64 v[164:165], v[24:25], 0, s[14:15]
	global_load_dword v115, v[164:165], off nt
	s_add_u32 s14, s14, 0x20000
	s_addc_u32 s15, s15, 0
	v_lshl_add_u64 v[164:165], v[38:39], 0, s[14:15]
	global_load_dword v116, v[164:165], off nt
	v_lshl_add_u64 v[164:165], v[36:37], 0, s[14:15]
	global_load_dword v117, v[164:165], off nt
	v_lshl_add_u64 v[164:165], v[34:35], 0, s[14:15]
	global_load_dword v118, v[164:165], off nt
	v_lshl_add_u64 v[164:165], v[32:33], 0, s[14:15]
	global_load_dword v119, v[164:165], off nt
	v_lshl_add_u64 v[164:165], v[30:31], 0, s[14:15]
	global_load_dword v120, v[164:165], off nt
	v_lshl_add_u64 v[164:165], v[28:29], 0, s[14:15]
	global_load_dword v121, v[164:165], off nt
	v_lshl_add_u64 v[164:165], v[26:27], 0, s[14:15]
	global_load_dword v122, v[164:165], off nt
	v_lshl_add_u64 v[164:165], v[24:25], 0, s[14:15]
	global_load_dword v123, v[164:165], off nt
	s_add_u32 s14, s14, 0x20000
	s_addc_u32 s15, s15, 0
	v_lshl_add_u64 v[164:165], v[38:39], 0, s[14:15]
	global_load_dword v124, v[164:165], off nt
	v_lshl_add_u64 v[164:165], v[36:37], 0, s[14:15]
	global_load_dword v125, v[164:165], off nt
	v_lshl_add_u64 v[164:165], v[34:35], 0, s[14:15]
	global_load_dword v126, v[164:165], off nt
	v_lshl_add_u64 v[164:165], v[32:33], 0, s[14:15]
	global_load_dword v127, v[164:165], off nt
	v_lshl_add_u64 v[164:165], v[30:31], 0, s[14:15]
	global_load_dword v128, v[164:165], off nt
	v_lshl_add_u64 v[164:165], v[28:29], 0, s[14:15]
	global_load_dword v129, v[164:165], off nt
	v_lshl_add_u64 v[164:165], v[26:27], 0, s[14:15]
	global_load_dword v130, v[164:165], off nt
	v_lshl_add_u64 v[164:165], v[24:25], 0, s[14:15]
	global_load_dword v131, v[164:165], off nt
	s_add_u32 s14, s14, 0x20000
	s_addc_u32 s15, s15, 0
	s_waitcnt vmcnt(24)
	ds_write_b32 v0, v100
	ds_write_b32 v0, v101 offset:264
	ds_write_b32 v0, v102 offset:528
	ds_write_b32 v0, v103 offset:792
	ds_write_b32 v0, v104 offset:1056
	ds_write_b32 v0, v105 offset:1320
	ds_write_b32 v0, v106 offset:1584
	ds_write_b32 v0, v107 offset:1848
	s_waitcnt vmcnt(16)
; #define LAS __attribute__((address_space(3)))
; __device__ __forceinline__ unsigned cvt_pk_bf16(float lo, float hi) { unsigned r; asm volatile("v_cvt_pk_bf16_f32 %0, %1, %2" : "=v"(r) : "v"(lo), "v"(hi)); return r; }
;     ...
;     for (int i = 0; i < 32; ++i) { const int kk = 2 * i + (lane >> 5); float v = __builtin_nontemporal_load(W + (size_t)(k0 + kk) * N + n0 + (lane & 31)); if (gain) v *= gain[k0 + kk]; scr[kk * 33 + (lane & 31)] = v; }
;     asm volatile("s_waitcnt lgkmcnt(0)" ::: "memory");
;     const int c = lane & 7;
; #pragma unroll
;     for (int j = 0; j < 4; ++j) { const int n = (lane >> 3) + 8 * j; const LAS float* s = scr + (8 * c) * 33 + n;
;         u32x4 o; o.x = cvt_pk_bf16(s[0 * 33], s[1 * 33]); o.y = cvt_pk_bf16(s[2 * 33], s[3 * 33]); o.z = cvt_pk_bf16(s[4 * 33], s[5 * 33]); o.w = cvt_pk_bf16(s[6 * 33], s[7 * 33]);
;         const int nn = n0 + n; const int orow = mode ? ((nn >> 7) * 256 + (nn & 127) + (mode == 2 ? 128 : 0)) : nn;
;         *(u32x4*)(WT + (size_t)orow * K + k0 + 8 * c) = o; }
	ds_write_b32 v0, v108 offset:2112
	ds_write_b32 v0, v109 offset:2376
	ds_write_b32 v0, v110 offset:2640
	ds_write_b32 v0, v111 offset:2904
	ds_write_b32 v0, v112 offset:3168
	ds_write_b32 v0, v113 offset:3432
	ds_write_b32 v0, v114 offset:3696
	ds_write_b32 v0, v115 offset:3960
	s_waitcnt vmcnt(8)
	ds_write_b32 v0, v116 offset:4224
	ds_write_b32 v0, v117 offset:4488
	ds_write_b32 v0, v118 offset:4752
	ds_write_b32 v0, v119 offset:5016
	ds_write_b32 v0, v120 offset:5280
	ds_write_b32 v0, v121 offset:5544
	ds_write_b32 v0, v122 offset:5808
	ds_write_b32 v0, v123 offset:6072
	s_waitcnt vmcnt(0)
	ds_write_b32 v0, v124 offset:6336
	ds_write_b32 v0, v125 offset:6600
	ds_write_b32 v0, v126 offset:6864
	ds_write_b32 v0, v127 offset:7128
	ds_write_b32 v0, v128 offset:7392
	ds_write_b32 v0, v129 offset:7656
	ds_write_b32 v0, v130 offset:7920
	ds_write_b32 v0, v131 offset:8184
	v_add_u32_e32 v0, 0x2100, v0
	s_and_b32 s11, s3, 0x7fffffc0
	s_add_i32 s8, s11, 0xffffb400
	s_lshl_b32 s11, s3, 5
	s_waitcnt lgkmcnt(0)
	ds_read2_b32 v[100:101], v44 offset1:33
	ds_read2_b32 v[102:103], v44 offset0:66 offset1:99
	ds_read2_b32 v[104:105], v44 offset0:132 offset1:165
	ds_read2_b32 v[106:107], v44 offset0:198 offset1:231
	ds_read2_b32 v[108:109], v44 offset0:8 offset1:41
	ds_read2_b32 v[110:111], v44 offset0:74 offset1:107
	ds_read2_b32 v[112:113], v44 offset0:140 offset1:173
	ds_read2_b32 v[114:115], v44 offset0:206 offset1:239
	ds_read2_b32 v[116:117], v44 offset0:16 offset1:49
	ds_read2_b32 v[118:119], v44 offset0:82 offset1:115
	ds_read2_b32 v[120:121], v44 offset0:148 offset1:181
	ds_read2_b32 v[122:123], v44 offset0:214 offset1:247
	ds_read2_b32 v[124:125], v44 offset0:24 offset1:57
	ds_read2_b32 v[126:127], v44 offset0:90 offset1:123
	ds_read2_b32 v[128:129], v44 offset0:156 offset1:189
	ds_read2_b32 v[130:131], v44 offset0:222 offset1:255
	s_waitcnt lgkmcnt(0)
	s_and_b32 s11, s11, 0x7e0
	s_waitcnt lgkmcnt(0)
	v_cvt_pk_bf16_f32 v26, v100, v101
	v_or_b32_e32 v0, s11, v3
	s_waitcnt lgkmcnt(0)
	v_cvt_pk_bf16_f32 v27, v102, v103
	v_mul_u32_u24_e32 v0, 0x1600, v0
	v_lshl_add_u64 v[24:25], s[8:9], 1, v[6:7]
	s_waitcnt lgkmcnt(0)
	v_cvt_pk_bf16_f32 v28, v104, v105
	v_lshlrev_b32_e32 v0, 1, v0
	s_waitcnt lgkmcnt(0)
	v_cvt_pk_bf16_f32 v29, v106, v107
	v_lshl_add_u64 v[30:31], v[24:25], 0, v[0:1]
	global_store_dwordx4 v[30:31], v[26:29], off
	v_or_b32_e32 v0, s11, v45
	s_waitcnt lgkmcnt(0)
	v_cvt_pk_bf16_f32 v26, v108, v109
	s_waitcnt lgkmcnt(0)
	v_cvt_pk_bf16_f32 v27, v110, v111
	v_mul_u32_u24_e32 v0, 0x1600, v0
	s_waitcnt lgkmcnt(0)
	v_cvt_pk_bf16_f32 v28, v112, v113
	v_lshlrev_b32_e32 v0, 1, v0
	s_waitcnt lgkmcnt(0)
	v_cvt_pk_bf16_f32 v29, v114, v115
	v_lshl_add_u64 v[30:31], v[24:25], 0, v[0:1]
	global_store_dwordx4 v[30:31], v[26:29], off
	v_or_b32_e32 v0, s11, v46
	s_waitcnt lgkmcnt(0)
	v_cvt_pk_bf16_f32 v26, v116, v117
	s_waitcnt lgkmcnt(0)
	v_cvt_pk_bf16_f32 v27, v118, v119
	v_mul_u32_u24_e32 v0, 0x1600, v0
	s_waitcnt lgkmcnt(0)
	v_cvt_pk_bf16_f32 v28, v120, v121
	v_lshlrev_b32_e32 v0, 1, v0
	s_waitcnt lgkmcnt(0)
	v_cvt_pk_bf16_f32 v29, v122, v123
	v_lshl_add_u64 v[30:31], v[24:25], 0, v[0:1]
	v_or_b32_e32 v0, s11, v47
	global_store_dwordx4 v[30:31], v[26:29], off
	v_mul_u32_u24_e32 v0, 0x1600, v0
	s_waitcnt lgkmcnt(0)
	v_cvt_pk_bf16_f32 v26, v124, v125
	v_lshlrev_b32_e32 v0, 1, v0
	s_waitcnt lgkmcnt(0)
	v_cvt_pk_bf16_f32 v27, v126, v127
	v_lshl_add_u64 v[24:25], v[24:25], 0, v[0:1]
	s_waitcnt lgkmcnt(0)
	v_cvt_pk_bf16_f32 v28, v128, v129
	s_waitcnt lgkmcnt(0)
	v_cvt_pk_bf16_f32 v29, v130, v131
	global_store_dwordx4 v[24:25], v[26:29], off
	s_waitcnt lgkmcnt(0)
	s_mov_b64 s[14:15], 0

;     ...
;     for (int i = 0; i < 32; ++i) { const int kk = 2 * i + (lane >> 5); float v = __builtin_nontemporal_load(W + (size_t)(k0 + kk) * N + n0 + (lane & 31)); if (gain) v *= gain[k0 + kk]; scr[kk * 33 + (lane & 31)] = v; }
.LBB0_919:
.LBB0_920:
	v_cndmask_b32_e64 v65, 0, 1, s[96:97]
	v_cmp_ne_u32_e64 s[42:43], 1, v65
	s_andn2_b64 vcc, exec, s[96:97]
	s_cbranch_vccnz .Lcvt_rows_7
	v_mbcnt_lo_u32_b32 v166, -1, 0
	v_mbcnt_hi_u32_b32 v166, -1, v166
	v_lshrrev_b32_e32 v169, 5, v166
	v_lshlrev_b32_e32 v169, 2, v169
	v_lshlrev_b32_e32 v166, 2, v166
	v_sub_u32_e32 v166, v166, v169
	v_mov_b32_e32 v167, 0
	v_lshl_add_u64 v[164:165], v[30:31], 0, v[166:167]
	global_load_dword v168, v[164:165], off
.Lcvt_rows_7:
	v_lshl_add_u64 v[164:165], v[26:27], 0, s[14:15]
	global_load_dword v100, v[164:165], off nt
	v_lshl_add_u64 v[164:165], v[38:39], 0, s[14:15]
	global_load_dword v101, v[164:165], off nt
	v_lshl_add_u64 v[164:165], v[42:43], 0, s[14:15]
	global_load_dword v102, v[164:165], off nt
	v_lshl_add_u64 v[164:165], v[40:41], 0, s[14:15]
	global_load_dword v103, v[164:165], off nt
	v_lshl_add_u64 v[164:165], v[36:37], 0, s[14:15]
	global_load_dword v104, v[164:165], off nt
	v_lshl_add_u64 v[164:165], v[32:33], 0, s[14:15]
	global_load_dword v105, v[164:165], off nt
	v_lshl_add_u64 v[164:165], v[28:29], 0, s[14:15]
	global_load_dword v106, v[164:165], off nt
	v_lshl_add_u64 v[164:165], v[24:25], 0, s[14:15]
	global_load_dword v107, v[164:165], off nt
	s_add_u32 s14, s14, 0x58000
	s_addc_u32 s15, s15, 0
	v_lshl_add_u64 v[164:165], v[26:27], 0, s[14:15]
	global_load_dword v108, v[164:165], off nt
	v_lshl_add_u64 v[164:165], v[38:39], 0, s[14:15]
	global_load_dword v109, v[164:165], off nt
	v_lshl_add_u64 v[164:165], v[42:43], 0, s[14:15]
	global_load_dword v110, v[164:165], off nt
	v_lshl_add_u64 v[164:165], v[40:41], 0, s[14:15]
	global_load_dword v111, v[164:165], off nt
	v_lshl_add_u64 v[164:165], v[36:37], 0, s[14:15]
	global_load_dword v112, v[164:165], off nt
	v_lshl_add_u64 v[164:165], v[32:33], 0, s[14:15]
	global_load_dword v113, v[164:165], off nt
	v_lshl_add_u64 v[164:165], v[28:29], 0, s[14:15]
	global_load_dword v114, v[164:165], off nt
	v_lshl_add_u64 v[164:165], v[24:25], 0, s[14:15]
	global_load_dword v115, v[164:165], off nt
	s_add_u32 s14, s14, 0x58000
	s_addc_u32 s15, s15, 0
	v_lshl_add_u64 v[164:165], v[26:27], 0, s[14:15]
	global_load_dword v116, v[164:165], off nt
	v_lshl_add_u64 v[164:165], v[38:39], 0, s[14:15]
	global_load_dword v117, v[164:165], off nt
	v_lshl_add_u64 v[164:165], v[42:43], 0, s[14:15]
	global_load_dword v118, v[164:165], off nt
	v_lshl_add_u64 v[164:165], v[40:41], 0, s[14:15]
	global_load_dword v119, v[164:165], off nt
	v_lshl_add_u64 v[164:165], v[36:37], 0, s[14:15]
	global_load_dword v120, v[164:165], off nt
	v_lshl_add_u64 v[164:165], v[32:33], 0, s[14:15]
	global_load_dword v121, v[164:165], off nt
	v_lshl_add_u64 v[164:165], v[28:29], 0, s[14:15]
	global_load_dword v122, v[164:165], off nt
	v_lshl_add_u64 v[164:165], v[24:25], 0, s[14:15]
	global_load_dword v123, v[164:165], off nt
	s_add_u32 s14, s14, 0x58000
	s_addc_u32 s15, s15, 0
	v_lshl_add_u64 v[164:165], v[26:27], 0, s[14:15]
	global_load_dword v124, v[164:165], off nt
	v_lshl_add_u64 v[164:165], v[38:39], 0, s[14:15]
	global_load_dword v125, v[164:165], off nt
	v_lshl_add_u64 v[164:165], v[42:43], 0, s[14:15]
	global_load_dword v126, v[164:165], off nt
	v_lshl_add_u64 v[164:165], v[40:41], 0, s[14:15]
	global_load_dword v127, v[164:165], off nt
	v_lshl_add_u64 v[164:165], v[36:37], 0, s[14:15]
	global_load_dword v128, v[164:165], off nt
	v_lshl_add_u64 v[164:165], v[32:33], 0, s[14:15]
	global_load_dword v129, v[164:165], off nt
	v_lshl_add_u64 v[164:165], v[28:29], 0, s[14:15]
	global_load_dword v130, v[164:165], off nt
	v_lshl_add_u64 v[164:165], v[24:25], 0, s[14:15]
	global_load_dword v131, v[164:165], off nt
	s_add_u32 s14, s14, 0x58000
	s_addc_u32 s15, s15, 0
	v_cndmask_b32_e64 v65, 0, 1, s[96:97]
	v_cmp_ne_u32_e64 s[42:43], 1, v65
	s_andn2_b64 vcc, exec, s[96:97]
	s_cbranch_vccnz .Lcvt_put_7
	s_waitcnt vmcnt(32)
	ds_bpermute_b32 v132, v169, v168
	ds_bpermute_b32 v133, v169, v168 offset:8
	ds_bpermute_b32 v134, v169, v168 offset:16
	ds_bpermute_b32 v135, v169, v168 offset:24
	ds_bpermute_b32 v136, v169, v168 offset:32
	ds_bpermute_b32 v137, v169, v168 offset:40
	ds_bpermute_b32 v138, v169, v168 offset:48
	ds_bpermute_b32 v139, v169, v168 offset:56
	ds_bpermute_b32 v140, v169, v168 offset:64
	ds_bpermute_b32 v141, v169, v168 offset:72
	ds_bpermute_b32 v142, v169, v168 offset:80
	ds_bpermute_b32 v143, v169, v168 offset:88
	ds_bpermute_b32 v144, v169, v168 offset:96
	ds_bpermute_b32 v145, v169, v168 offset:104
	ds_bpermute_b32 v146, v169, v168 offset:112
	ds_bpermute_b32 v147, v169, v168 offset:120
	ds_bpermute_b32 v148, v169, v168 offset:128
	ds_bpermute_b32 v149, v169, v168 offset:136
	ds_bpermute_b32 v150, v169, v168 offset:144
	ds_bpermute_b32 v151, v169, v168 offset:152
	ds_bpermute_b32 v152, v169, v168 offset:160
	ds_bpermute_b32 v153, v169, v168 offset:168
	ds_bpermute_b32 v154, v169, v168 offset:176
	ds_bpermute_b32 v155, v169, v168 offset:184
	ds_bpermute_b32 v156, v169, v168 offset:192
	ds_bpermute_b32 v157, v169, v168 offset:200
	ds_bpermute_b32 v158, v169, v168 offset:208
	ds_bpermute_b32 v159, v169, v168 offset:216
	ds_bpermute_b32 v160, v169, v168 offset:224
	ds_bpermute_b32 v161, v169, v168 offset:232
	ds_bpermute_b32 v162, v169, v168 offset:240
	ds_bpermute_b32 v163, v169, v168 offset:248
	s_waitcnt vmcnt(0) lgkmcnt(0)
	v_mul_f32_e32 v100, v100, v132
	v_mul_f32_e32 v101, v101, v133
	v_mul_f32_e32 v102, v102, v134
	v_mul_f32_e32 v103, v103, v135
	v_mul_f32_e32 v104, v104, v136
	v_mul_f32_e32 v105, v105, v137
	v_mul_f32_e32 v106, v106, v138
	v_mul_f32_e32 v107, v107, v139
	v_mul_f32_e32 v108, v108, v140
	v_mul_f32_e32 v109, v109, v141
	v_mul_f32_e32 v110, v110, v142
	v_mul_f32_e32 v111, v111, v143
	v_mul_f32_e32 v112, v112, v144
	v_mul_f32_e32 v113, v113, v145
	v_mul_f32_e32 v114, v114, v146
	v_mul_f32_e32 v115, v115, v147
	v_mul_f32_e32 v116, v116, v148
	v_mul_f32_e32 v117, v117, v149
	v_mul_f32_e32 v118, v118, v150
	v_mul_f32_e32 v119, v119, v151
	v_mul_f32_e32 v120, v120, v152
	v_mul_f32_e32 v121, v121, v153
	v_mul_f32_e32 v122, v122, v154
	v_mul_f32_e32 v123, v123, v155
	v_mul_f32_e32 v124, v124, v156
	v_mul_f32_e32 v125, v125, v157
	v_mul_f32_e32 v126, v126, v158
	v_mul_f32_e32 v127, v127, v159
	v_mul_f32_e32 v128, v128, v160
	v_mul_f32_e32 v129, v129, v161
	v_mul_f32_e32 v130, v130, v162
	v_mul_f32_e32 v131, v131, v163
; #define LAS __attribute__((address_space(3)))
; __device__ __forceinline__ unsigned cvt_pk_bf16(float lo, float hi) { unsigned r; asm volatile("v_cvt_pk_bf16_f32 %0, %1, %2" : "=v"(r) : "v"(lo), "v"(hi)); return r; }
;     ...
;     for (int i = 0; i < 32; ++i) { const int kk = 2 * i + (lane >> 5); float v = __builtin_nontemporal_load(W + (size_t)(k0 + kk) * N + n0 + (lane & 31)); if (gain) v *= gain[k0 + kk]; scr[kk * 33 + (lane & 31)] = v; }
;     asm volatile("s_waitcnt lgkmcnt(0)" ::: "memory");
;     const int c = lane & 7;
; #pragma unroll
;     for (int j = 0; j < 4; ++j) { const int n = (lane >> 3) + 8 * j; const LAS float* s = scr + (8 * c) * 33 + n;
;         u32x4 o; o.x = cvt_pk_bf16(s[0 * 33], s[1 * 33]); o.y = cvt_pk_bf16(s[2 * 33], s[3 * 33]); o.z = cvt_pk_bf16(s[4 * 33], s[5 * 33]); o.w = cvt_pk_bf16(s[6 * 33], s[7 * 33]);
;         const int nn = n0 + n; const int orow = mode ? ((nn >> 7) * 256 + (nn & 127) + (mode == 2 ? 128 : 0)) : nn;
;         *(u32x4*)(WT + (size_t)orow * K + k0 + 8 * c) = o; }
.Lcvt_put_7:
	s_waitcnt vmcnt(0)
	ds_write_b32 v0, v100
	ds_write_b32 v0, v101 offset:264
	ds_write_b32 v0, v102 offset:528
	ds_write_b32 v0, v103 offset:792
	ds_write_b32 v0, v104 offset:1056
	ds_write_b32 v0, v105 offset:1320
	ds_write_b32 v0, v106 offset:1584
	ds_write_b32 v0, v107 offset:1848
	ds_write_b32 v0, v108 offset:2112
	ds_write_b32 v0, v109 offset:2376
	ds_write_b32 v0, v110 offset:2640
	ds_write_b32 v0, v111 offset:2904
	ds_write_b32 v0, v112 offset:3168
	ds_write_b32 v0, v113 offset:3432
	ds_write_b32 v0, v114 offset:3696
	ds_write_b32 v0, v115 offset:3960
	ds_write_b32 v0, v116 offset:4224
	ds_write_b32 v0, v117 offset:4488
	ds_write_b32 v0, v118 offset:4752
	ds_write_b32 v0, v119 offset:5016
	ds_write_b32 v0, v120 offset:5280
	ds_write_b32 v0, v121 offset:5544
	ds_write_b32 v0, v122 offset:5808
	ds_write_b32 v0, v123 offset:6072
	ds_write_b32 v0, v124 offset:6336
	ds_write_b32 v0, v125 offset:6600
	ds_write_b32 v0, v126 offset:6864
	ds_write_b32 v0, v127 offset:7128
	ds_write_b32 v0, v128 offset:7392
	ds_write_b32 v0, v129 offset:7656
	ds_write_b32 v0, v130 offset:7920
	ds_write_b32 v0, v131 offset:8184
	v_add_u32_e32 v0, 0x2100, v0
	v_lshl_add_u64 v[30:31], v[30:31], 0, 64
	v_lshl_add_u64 v[30:31], v[30:31], 0, 64
	v_lshl_add_u64 v[30:31], v[30:31], 0, 64
	v_lshl_add_u64 v[30:31], v[30:31], 0, 64
	v_lshl_add_u64 v[34:35], v[34:35], 0, 64
	v_lshl_add_u64 v[34:35], v[34:35], 0, 64
	v_lshl_add_u64 v[34:35], v[34:35], 0, 64
	v_lshl_add_u64 v[34:35], v[34:35], 0, 64
	s_branch .LBB0_936
.LBB0_936:
	s_waitcnt lgkmcnt(0)
	ds_read2_b32 v[100:101], v44 offset1:33
	ds_read2_b32 v[102:103], v44 offset0:66 offset1:99
	ds_read2_b32 v[104:105], v44 offset0:132 offset1:165
	ds_read2_b32 v[106:107], v44 offset0:198 offset1:231
	ds_read2_b32 v[108:109], v44 offset0:8 offset1:41
	ds_read2_b32 v[110:111], v44 offset0:74 offset1:107
	ds_read2_b32 v[112:113], v44 offset0:140 offset1:173
	ds_read2_b32 v[114:115], v44 offset0:206 offset1:239
	ds_read2_b32 v[116:117], v44 offset0:16 offset1:49
	ds_read2_b32 v[118:119], v44 offset0:82 offset1:115
	ds_read2_b32 v[120:121], v44 offset0:148 offset1:181
	ds_read2_b32 v[122:123], v44 offset0:214 offset1:247
	ds_read2_b32 v[124:125], v44 offset0:24 offset1:57
	ds_read2_b32 v[126:127], v44 offset0:90 offset1:123
	ds_read2_b32 v[128:129], v44 offset0:156 offset1:189
	ds_read2_b32 v[130:131], v44 offset0:222 offset1:255
	s_waitcnt lgkmcnt(0)
	s_lshl_b32 s14, s17, 6
	s_and_b32 s14, s14, 0x3f00
	s_and_b32 s11, s11, 0x60
	s_bitset1_b32 s14, 7
	s_and_b32 s15, 0xffff, s16
	s_waitcnt lgkmcnt(0)
	v_cvt_pk_bf16_f32 v26, v100, v101
	v_or_b32_e32 v0, s11, v3
	s_lshl_b32 s8, s15, 1
	s_waitcnt lgkmcnt(0)
	v_cvt_pk_bf16_f32 v27, v102, v103
	v_or_b32_e32 v0, s14, v0
	v_lshl_add_u64 v[24:25], v[8:9], 0, s[8:9]
	s_waitcnt lgkmcnt(0)
	v_cvt_pk_bf16_f32 v28, v104, v105
	v_lshlrev_b32_e32 v0, 12, v0
	s_waitcnt lgkmcnt(0)
	v_cvt_pk_bf16_f32 v29, v106, v107
	v_lshl_add_u64 v[30:31], v[24:25], 0, v[0:1]
	global_store_dwordx4 v[30:31], v[26:29], off
	v_or_b32_e32 v0, s11, v45
	s_waitcnt lgkmcnt(0)
	v_cvt_pk_bf16_f32 v26, v108, v109
	s_waitcnt lgkmcnt(0)
	v_cvt_pk_bf16_f32 v27, v110, v111
	v_or_b32_e32 v0, s14, v0
	s_waitcnt lgkmcnt(0)
	v_cvt_pk_bf16_f32 v28, v112, v113
	v_lshlrev_b32_e32 v0, 12, v0
	s_waitcnt lgkmcnt(0)
	v_cvt_pk_bf16_f32 v29, v114, v115
	v_lshl_add_u64 v[30:31], v[24:25], 0, v[0:1]
	global_store_dwordx4 v[30:31], v[26:29], off
	v_or_b32_e32 v0, s11, v46
	s_waitcnt lgkmcnt(0)
	v_cvt_pk_bf16_f32 v26, v116, v117
	s_waitcnt lgkmcnt(0)
	v_cvt_pk_bf16_f32 v27, v118, v119
	v_or_b32_e32 v0, s14, v0
	s_waitcnt lgkmcnt(0)
	v_cvt_pk_bf16_f32 v28, v120, v121
	v_lshlrev_b32_e32 v0, 12, v0
	s_waitcnt lgkmcnt(0)
	v_cvt_pk_bf16_f32 v29, v122, v123
	v_lshl_add_u64 v[30:31], v[24:25], 0, v[0:1]
	v_or_b32_e32 v0, s11, v47
	global_store_dwordx4 v[30:31], v[26:29], off
	v_or_b32_e32 v0, s14, v0
	s_waitcnt lgkmcnt(0)
	v_cvt_pk_bf16_f32 v26, v124, v125
	v_lshlrev_b32_e32 v0, 12, v0
	s_waitcnt lgkmcnt(0)
	v_cvt_pk_bf16_f32 v27, v126, v127
	v_lshl_add_u64 v[24:25], v[24:25], 0, v[0:1]
	s_waitcnt lgkmcnt(0)
	v_cvt_pk_bf16_f32 v28, v128, v129
	s_waitcnt lgkmcnt(0)
	v_cvt_pk_bf16_f32 v29, v130, v131
	global_store_dwordx4 v[24:25], v[26:29], off
	s_waitcnt lgkmcnt(0)

; #define LAS __attribute__((address_space(3)))
; __device__ __forceinline__ unsigned cvt_pk_bf16(float lo, float hi) { unsigned r; asm volatile("v_cvt_pk_bf16_f32 %0, %1, %2" : "=v"(r) : "v"(lo), "v"(hi)); return r; }
;     ...
;     const int c = lane & 7;
; #pragma unroll
;     for (int j = 0; j < 4; ++j) { const int n = (lane >> 3) + 8 * j; const LAS float* s = scr + (8 * c) * 33 + n;
;         u32x4 o; o.x = cvt_pk_bf16(s[0 * 33], s[1 * 33]); o.y = cvt_pk_bf16(s[2 * 33], s[3 * 33]); o.z = cvt_pk_bf16(s[4 * 33], s[5 * 33]); o.w = cvt_pk_bf16(s[6 * 33], s[7 * 33]);
;         const int nn = n0 + n; const int orow = mode ? ((nn >> 7) * 256 + (nn & 127) + (mode == 2 ? 128 : 0)) : nn;
;         *(u32x4*)(WT + (size_t)orow * K + k0 + 8 * c) = o; }
;     asm volatile("s_waitcnt lgkmcnt(0)" ::: "memory");
.LBB0_957:
	s_waitcnt lgkmcnt(0)
	ds_read2_b32 v[100:101], v44 offset1:33
	ds_read2_b32 v[102:103], v44 offset0:66 offset1:99
	ds_read2_b32 v[104:105], v44 offset0:132 offset1:165
	ds_read2_b32 v[106:107], v44 offset0:198 offset1:231
	ds_read2_b32 v[108:109], v44 offset0:8 offset1:41
	ds_read2_b32 v[110:111], v44 offset0:74 offset1:107
	ds_read2_b32 v[112:113], v44 offset0:140 offset1:173
	ds_read2_b32 v[114:115], v44 offset0:206 offset1:239
	ds_read2_b32 v[116:117], v44 offset0:16 offset1:49
	ds_read2_b32 v[118:119], v44 offset0:82 offset1:115
	ds_read2_b32 v[120:121], v44 offset0:148 offset1:181
	ds_read2_b32 v[122:123], v44 offset0:214 offset1:247
	ds_read2_b32 v[124:125], v44 offset0:24 offset1:57
	ds_read2_b32 v[126:127], v44 offset0:90 offset1:123
	ds_read2_b32 v[128:129], v44 offset0:156 offset1:189
	ds_read2_b32 v[130:131], v44 offset0:222 offset1:255
	s_waitcnt lgkmcnt(0)
	s_lshl_b32 s14, s17, 6
	s_and_b32 s11, s11, 0x60
	s_and_b32 s14, s14, 0x3f00
	s_and_b32 s15, 0xffff, s16
	s_waitcnt lgkmcnt(0)
	v_cvt_pk_bf16_f32 v26, v100, v101
	v_or_b32_e32 v0, s11, v3
	s_lshl_b32 s8, s15, 1
	s_waitcnt lgkmcnt(0)
	v_cvt_pk_bf16_f32 v27, v102, v103
	v_or_b32_e32 v0, s14, v0
	v_lshl_add_u64 v[24:25], v[8:9], 0, s[8:9]
	s_waitcnt lgkmcnt(0)
	v_cvt_pk_bf16_f32 v28, v104, v105
	v_lshlrev_b32_e32 v0, 12, v0
	s_waitcnt lgkmcnt(0)
	v_cvt_pk_bf16_f32 v29, v106, v107
	v_lshl_add_u64 v[30:31], v[24:25], 0, v[0:1]
	global_store_dwordx4 v[30:31], v[26:29], off
	v_or_b32_e32 v0, s11, v45
	s_waitcnt lgkmcnt(0)
	v_cvt_pk_bf16_f32 v26, v108, v109
	s_waitcnt lgkmcnt(0)
	v_cvt_pk_bf16_f32 v27, v110, v111
	v_or_b32_e32 v0, s14, v0
	s_waitcnt lgkmcnt(0)
	v_cvt_pk_bf16_f32 v28, v112, v113
	v_lshlrev_b32_e32 v0, 12, v0
	s_waitcnt lgkmcnt(0)
	v_cvt_pk_bf16_f32 v29, v114, v115
	v_lshl_add_u64 v[30:31], v[24:25], 0, v[0:1]
	global_store_dwordx4 v[30:31], v[26:29], off
	v_or_b32_e32 v0, s11, v46
	s_waitcnt lgkmcnt(0)
	v_cvt_pk_bf16_f32 v26, v116, v117
	s_waitcnt lgkmcnt(0)
	v_cvt_pk_bf16_f32 v27, v118, v119
	v_or_b32_e32 v0, s14, v0
	s_waitcnt lgkmcnt(0)
	v_cvt_pk_bf16_f32 v28, v120, v121
	v_lshlrev_b32_e32 v0, 12, v0
	s_waitcnt lgkmcnt(0)
	v_cvt_pk_bf16_f32 v29, v122, v123
	v_lshl_add_u64 v[30:31], v[24:25], 0, v[0:1]
	v_or_b32_e32 v0, s11, v47
	global_store_dwordx4 v[30:31], v[26:29], off
	v_or_b32_e32 v0, s14, v0
	s_waitcnt lgkmcnt(0)
	v_cvt_pk_bf16_f32 v26, v124, v125
	v_lshlrev_b32_e32 v0, 12, v0
	s_waitcnt lgkmcnt(0)
	v_cvt_pk_bf16_f32 v27, v126, v127
	v_lshl_add_u64 v[24:25], v[24:25], 0, v[0:1]
	s_waitcnt lgkmcnt(0)
	v_cvt_pk_bf16_f32 v28, v128, v129
	s_waitcnt lgkmcnt(0)
	v_cvt_pk_bf16_f32 v29, v130, v131
	global_store_dwordx4 v[24:25], v[26:29], off
	s_waitcnt lgkmcnt(0)

; #define LAS __attribute__((address_space(3)))
; __device__ __forceinline__ unsigned cvt_pk_bf16(float lo, float hi) { unsigned r; asm volatile("v_cvt_pk_bf16_f32 %0, %1, %2" : "=v"(r) : "v"(lo), "v"(hi)); return r; }
;     ...
;     for (int i = 0; i < 32; ++i) { const int kk = 2 * i + (lane >> 5); float v = __builtin_nontemporal_load(W + (size_t)(k0 + kk) * N + n0 + (lane & 31)); if (gain) v *= gain[k0 + kk]; scr[kk * 33 + (lane & 31)] = v; }
;     asm volatile("s_waitcnt lgkmcnt(0)" ::: "memory");
;     const int c = lane & 7;
; #pragma unroll
;     for (int j = 0; j < 4; ++j) { const int n = (lane >> 3) + 8 * j; const LAS float* s = scr + (8 * c) * 33 + n;
;         u32x4 o; o.x = cvt_pk_bf16(s[0 * 33], s[1 * 33]); o.y = cvt_pk_bf16(s[2 * 33], s[3 * 33]); o.z = cvt_pk_bf16(s[4 * 33], s[5 * 33]); o.w = cvt_pk_bf16(s[6 * 33], s[7 * 33]);
;         const int nn = n0 + n; const int orow = mode ? ((nn >> 7) * 256 + (nn & 127) + (mode == 2 ? 128 : 0)) : nn;
;         *(u32x4*)(WT + (size_t)orow * K + k0 + 8 * c) = o; }
.LBB0_961:
	v_lshl_add_u64 v[164:165], v[38:39], 0, s[14:15]
	global_load_dword v100, v[164:165], off nt
	v_lshl_add_u64 v[164:165], v[36:37], 0, s[14:15]
	global_load_dword v101, v[164:165], off nt
	v_lshl_add_u64 v[164:165], v[34:35], 0, s[14:15]
	global_load_dword v102, v[164:165], off nt
	v_lshl_add_u64 v[164:165], v[32:33], 0, s[14:15]
	global_load_dword v103, v[164:165], off nt
	v_lshl_add_u64 v[164:165], v[30:31], 0, s[14:15]
	global_load_dword v104, v[164:165], off nt
	v_lshl_add_u64 v[164:165], v[28:29], 0, s[14:15]
	global_load_dword v105, v[164:165], off nt
	v_lshl_add_u64 v[164:165], v[26:27], 0, s[14:15]
	global_load_dword v106, v[164:165], off nt
	v_lshl_add_u64 v[164:165], v[24:25], 0, s[14:15]
	global_load_dword v107, v[164:165], off nt
	s_add_u32 s14, s14, 0x20000
	s_addc_u32 s15, s15, 0
	v_lshl_add_u64 v[164:165], v[38:39], 0, s[14:15]
	global_load_dword v108, v[164:165], off nt
	v_lshl_add_u64 v[164:165], v[36:37], 0, s[14:15]
	global_load_dword v109, v[164:165], off nt
	v_lshl_add_u64 v[164:165], v[34:35], 0, s[14:15]
	global_load_dword v110, v[164:165], off nt
	v_lshl_add_u64 v[164:165], v[32:33], 0, s[14:15]
	global_load_dword v111, v[164:165], off nt
	v_lshl_add_u64 v[164:165], v[30:31], 0, s[14:15]
	global_load_dword v112, v[164:165], off nt
	v_lshl_add_u64 v[164:165], v[28:29], 0, s[14:15]
	global_load_dword v113, v[164:165], off nt
	v_lshl_add_u64 v[164:165], v[26:27], 0, s[14:15]
	global_load_dword v114, v[164:165], off nt
	v_lshl_add_u64 v[164:165], v[24:25], 0, s[14:15]
	global_load_dword v115, v[164:165], off nt
	s_add_u32 s14, s14, 0x20000
	s_addc_u32 s15, s15, 0
	v_lshl_add_u64 v[164:165], v[38:39], 0, s[14:15]
	global_load_dword v116, v[164:165], off nt
	v_lshl_add_u64 v[164:165], v[36:37], 0, s[14:15]
	global_load_dword v117, v[164:165], off nt
	v_lshl_add_u64 v[164:165], v[34:35], 0, s[14:15]
	global_load_dword v118, v[164:165], off nt
	v_lshl_add_u64 v[164:165], v[32:33], 0, s[14:15]
	global_load_dword v119, v[164:165], off nt
	v_lshl_add_u64 v[164:165], v[30:31], 0, s[14:15]
	global_load_dword v120, v[164:165], off nt
	v_lshl_add_u64 v[164:165], v[28:29], 0, s[14:15]
	global_load_dword v121, v[164:165], off nt
	v_lshl_add_u64 v[164:165], v[26:27], 0, s[14:15]
	global_load_dword v122, v[164:165], off nt
	v_lshl_add_u64 v[164:165], v[24:25], 0, s[14:15]
	global_load_dword v123, v[164:165], off nt
	s_add_u32 s14, s14, 0x20000
	s_addc_u32 s15, s15, 0
	v_lshl_add_u64 v[164:165], v[38:39], 0, s[14:15]
	global_load_dword v124, v[164:165], off nt
	v_lshl_add_u64 v[164:165], v[36:37], 0, s[14:15]
	global_load_dword v125, v[164:165], off nt
	v_lshl_add_u64 v[164:165], v[34:35], 0, s[14:15]
	global_load_dword v126, v[164:165], off nt
	v_lshl_add_u64 v[164:165], v[32:33], 0, s[14:15]
	global_load_dword v127, v[164:165], off nt
	v_lshl_add_u64 v[164:165], v[30:31], 0, s[14:15]
	global_load_dword v128, v[164:165], off nt
	v_lshl_add_u64 v[164:165], v[28:29], 0, s[14:15]
	global_load_dword v129, v[164:165], off nt
	v_lshl_add_u64 v[164:165], v[26:27], 0, s[14:15]
	global_load_dword v130, v[164:165], off nt
	v_lshl_add_u64 v[164:165], v[24:25], 0, s[14:15]
	global_load_dword v131, v[164:165], off nt
	s_add_u32 s14, s14, 0x20000
	s_addc_u32 s15, s15, 0
	s_waitcnt vmcnt(24)
	ds_write_b32 v0, v100
	ds_write_b32 v0, v101 offset:264
	ds_write_b32 v0, v102 offset:528
	ds_write_b32 v0, v103 offset:792
	ds_write_b32 v0, v104 offset:1056
	ds_write_b32 v0, v105 offset:1320
	ds_write_b32 v0, v106 offset:1584
	ds_write_b32 v0, v107 offset:1848
	s_waitcnt vmcnt(16)
	ds_write_b32 v0, v108 offset:2112
	ds_write_b32 v0, v109 offset:2376
	ds_write_b32 v0, v110 offset:2640
	ds_write_b32 v0, v111 offset:2904
	ds_write_b32 v0, v112 offset:3168
	ds_write_b32 v0, v113 offset:3432
	ds_write_b32 v0, v114 offset:3696
	ds_write_b32 v0, v115 offset:3960
	s_waitcnt vmcnt(8)
	ds_write_b32 v0, v116 offset:4224
	ds_write_b32 v0, v117 offset:4488
	ds_write_b32 v0, v118 offset:4752
	ds_write_b32 v0, v119 offset:5016
	ds_write_b32 v0, v120 offset:5280
	ds_write_b32 v0, v121 offset:5544
	ds_write_b32 v0, v122 offset:5808
	ds_write_b32 v0, v123 offset:6072
	s_waitcnt vmcnt(0)
	ds_write_b32 v0, v124 offset:6336
	ds_write_b32 v0, v125 offset:6600
	ds_write_b32 v0, v126 offset:6864
	ds_write_b32 v0, v127 offset:7128
	ds_write_b32 v0, v128 offset:7392
	ds_write_b32 v0, v129 offset:7656
	ds_write_b32 v0, v130 offset:7920
	ds_write_b32 v0, v131 offset:8184
	v_add_u32_e32 v0, 0x2100, v0
	s_add_i32 s10, s3, 0xe800
	s_waitcnt lgkmcnt(0)
	ds_read2_b32 v[100:101], v44 offset1:33
	ds_read2_b32 v[102:103], v44 offset0:66 offset1:99
	ds_read2_b32 v[104:105], v44 offset0:132 offset1:165
	ds_read2_b32 v[106:107], v44 offset0:198 offset1:231
	ds_read2_b32 v[108:109], v44 offset0:8 offset1:41
	ds_read2_b32 v[110:111], v44 offset0:74 offset1:107
	ds_read2_b32 v[112:113], v44 offset0:140 offset1:173
	ds_read2_b32 v[114:115], v44 offset0:206 offset1:239
	ds_read2_b32 v[116:117], v44 offset0:16 offset1:49
	ds_read2_b32 v[118:119], v44 offset0:82 offset1:115
	ds_read2_b32 v[120:121], v44 offset0:148 offset1:181
	ds_read2_b32 v[122:123], v44 offset0:214 offset1:247
	ds_read2_b32 v[124:125], v44 offset0:24 offset1:57
	ds_read2_b32 v[126:127], v44 offset0:90 offset1:123
	ds_read2_b32 v[128:129], v44 offset0:156 offset1:189
	ds_read2_b32 v[130:131], v44 offset0:222 offset1:255
	s_waitcnt lgkmcnt(0)
	s_and_b32 s11, s10, 0xffc0
	s_lshl_b32 s10, s3, 5
	s_and_b32 s10, s10, 0x7e0
	s_waitcnt lgkmcnt(0)
	v_cvt_pk_bf16_f32 v24, v100, v101
	s_lshl_b32 s8, s11, 1
	s_waitcnt lgkmcnt(0)
	v_cvt_pk_bf16_f32 v25, v102, v103
	v_or_b32_e32 v0, s10, v3
	v_lshl_add_u64 v[28:29], v[10:11], 0, s[8:9]
	s_waitcnt lgkmcnt(0)
	v_cvt_pk_bf16_f32 v26, v104, v105
	v_lshlrev_b32_e32 v0, 12, v0
	s_waitcnt lgkmcnt(0)
	v_cvt_pk_bf16_f32 v27, v106, v107
	v_lshl_add_u64 v[30:31], v[28:29], 0, v[0:1]
	global_store_dwordx4 v[30:31], v[24:27], off
	v_or_b32_e32 v0, s10, v45
	s_waitcnt lgkmcnt(0)
	v_cvt_pk_bf16_f32 v24, v108, v109
	s_waitcnt lgkmcnt(0)
	v_cvt_pk_bf16_f32 v25, v110, v111
	s_waitcnt lgkmcnt(0)
	v_cvt_pk_bf16_f32 v26, v112, v113
	v_lshlrev_b32_e32 v0, 12, v0
	s_waitcnt lgkmcnt(0)
	v_cvt_pk_bf16_f32 v27, v114, v115
	v_lshl_add_u64 v[30:31], v[28:29], 0, v[0:1]
	global_store_dwordx4 v[30:31], v[24:27], off
	v_or_b32_e32 v0, s10, v46
	s_waitcnt lgkmcnt(0)
	v_cvt_pk_bf16_f32 v24, v116, v117
	s_waitcnt lgkmcnt(0)
	v_cvt_pk_bf16_f32 v25, v118, v119
	s_waitcnt lgkmcnt(0)
	v_cvt_pk_bf16_f32 v26, v120, v121
	v_lshlrev_b32_e32 v0, 12, v0
	s_waitcnt lgkmcnt(0)
	v_cvt_pk_bf16_f32 v27, v122, v123
	v_lshl_add_u64 v[30:31], v[28:29], 0, v[0:1]
	global_store_dwordx4 v[30:31], v[24:27], off
	v_or_b32_e32 v0, s10, v47
	s_waitcnt lgkmcnt(0)
	v_cvt_pk_bf16_f32 v24, v124, v125
	v_lshlrev_b32_e32 v0, 12, v0
	s_waitcnt lgkmcnt(0)
	v_cvt_pk_bf16_f32 v25, v126, v127
	v_lshl_add_u64 v[28:29], v[28:29], 0, v[0:1]
	s_waitcnt lgkmcnt(0)
	v_cvt_pk_bf16_f32 v26, v128, v129
	s_waitcnt lgkmcnt(0)
	v_cvt_pk_bf16_f32 v27, v130, v131
	global_store_dwordx4 v[28:29], v[24:27], off
	s_waitcnt lgkmcnt(0)

;     ...
;     for (int i = 0; i < 32; ++i) { const int kk = 2 * i + (lane >> 5); float v = __builtin_nontemporal_load(W + (size_t)(k0 + kk) * N + n0 + (lane & 31)); if (gain) v *= gain[k0 + kk]; scr[kk * 33 + (lane & 31)] = v; }
.LBB0_966:
.LBB0_967:
	s_and_b64 vcc, exec, s[52:53]
	s_cbranch_vccnz .Lcvt_rows_9
	v_mbcnt_lo_u32_b32 v166, -1, 0
	v_mbcnt_hi_u32_b32 v166, -1, v166
	v_lshrrev_b32_e32 v169, 5, v166
	v_lshlrev_b32_e32 v169, 2, v169
	v_lshlrev_b32_e32 v166, 2, v166
	v_sub_u32_e32 v166, v166, v169
	v_mov_b32_e32 v167, 0
	v_lshl_add_u64 v[164:165], v[30:31], 0, v[166:167]
	global_load_dword v168, v[164:165], off
.Lcvt_rows_9:
	v_lshl_add_u64 v[164:165], v[26:27], 0, s[18:19]
	global_load_dword v100, v[164:165], off nt
	v_lshl_add_u64 v[164:165], v[34:35], 0, s[18:19]
	global_load_dword v101, v[164:165], off nt
	v_lshl_add_u64 v[164:165], v[42:43], 0, s[18:19]
	global_load_dword v102, v[164:165], off nt
	v_lshl_add_u64 v[164:165], v[40:41], 0, s[18:19]
	global_load_dword v103, v[164:165], off nt
	v_lshl_add_u64 v[164:165], v[36:37], 0, s[18:19]
	global_load_dword v104, v[164:165], off nt
	v_lshl_add_u64 v[164:165], v[32:33], 0, s[18:19]
	global_load_dword v105, v[164:165], off nt
	v_lshl_add_u64 v[164:165], v[28:29], 0, s[18:19]
	global_load_dword v106, v[164:165], off nt
	v_lshl_add_u64 v[164:165], v[24:25], 0, s[18:19]
	global_load_dword v107, v[164:165], off nt
	s_add_u32 s18, s18, 0x60000
	s_addc_u32 s19, s19, 0
	v_lshl_add_u64 v[164:165], v[26:27], 0, s[18:19]
	global_load_dword v108, v[164:165], off nt
	v_lshl_add_u64 v[164:165], v[34:35], 0, s[18:19]
	global_load_dword v109, v[164:165], off nt
	v_lshl_add_u64 v[164:165], v[42:43], 0, s[18:19]
	global_load_dword v110, v[164:165], off nt
	v_lshl_add_u64 v[164:165], v[40:41], 0, s[18:19]
	global_load_dword v111, v[164:165], off nt
	v_lshl_add_u64 v[164:165], v[36:37], 0, s[18:19]
	global_load_dword v112, v[164:165], off nt
	v_lshl_add_u64 v[164:165], v[32:33], 0, s[18:19]
	global_load_dword v113, v[164:165], off nt
	v_lshl_add_u64 v[164:165], v[28:29], 0, s[18:19]
	global_load_dword v114, v[164:165], off nt
	v_lshl_add_u64 v[164:165], v[24:25], 0, s[18:19]
	global_load_dword v115, v[164:165], off nt
	s_add_u32 s18, s18, 0x60000
	s_addc_u32 s19, s19, 0
	v_lshl_add_u64 v[164:165], v[26:27], 0, s[18:19]
	global_load_dword v116, v[164:165], off nt
	v_lshl_add_u64 v[164:165], v[34:35], 0, s[18:19]
	global_load_dword v117, v[164:165], off nt
	v_lshl_add_u64 v[164:165], v[42:43], 0, s[18:19]
	global_load_dword v118, v[164:165], off nt
	v_lshl_add_u64 v[164:165], v[40:41], 0, s[18:19]
	global_load_dword v119, v[164:165], off nt
	v_lshl_add_u64 v[164:165], v[36:37], 0, s[18:19]
	global_load_dword v120, v[164:165], off nt
	v_lshl_add_u64 v[164:165], v[32:33], 0, s[18:19]
	global_load_dword v121, v[164:165], off nt
	v_lshl_add_u64 v[164:165], v[28:29], 0, s[18:19]
	global_load_dword v122, v[164:165], off nt
	v_lshl_add_u64 v[164:165], v[24:25], 0, s[18:19]
	global_load_dword v123, v[164:165], off nt
	s_add_u32 s18, s18, 0x60000
	s_addc_u32 s19, s19, 0
	v_lshl_add_u64 v[164:165], v[26:27], 0, s[18:19]
	global_load_dword v124, v[164:165], off nt
	v_lshl_add_u64 v[164:165], v[34:35], 0, s[18:19]
	global_load_dword v125, v[164:165], off nt
	v_lshl_add_u64 v[164:165], v[42:43], 0, s[18:19]
	global_load_dword v126, v[164:165], off nt
	v_lshl_add_u64 v[164:165], v[40:41], 0, s[18:19]
	global_load_dword v127, v[164:165], off nt
	v_lshl_add_u64 v[164:165], v[36:37], 0, s[18:19]
	global_load_dword v128, v[164:165], off nt
	v_lshl_add_u64 v[164:165], v[32:33], 0, s[18:19]
	global_load_dword v129, v[164:165], off nt
	v_lshl_add_u64 v[164:165], v[28:29], 0, s[18:19]
	global_load_dword v130, v[164:165], off nt
	v_lshl_add_u64 v[164:165], v[24:25], 0, s[18:19]
	global_load_dword v131, v[164:165], off nt
	s_add_u32 s18, s18, 0x60000
	s_addc_u32 s19, s19, 0
	s_and_b64 vcc, exec, s[52:53]
	s_cbranch_vccnz .Lcvt_put_9
	s_waitcnt vmcnt(32)
	ds_bpermute_b32 v132, v169, v168
	ds_bpermute_b32 v133, v169, v168 offset:8
	ds_bpermute_b32 v134, v169, v168 offset:16
	ds_bpermute_b32 v135, v169, v168 offset:24
	ds_bpermute_b32 v136, v169, v168 offset:32
	ds_bpermute_b32 v137, v169, v168 offset:40
	ds_bpermute_b32 v138, v169, v168 offset:48
	ds_bpermute_b32 v139, v169, v168 offset:56
	ds_bpermute_b32 v140, v169, v168 offset:64
	ds_bpermute_b32 v141, v169, v168 offset:72
	ds_bpermute_b32 v142, v169, v168 offset:80
	ds_bpermute_b32 v143, v169, v168 offset:88
	ds_bpermute_b32 v144, v169, v168 offset:96
	ds_bpermute_b32 v145, v169, v168 offset:104
	ds_bpermute_b32 v146, v169, v168 offset:112
	ds_bpermute_b32 v147, v169, v168 offset:120
	ds_bpermute_b32 v148, v169, v168 offset:128
	ds_bpermute_b32 v149, v169, v168 offset:136
	ds_bpermute_b32 v150, v169, v168 offset:144
	ds_bpermute_b32 v151, v169, v168 offset:152
	ds_bpermute_b32 v152, v169, v168 offset:160
	ds_bpermute_b32 v153, v169, v168 offset:168
	ds_bpermute_b32 v154, v169, v168 offset:176
	ds_bpermute_b32 v155, v169, v168 offset:184
	ds_bpermute_b32 v156, v169, v168 offset:192
	ds_bpermute_b32 v157, v169, v168 offset:200
	ds_bpermute_b32 v158, v169, v168 offset:208
	ds_bpermute_b32 v159, v169, v168 offset:216
	ds_bpermute_b32 v160, v169, v168 offset:224
	ds_bpermute_b32 v161, v169, v168 offset:232
	ds_bpermute_b32 v162, v169, v168 offset:240
	ds_bpermute_b32 v163, v169, v168 offset:248
	s_waitcnt vmcnt(0) lgkmcnt(0)
	v_mul_f32_e32 v100, v100, v132
	v_mul_f32_e32 v101, v101, v133
	v_mul_f32_e32 v102, v102, v134
	v_mul_f32_e32 v103, v103, v135
	v_mul_f32_e32 v104, v104, v136
	v_mul_f32_e32 v105, v105, v137
	v_mul_f32_e32 v106, v106, v138
	v_mul_f32_e32 v107, v107, v139
	v_mul_f32_e32 v108, v108, v140
	v_mul_f32_e32 v109, v109, v141
	v_mul_f32_e32 v110, v110, v142
	v_mul_f32_e32 v111, v111, v143
	v_mul_f32_e32 v112, v112, v144
	v_mul_f32_e32 v113, v113, v145
	v_mul_f32_e32 v114, v114, v146
	v_mul_f32_e32 v115, v115, v147
	v_mul_f32_e32 v116, v116, v148
	v_mul_f32_e32 v117, v117, v149
	v_mul_f32_e32 v118, v118, v150
	v_mul_f32_e32 v119, v119, v151
	v_mul_f32_e32 v120, v120, v152
	v_mul_f32_e32 v121, v121, v153
	v_mul_f32_e32 v122, v122, v154
	v_mul_f32_e32 v123, v123, v155
	v_mul_f32_e32 v124, v124, v156
	v_mul_f32_e32 v125, v125, v157
	v_mul_f32_e32 v126, v126, v158
	v_mul_f32_e32 v127, v127, v159
	v_mul_f32_e32 v128, v128, v160
	v_mul_f32_e32 v129, v129, v161
	v_mul_f32_e32 v130, v130, v162
	v_mul_f32_e32 v131, v131, v163
;     ...
;     for (int i = 0; i < 32; ++i) { const int kk = 2 * i + (lane >> 5); float v = __builtin_nontemporal_load(W + (size_t)(k0 + kk) * N + n0 + (lane & 31)); if (gain) v *= gain[k0 + kk]; scr[kk * 33 + (lane & 31)] = v; }
.Lcvt_put_9:
	s_waitcnt vmcnt(0)
	ds_write_b32 v0, v100
	ds_write_b32 v0, v101 offset:264
	ds_write_b32 v0, v102 offset:528
	ds_write_b32 v0, v103 offset:792
	ds_write_b32 v0, v104 offset:1056
	ds_write_b32 v0, v105 offset:1320
	ds_write_b32 v0, v106 offset:1584
	ds_write_b32 v0, v107 offset:1848
	ds_write_b32 v0, v108 offset:2112
	ds_write_b32 v0, v109 offset:2376
	ds_write_b32 v0, v110 offset:2640
	ds_write_b32 v0, v111 offset:2904
	ds_write_b32 v0, v112 offset:3168
	ds_write_b32 v0, v113 offset:3432
	ds_write_b32 v0, v114 offset:3696
	ds_write_b32 v0, v115 offset:3960
	ds_write_b32 v0, v116 offset:4224
	ds_write_b32 v0, v117 offset:4488
	ds_write_b32 v0, v118 offset:4752
	ds_write_b32 v0, v119 offset:5016
	ds_write_b32 v0, v120 offset:5280
	ds_write_b32 v0, v121 offset:5544
	ds_write_b32 v0, v122 offset:5808
	ds_write_b32 v0, v123 offset:6072
	ds_write_b32 v0, v124 offset:6336
	ds_write_b32 v0, v125 offset:6600
	ds_write_b32 v0, v126 offset:6864
	ds_write_b32 v0, v127 offset:7128
	ds_write_b32 v0, v128 offset:7392
	ds_write_b32 v0, v129 offset:7656
	ds_write_b32 v0, v130 offset:7920
	ds_write_b32 v0, v131 offset:8184
	v_add_u32_e32 v0, 0x2100, v0
	v_lshl_add_u64 v[30:31], v[30:31], 0, 64
	v_lshl_add_u64 v[30:31], v[30:31], 0, 64
	v_lshl_add_u64 v[30:31], v[30:31], 0, 64
	v_lshl_add_u64 v[30:31], v[30:31], 0, 64
	v_lshl_add_u64 v[38:39], v[38:39], 0, 64
	v_lshl_add_u64 v[38:39], v[38:39], 0, 64
	v_lshl_add_u64 v[38:39], v[38:39], 0, 64
	v_lshl_add_u64 v[38:39], v[38:39], 0, 64
	s_branch .LBB0_908

; __device__ __forceinline__ float bf_lo(unsigned w) { return __uint_as_float(w << 16); }
; __device__ __forceinline__ float bf_hi(unsigned w) { return __uint_as_float(w & 0xffff0000u); }
; __global__ void __launch_bounds__(512, 2) hymba_fwd(Args a) {
;     ...
;         for (int orow = gw; orow < NB * SEQ; orow += NGW) {
;             const int bb = orow / SEQ, s = orow % SEQ; const int row = bb * LTOK + CH + s;
;             const float rstd = row_rstd(ssqA, row);
; #pragma unroll
;             for (int j = 0; j < 8; ++j) {
;                 const u32x2 hi = *((const u32x2*)(hb + (size_t)row * DM) + 64 * j + lane);
;                 const f32x4 v = (f32x4){bf_lo(hi.x), bf_hi(hi.x), bf_lo(hi.y), bf_hi(hi.y)};
;                 *((f32x4*)(a.out + (size_t)orow * DM) + 64 * j + lane) = v * rstd * wv[j]; }
;         }
.LBB0_1138:
	s_ashr_i32 s1, s0, 31
	s_lshr_b32 s3, s1, 20
	s_add_i32 s3, s0, s3
	s_ashr_i32 s3, s3, 12
	s_lshl_b32 s3, s3, 7
	s_add_i32 s3, s0, s3
	s_add_i32 s4, s3, 0x80
	s_ashr_i32 s5, s4, 31
	s_lshl_b64 s[6:7], s[4:5], 7
	s_add_u32 s6, s70, s6
	s_addc_u32 s7, s71, s7
	global_load_dwordx4 v[38:41], v33, s[6:7]
	global_load_dwordx4 v[42:45], v33, s[6:7] offset:16
	global_load_dwordx4 v[46:49], v33, s[6:7] offset:32
	global_load_dwordx4 v[50:53], v33, s[6:7] offset:48
	global_load_dwordx4 v[54:57], v33, s[6:7] offset:64
	global_load_dwordx4 v[58:61], v33, s[6:7] offset:80
	global_load_dwordx4 v[62:65], v33, s[6:7] offset:96
	global_load_dwordx4 v[66:69], v33, s[6:7] offset:112
	s_lshl_b64 s[4:5], s[4:5], 12
	v_lshl_add_u64 v[70:71], v[34:35], 0, s[4:5]
	global_load_dwordx2 v[72:73], v[70:71], off
	global_load_dwordx2 v[82:83], v[70:71], off offset:512
	global_load_dwordx2 v[84:85], v[70:71], off offset:1024
	global_load_dwordx2 v[86:87], v[70:71], off offset:1536
	global_load_dwordx2 v[88:89], v[70:71], off offset:2048
	global_load_dwordx2 v[90:91], v[70:71], off offset:2560
	global_load_dwordx2 v[92:93], v[70:71], off offset:3072
	global_load_dwordx2 v[94:95], v[70:71], off offset:3584
	s_lshl_b64 s[4:5], s[0:1], 13
	v_lshl_add_u64 v[74:75], v[36:37], 0, s[4:5]
	s_add_i32 s0, s0, s8
	s_cmpk_gt_i32 s0, 0x3fff
	s_waitcnt vmcnt(15)
	v_mov_b32_e32 v76, v38
	s_waitcnt vmcnt(14)
	v_mov_b32_e32 v77, v42
	v_mov_b32_e32 v42, v39
	v_mov_b32_e32 v38, v40
	v_mov_b32_e32 v39, v44
	v_mov_b32_e32 v44, v41
	s_waitcnt vmcnt(13)
	v_mov_b32_e32 v40, v47
	v_mov_b32_e32 v41, v48
	v_mov_b32_e32 v47, v49
	v_pk_add_f32 v[42:43], v[76:77], v[42:43]
	v_pk_add_f32 v[38:39], v[38:39], v[44:45]
	v_pk_add_f32 v[40:41], v[40:41], v[46:47]
	v_pk_add_f32 v[38:39], v[42:43], v[38:39]
	v_pk_add_f32 v[40:41], v[40:41], v[40:41] op_sel:[0,1] op_sel_hi:[1,0]
	v_add_f32_e32 v38, 0, v38
	s_waitcnt vmcnt(12)
	v_add_f32_e32 v48, v50, v51
	v_add_f32_e32 v50, v52, v53
	s_waitcnt vmcnt(11)
	v_mov_b32_e32 v53, v54
	v_mov_b32_e32 v49, v56
	v_mov_b32_e32 v51, v57
	v_mov_b32_e32 v41, v55
	v_add_f32_e32 v52, v38, v39
	s_waitcnt vmcnt(10)
	v_mov_b32_e32 v56, v59
	v_mov_b32_e32 v57, v60
	v_mov_b32_e32 v59, v61
	v_pk_add_f32 v[44:45], v[48:49], v[50:51]
	v_pk_add_f32 v[38:39], v[52:53], v[40:41]
	v_pk_add_f32 v[46:47], v[56:57], v[58:59]
	v_pk_add_f32 v[38:39], v[38:39], v[44:45]
	v_pk_add_f32 v[42:43], v[46:47], v[46:47] op_sel:[0,1] op_sel_hi:[1,0]
	v_pk_add_f32 v[38:39], v[38:39], v[38:39] op_sel:[0,1] op_sel_hi:[1,0]
	s_waitcnt vmcnt(9)
	v_add_f32_e32 v60, v62, v63
	v_add_f32_e32 v62, v64, v65
	s_waitcnt vmcnt(8)
	v_mov_b32_e32 v61, v68
	v_mov_b32_e32 v63, v69
	v_mov_b32_e32 v43, v67
	v_mov_b32_e32 v39, v66
	v_pk_add_f32 v[48:49], v[60:61], v[62:63]
	v_pk_add_f32 v[38:39], v[38:39], v[42:43]
	s_waitcnt vmcnt(7)
	v_lshlrev_b32_e32 v50, 16, v72
	v_pk_add_f32 v[38:39], v[38:39], v[48:49]
	v_and_b32_e32 v51, 0xffff0000, v72
	v_add_f32_e32 v38, v38, v39
	v_fmamk_f32 v38, v38, 0x3a000000, v32
	v_rsq_f32_e32 v42, v38
	v_lshlrev_b32_e32 v38, 16, v73
	v_and_b32_e32 v39, 0xffff0000, v73
	v_pk_mul_f32 v[44:45], v[42:43], v[50:51] op_sel_hi:[0,1]
	v_pk_mul_f32 v[38:39], v[42:43], v[38:39] op_sel_hi:[0,1]
	v_pk_mul_f32 v[40:41], v[2:3], v[38:39]
	v_pk_mul_f32 v[38:39], v[0:1], v[44:45]
	global_store_dwordx4 v[74:75], v[38:41], off
	s_nop 0
	s_waitcnt vmcnt(7)
	v_lshlrev_b32_e32 v40, 16, v82
	v_and_b32_e32 v41, 0xffff0000, v82
	v_lshlrev_b32_e32 v38, 16, v83
	v_and_b32_e32 v39, 0xffff0000, v83
	v_pk_mul_f32 v[44:45], v[42:43], v[40:41] op_sel_hi:[0,1]
	v_pk_mul_f32 v[38:39], v[42:43], v[38:39] op_sel_hi:[0,1]
	v_pk_mul_f32 v[40:41], v[6:7], v[38:39]
	v_pk_mul_f32 v[38:39], v[4:5], v[44:45]
	global_store_dwordx4 v[74:75], v[38:41], off offset:1024
	s_nop 0
	s_waitcnt vmcnt(7)
	v_lshlrev_b32_e32 v40, 16, v84
	v_and_b32_e32 v41, 0xffff0000, v84
	v_lshlrev_b32_e32 v38, 16, v85
	v_and_b32_e32 v39, 0xffff0000, v85
	v_pk_mul_f32 v[44:45], v[42:43], v[40:41] op_sel_hi:[0,1]
	v_pk_mul_f32 v[38:39], v[42:43], v[38:39] op_sel_hi:[0,1]
	v_pk_mul_f32 v[40:41], v[10:11], v[38:39]
	v_pk_mul_f32 v[38:39], v[8:9], v[44:45]
	global_store_dwordx4 v[74:75], v[38:41], off offset:2048
	s_nop 0
	s_waitcnt vmcnt(7)
	v_lshlrev_b32_e32 v40, 16, v86
	v_and_b32_e32 v41, 0xffff0000, v86
	v_lshlrev_b32_e32 v38, 16, v87
	v_and_b32_e32 v39, 0xffff0000, v87
	v_pk_mul_f32 v[44:45], v[42:43], v[40:41] op_sel_hi:[0,1]
	v_pk_mul_f32 v[38:39], v[42:43], v[38:39] op_sel_hi:[0,1]
	v_pk_mul_f32 v[40:41], v[14:15], v[38:39]
	v_pk_mul_f32 v[38:39], v[12:13], v[44:45]
	global_store_dwordx4 v[74:75], v[38:41], off offset:3072
	v_add_co_u32_e32 v44, vcc, s2, v74
	s_nop 0
	s_waitcnt vmcnt(7)
	v_lshlrev_b32_e32 v40, 16, v88
	v_and_b32_e32 v41, 0xffff0000, v88
	v_lshlrev_b32_e32 v38, 16, v89
	v_and_b32_e32 v39, 0xffff0000, v89
	v_pk_mul_f32 v[46:47], v[42:43], v[40:41] op_sel_hi:[0,1]
	v_pk_mul_f32 v[38:39], v[42:43], v[38:39] op_sel_hi:[0,1]
	v_addc_co_u32_e32 v45, vcc, 0, v75, vcc
	v_pk_mul_f32 v[40:41], v[18:19], v[38:39]
	v_pk_mul_f32 v[38:39], v[16:17], v[46:47]
	global_store_dwordx4 v[44:45], v[38:41], off
	s_nop 0
	s_waitcnt vmcnt(7)
	v_lshlrev_b32_e32 v40, 16, v90
	v_and_b32_e32 v41, 0xffff0000, v90
	v_lshlrev_b32_e32 v38, 16, v91
	v_and_b32_e32 v39, 0xffff0000, v91
	v_pk_mul_f32 v[46:47], v[42:43], v[40:41] op_sel_hi:[0,1]
	v_pk_mul_f32 v[38:39], v[42:43], v[38:39] op_sel_hi:[0,1]
	v_pk_mul_f32 v[40:41], v[22:23], v[38:39]
	v_pk_mul_f32 v[38:39], v[20:21], v[46:47]
	global_store_dwordx4 v[44:45], v[38:41], off offset:1024
	s_nop 0
	s_waitcnt vmcnt(7)
	v_lshlrev_b32_e32 v40, 16, v92
	v_and_b32_e32 v41, 0xffff0000, v92
	v_lshlrev_b32_e32 v38, 16, v93
	v_and_b32_e32 v39, 0xffff0000, v93
	v_pk_mul_f32 v[46:47], v[42:43], v[40:41] op_sel_hi:[0,1]
	v_pk_mul_f32 v[38:39], v[42:43], v[38:39] op_sel_hi:[0,1]
	v_pk_mul_f32 v[40:41], v[26:27], v[38:39]
	v_pk_mul_f32 v[38:39], v[24:25], v[46:47]
	global_store_dwordx4 v[44:45], v[38:41], off offset:2048
	s_nop 0
	s_waitcnt vmcnt(7)
	v_lshlrev_b32_e32 v40, 16, v94
	v_and_b32_e32 v41, 0xffff0000, v94
	v_lshlrev_b32_e32 v38, 16, v95
	v_and_b32_e32 v39, 0xffff0000, v95
	v_pk_mul_f32 v[46:47], v[42:43], v[40:41] op_sel_hi:[0,1]
	v_pk_mul_f32 v[38:39], v[42:43], v[38:39] op_sel_hi:[0,1]
	v_pk_mul_f32 v[40:41], v[30:31], v[38:39]
	v_pk_mul_f32 v[38:39], v[28:29], v[46:47]
	global_store_dwordx4 v[44:45], v[38:41], off offset:3072
	s_cbranch_scc0 .LBB0_1138
